# v16 with s_setprio inverted: loading half at prio 1, computing half at prio 0
# baseline (speedup 1.0000x reference)
.LBB0_543:
	s_ashr_i32 s23, s22, 31
	s_lshl_b64 s[24:25], s[22:23], 19
	ds_read_b128 v[0:3], v165
	ds_read_b128 v[4:7], v165 offset:1024
	ds_read_b128 v[8:11], v165 offset:2048
	ds_read_b128 v[12:15], v165 offset:3072
	ds_read_b128 v[16:19], v166
	ds_read_b128 v[20:23], v166 offset:1024
	ds_read_b128 v[24:27], v166 offset:2048
	ds_read_b128 v[28:31], v166 offset:3072
	s_add_u32 s7, s40, s24
	s_addc_u32 s23, s41, s25
	s_ashr_i32 s21, s20, 31
	s_lshl_b64 s[24:25], s[20:21], 9
	s_add_u32 s24, s7, s24
	s_addc_u32 s25, s23, s25
	s_and_b64 s[26:27], s[4:5], exec
	s_cselect_b32 s37, s25, s29
	s_cselect_b32 s36, s24, s28
	s_lshl_b64 s[26:27], s[20:21], 17
	s_add_u32 s26, s38, s26
	s_addc_u32 s27, s39, s27
	s_and_b64 s[34:35], s[4:5], exec
	s_cselect_b32 s35, s27, s31
	s_cselect_b32 s34, s26, s30
	s_add_u32 s58, s28, 0x40080
	s_addc_u32 s59, s29, 0
	s_add_i32 s60, s43, 0xc000
	v_lshl_add_u64 v[64:65], s[58:59], 0, v[146:147]
	s_mov_b32 m0, s60
	s_add_i32 s7, s43, 0xe000
	ds_read_b128 v[32:35], v167
	ds_read_b128 v[36:39], v167 offset:1024
	ds_read_b128 v[40:43], v167 offset:2048
	ds_read_b128 v[44:47], v167 offset:3072
	ds_read_b128 v[48:51], v167 offset:4096
	ds_read_b128 v[52:55], v167 offset:5120
	ds_read_b128 v[56:59], v167 offset:6144
	ds_read_b128 v[60:63], v167 offset:7168
	global_load_lds_dwordx4 v[64:65], off
	v_lshl_add_u64 v[64:65], s[58:59], 0, v[142:143]
	s_mov_b32 m0, s7
	s_nop 0
	global_load_lds_dwordx4 v[64:65], off
	s_waitcnt vmcnt(8)
	s_waitcnt lgkmcnt(0)
	s_barrier
	s_setprio 0
	s_waitcnt lgkmcnt(0)
	v_mfma_f32_16x16x32_bf16 v[64:67], v[0:3], v[32:35], 0
	v_mfma_f32_16x16x32_bf16 v[68:71], v[8:11], v[32:35], 0
	v_mfma_f32_16x16x32_bf16 v[72:75], v[0:3], v[40:43], 0
	v_mfma_f32_16x16x32_bf16 v[76:79], v[8:11], v[40:43], 0
	v_mfma_f32_16x16x32_bf16 v[80:83], v[0:3], v[48:51], 0
	v_mfma_f32_16x16x32_bf16 v[84:87], v[8:11], v[48:51], 0
	v_mfma_f32_16x16x32_bf16 v[88:91], v[0:3], v[56:59], 0
	v_mfma_f32_16x16x32_bf16 v[92:95], v[8:11], v[56:59], 0
	v_mfma_f32_16x16x32_bf16 v[64:67], v[4:7], v[36:39], v[64:67]
	v_mfma_f32_16x16x32_bf16 v[68:71], v[12:15], v[36:39], v[68:71]
	v_mfma_f32_16x16x32_bf16 v[72:75], v[4:7], v[44:47], v[72:75]
	v_mfma_f32_16x16x32_bf16 v[76:79], v[12:15], v[44:47], v[76:79]
	v_mfma_f32_16x16x32_bf16 v[80:83], v[4:7], v[52:55], v[80:83]
	v_mfma_f32_16x16x32_bf16 v[84:87], v[12:15], v[52:55], v[84:87]
	v_mfma_f32_16x16x32_bf16 v[88:91], v[4:7], v[60:63], v[88:91]
	v_mfma_f32_16x16x32_bf16 v[92:95], v[12:15], v[60:63], v[92:95]
	s_setprio 1
	s_setprio 0
	v_mfma_f32_16x16x32_bf16 v[96:99], v[16:19], v[32:35], 0
	v_mfma_f32_16x16x32_bf16 v[32:35], v[24:27], v[32:35], 0
	v_mfma_f32_16x16x32_bf16 v[96:99], v[20:23], v[36:39], v[96:99]
	v_mfma_f32_16x16x32_bf16 v[32:35], v[28:31], v[36:39], v[32:35]
	v_mfma_f32_16x16x32_bf16 v[36:39], v[16:19], v[40:43], 0
	v_mfma_f32_16x16x32_bf16 v[40:43], v[24:27], v[40:43], 0
	v_mfma_f32_16x16x32_bf16 v[36:39], v[20:23], v[44:47], v[36:39]
	v_mfma_f32_16x16x32_bf16 v[40:43], v[28:31], v[44:47], v[40:43]
	v_mfma_f32_16x16x32_bf16 v[44:47], v[16:19], v[48:51], 0
	v_mfma_f32_16x16x32_bf16 v[48:51], v[24:27], v[48:51], 0
	v_mfma_f32_16x16x32_bf16 v[44:47], v[20:23], v[52:55], v[44:47]
	v_mfma_f32_16x16x32_bf16 v[48:51], v[28:31], v[52:55], v[48:51]
	v_mfma_f32_16x16x32_bf16 v[52:55], v[16:19], v[56:59], 0
	v_mfma_f32_16x16x32_bf16 v[56:59], v[24:27], v[56:59], 0
	v_mfma_f32_16x16x32_bf16 v[52:55], v[20:23], v[60:63], v[52:55]
	v_mfma_f32_16x16x32_bf16 v[56:59], v[28:31], v[60:63], v[56:59]
	s_setprio 1
	s_barrier
	s_add_i32 s58, s54, s42
	v_lshl_add_u64 v[150:151], s[30:31], 0, v[144:145]
	s_add_i32 s21, s58, 0x2000
	v_lshl_add_u64 v[128:129], v[150:151], 0, s[16:17]
	s_mov_b32 m0, s58
	v_lshl_add_u64 v[152:153], s[30:31], 0, v[140:141]
	s_add_u32 s62, s30, 0x10100
	ds_read_b128 v[60:63], v167 offset:16384
	ds_read_b128 v[100:103], v167 offset:17408
	ds_read_b128 v[104:107], v167 offset:18432
	ds_read_b128 v[108:111], v167 offset:19456
	ds_read_b128 v[112:115], v167 offset:20480
	ds_read_b128 v[116:119], v167 offset:21504
	ds_read_b128 v[120:123], v167 offset:22528
	ds_read_b128 v[124:127], v167 offset:23552
	global_load_lds_dwordx4 v[128:129], off
	v_lshl_add_u64 v[128:129], v[152:153], 0, s[16:17]
	s_mov_b32 m0, s21
	s_addc_u32 s63, s31, 0
	s_add_i32 s23, s55, s42
	global_load_lds_dwordx4 v[128:129], off
	v_lshl_add_u64 v[128:129], s[62:63], 0, v[144:145]
	s_mov_b32 m0, s23
	s_add_i32 s57, s23, 0x2000
	global_load_lds_dwordx4 v[128:129], off
	v_lshl_add_u64 v[128:129], s[62:63], 0, v[140:141]
	s_mov_b32 m0, s57
	v_lshl_add_u64 v[162:163], s[28:29], 0, v[146:147]
	global_load_lds_dwordx4 v[128:129], off
	v_lshl_add_u64 v[128:129], v[162:163], 0, s[16:17]
	s_mov_b32 m0, s43
	v_lshl_add_u64 v[176:177], s[28:29], 0, v[142:143]
	global_load_lds_dwordx4 v[128:129], off
	v_lshl_add_u64 v[128:129], v[176:177], 0, s[16:17]
	s_mov_b32 m0, s44
	s_nop 0
	global_load_lds_dwordx4 v[128:129], off
	s_waitcnt vmcnt(8)
	s_waitcnt lgkmcnt(0)
	s_barrier
	s_setprio 0
	s_waitcnt lgkmcnt(0)
	v_mfma_f32_16x16x32_bf16 v[128:131], v[0:3], v[60:63], 0
	v_mfma_f32_16x16x32_bf16 v[136:139], v[0:3], v[104:107], 0
	v_mfma_f32_16x16x32_bf16 v[158:161], v[0:3], v[112:115], 0
	v_mfma_f32_16x16x32_bf16 v[0:3], v[0:3], v[120:123], 0
	v_mfma_f32_16x16x32_bf16 v[128:131], v[4:7], v[100:103], v[128:131]
	v_mfma_f32_16x16x32_bf16 v[136:139], v[4:7], v[108:111], v[136:139]
	v_mfma_f32_16x16x32_bf16 v[158:161], v[4:7], v[116:119], v[158:161]
	v_mfma_f32_16x16x32_bf16 v[0:3], v[4:7], v[124:127], v[0:3]
	v_mfma_f32_16x16x32_bf16 v[4:7], v[8:11], v[120:123], 0
	v_mfma_f32_16x16x32_bf16 v[132:135], v[8:11], v[60:63], 0
	v_mfma_f32_16x16x32_bf16 v[154:157], v[8:11], v[104:107], 0
	v_mfma_f32_16x16x32_bf16 v[168:171], v[8:11], v[112:115], 0
	v_mfma_f32_16x16x32_bf16 v[4:7], v[12:15], v[124:127], v[4:7]
	v_mfma_f32_16x16x32_bf16 v[132:135], v[12:15], v[100:103], v[132:135]
	v_mfma_f32_16x16x32_bf16 v[154:157], v[12:15], v[108:111], v[154:157]
	v_mfma_f32_16x16x32_bf16 v[168:171], v[12:15], v[116:119], v[168:171]
	s_setprio 1
	s_setprio 0
	v_mfma_f32_16x16x32_bf16 v[8:11], v[16:19], v[60:63], 0
	v_mfma_f32_16x16x32_bf16 v[12:15], v[24:27], v[60:63], 0
	v_mfma_f32_16x16x32_bf16 v[8:11], v[20:23], v[100:103], v[8:11]
	v_mfma_f32_16x16x32_bf16 v[12:15], v[28:31], v[100:103], v[12:15]
	v_mfma_f32_16x16x32_bf16 v[60:63], v[16:19], v[104:107], 0
	v_mfma_f32_16x16x32_bf16 v[100:103], v[24:27], v[104:107], 0
	v_mfma_f32_16x16x32_bf16 v[104:107], v[16:19], v[112:115], 0
	v_mfma_f32_16x16x32_bf16 v[16:19], v[16:19], v[120:123], 0
	v_mfma_f32_16x16x32_bf16 v[60:63], v[20:23], v[108:111], v[60:63]
	v_mfma_f32_16x16x32_bf16 v[100:103], v[28:31], v[108:111], v[100:103]
	v_mfma_f32_16x16x32_bf16 v[104:107], v[20:23], v[116:119], v[104:107]
	v_mfma_f32_16x16x32_bf16 v[108:111], v[24:27], v[112:115], 0
	v_mfma_f32_16x16x32_bf16 v[16:19], v[20:23], v[124:127], v[16:19]
	v_mfma_f32_16x16x32_bf16 v[20:23], v[24:27], v[120:123], 0
	v_mfma_f32_16x16x32_bf16 v[108:111], v[28:31], v[116:119], v[108:111]
	v_mfma_f32_16x16x32_bf16 v[20:23], v[28:31], v[124:127], v[20:23]
	s_setprio 1
	s_barrier
	s_add_i32 s61, 0, 0x18000
	s_add_i32 s64, 0, 0x1c000
	v_add_u32_e32 v148, s61, v164
	v_add_u32_e32 v238, s64, v164
	ds_read_b128 v[24:27], v148
	ds_read_b128 v[28:31], v148 offset:1024
	ds_read_b128 v[112:115], v148 offset:2048
	ds_read_b128 v[116:119], v148 offset:3072
	ds_read_b128 v[120:123], v238
	ds_read_b128 v[124:127], v238 offset:1024
	ds_read_b128 v[172:175], v238 offset:2048
	ds_read_b128 v[180:183], v238 offset:3072
	s_add_u32 s62, s28, 0x40100
	s_addc_u32 s63, s29, 0
	s_mov_b32 m0, s45
	v_lshl_add_u64 v[178:179], s[62:63], 0, v[146:147]
	ds_read_b128 v[184:187], v167 offset:32768
	ds_read_b128 v[188:191], v167 offset:33792
	ds_read_b128 v[192:195], v167 offset:34816
	ds_read_b128 v[196:199], v167 offset:35840
	ds_read_b128 v[200:203], v167 offset:36864
	ds_read_b128 v[204:207], v167 offset:37888
	ds_read_b128 v[214:217], v167 offset:38912
	ds_read_b128 v[218:221], v167 offset:39936
	global_load_lds_dwordx4 v[178:179], off
	v_lshl_add_u64 v[178:179], s[62:63], 0, v[142:143]
	s_mov_b32 m0, s46
	s_nop 0
	global_load_lds_dwordx4 v[178:179], off
	s_waitcnt vmcnt(8)
	s_waitcnt lgkmcnt(0)
	s_barrier
	s_setprio 0
	s_waitcnt lgkmcnt(0)
	v_mfma_f32_16x16x32_bf16 v[64:67], v[24:27], v[184:187], v[64:67]
	v_mfma_f32_16x16x32_bf16 v[68:71], v[112:115], v[184:187], v[68:71]
	v_mfma_f32_16x16x32_bf16 v[72:75], v[24:27], v[192:195], v[72:75]
	v_mfma_f32_16x16x32_bf16 v[76:79], v[112:115], v[192:195], v[76:79]
	v_mfma_f32_16x16x32_bf16 v[80:83], v[24:27], v[200:203], v[80:83]
	v_mfma_f32_16x16x32_bf16 v[84:87], v[112:115], v[200:203], v[84:87]
	v_mfma_f32_16x16x32_bf16 v[88:91], v[24:27], v[214:217], v[88:91]
	v_mfma_f32_16x16x32_bf16 v[92:95], v[112:115], v[214:217], v[92:95]
	v_mfma_f32_16x16x32_bf16 v[64:67], v[28:31], v[188:191], v[64:67]
	v_mfma_f32_16x16x32_bf16 v[68:71], v[116:119], v[188:191], v[68:71]
	v_mfma_f32_16x16x32_bf16 v[72:75], v[28:31], v[196:199], v[72:75]
	v_mfma_f32_16x16x32_bf16 v[76:79], v[116:119], v[196:199], v[76:79]
	v_mfma_f32_16x16x32_bf16 v[80:83], v[28:31], v[204:207], v[80:83]
	v_mfma_f32_16x16x32_bf16 v[84:87], v[116:119], v[204:207], v[84:87]
	v_mfma_f32_16x16x32_bf16 v[88:91], v[28:31], v[218:221], v[88:91]
	v_mfma_f32_16x16x32_bf16 v[92:95], v[116:119], v[218:221], v[92:95]
	s_setprio 1
	s_setprio 0
	v_mfma_f32_16x16x32_bf16 v[96:99], v[120:123], v[184:187], v[96:99]
	v_mfma_f32_16x16x32_bf16 v[32:35], v[172:175], v[184:187], v[32:35]
	v_mfma_f32_16x16x32_bf16 v[36:39], v[120:123], v[192:195], v[36:39]
	v_mfma_f32_16x16x32_bf16 v[40:43], v[172:175], v[192:195], v[40:43]
	v_mfma_f32_16x16x32_bf16 v[44:47], v[120:123], v[200:203], v[44:47]
	v_mfma_f32_16x16x32_bf16 v[48:51], v[172:175], v[200:203], v[48:51]
	v_mfma_f32_16x16x32_bf16 v[52:55], v[120:123], v[214:217], v[52:55]
	v_mfma_f32_16x16x32_bf16 v[56:59], v[172:175], v[214:217], v[56:59]
	v_mfma_f32_16x16x32_bf16 v[96:99], v[124:127], v[188:191], v[96:99]
	v_mfma_f32_16x16x32_bf16 v[32:35], v[180:183], v[188:191], v[32:35]
	v_mfma_f32_16x16x32_bf16 v[36:39], v[124:127], v[196:199], v[36:39]
	v_mfma_f32_16x16x32_bf16 v[40:43], v[180:183], v[196:199], v[40:43]
	v_mfma_f32_16x16x32_bf16 v[44:47], v[124:127], v[204:207], v[44:47]
	v_mfma_f32_16x16x32_bf16 v[48:51], v[180:183], v[204:207], v[48:51]
	v_mfma_f32_16x16x32_bf16 v[52:55], v[124:127], v[218:221], v[52:55]
	v_mfma_f32_16x16x32_bf16 v[56:59], v[180:183], v[218:221], v[56:59]
	s_setprio 1
	s_barrier
	s_add_i32 s61, s61, s42
	s_add_i32 s59, s61, 0x2000
	v_lshl_add_u64 v[150:151], v[150:151], 0, s[18:19]
	s_mov_b32 m0, s61
	s_add_u32 s62, s30, 0x10180
	ds_read_b128 v[184:187], v167 offset:49152
	ds_read_b128 v[188:191], v167 offset:50176
	ds_read_b128 v[192:195], v167 offset:51200
	ds_read_b128 v[196:199], v167 offset:52224
	ds_read_b128 v[200:203], v167 offset:53248
	ds_read_b128 v[204:207], v167 offset:54272
	ds_read_b128 v[214:217], v167 offset:55296
	ds_read_b128 v[218:221], v167 offset:56320
	global_load_lds_dwordx4 v[150:151], off
	v_lshl_add_u64 v[150:151], v[152:153], 0, s[18:19]
	s_mov_b32 m0, s59
	s_addc_u32 s63, s31, 0
	s_add_i32 s30, s64, s42
	global_load_lds_dwordx4 v[150:151], off
	v_lshl_add_u64 v[150:151], s[62:63], 0, v[144:145]
	s_mov_b32 m0, s30
	s_add_i32 s31, s30, 0x2000
	global_load_lds_dwordx4 v[150:151], off
	v_lshl_add_u64 v[150:151], s[62:63], 0, v[140:141]
	s_mov_b32 m0, s31
	s_nop 0
	global_load_lds_dwordx4 v[150:151], off
	v_lshl_add_u64 v[150:151], v[162:163], 0, s[18:19]
	s_mov_b32 m0, s50
	s_nop 0
	global_load_lds_dwordx4 v[150:151], off
	v_lshl_add_u64 v[150:151], v[176:177], 0, s[18:19]
	s_mov_b32 m0, s51
	s_nop 0
	global_load_lds_dwordx4 v[150:151], off
	s_waitcnt vmcnt(8)
	s_waitcnt lgkmcnt(0)
	s_barrier
	s_setprio 0
	s_waitcnt lgkmcnt(0)
	v_mfma_f32_16x16x32_bf16 v[128:131], v[24:27], v[184:187], v[128:131]
	v_mfma_f32_16x16x32_bf16 v[0:3], v[24:27], v[214:217], v[0:3]
	v_mfma_f32_16x16x32_bf16 v[4:7], v[112:115], v[214:217], v[4:7]
	v_mfma_f32_16x16x32_bf16 v[128:131], v[28:31], v[188:191], v[128:131]
	v_mfma_f32_16x16x32_bf16 v[132:135], v[112:115], v[184:187], v[132:135]
	v_mfma_f32_16x16x32_bf16 v[136:139], v[24:27], v[192:195], v[136:139]
	v_mfma_f32_16x16x32_bf16 v[154:157], v[112:115], v[192:195], v[154:157]
	v_mfma_f32_16x16x32_bf16 v[158:161], v[24:27], v[200:203], v[158:161]
	v_mfma_f32_16x16x32_bf16 v[168:171], v[112:115], v[200:203], v[168:171]
	v_mfma_f32_16x16x32_bf16 v[0:3], v[28:31], v[218:221], v[0:3]
	v_mfma_f32_16x16x32_bf16 v[4:7], v[116:119], v[218:221], v[4:7]
	v_mfma_f32_16x16x32_bf16 v[132:135], v[116:119], v[188:191], v[132:135]
	v_mfma_f32_16x16x32_bf16 v[136:139], v[28:31], v[196:199], v[136:139]
	v_mfma_f32_16x16x32_bf16 v[154:157], v[116:119], v[196:199], v[154:157]
	v_mfma_f32_16x16x32_bf16 v[158:161], v[28:31], v[204:207], v[158:161]
	v_mfma_f32_16x16x32_bf16 v[168:171], v[116:119], v[204:207], v[168:171]
	s_setprio 1
	s_setprio 0
	v_mfma_f32_16x16x32_bf16 v[8:11], v[120:123], v[184:187], v[8:11]
	v_mfma_f32_16x16x32_bf16 v[12:15], v[172:175], v[184:187], v[12:15]
	v_mfma_f32_16x16x32_bf16 v[24:27], v[120:123], v[192:195], v[60:63]
	v_mfma_f32_16x16x32_bf16 v[28:31], v[172:175], v[192:195], v[100:103]
	v_mfma_f32_16x16x32_bf16 v[60:63], v[120:123], v[200:203], v[104:107]
	v_mfma_f32_16x16x32_bf16 v[100:103], v[172:175], v[200:203], v[108:111]
	v_mfma_f32_16x16x32_bf16 v[16:19], v[120:123], v[214:217], v[16:19]
	v_mfma_f32_16x16x32_bf16 v[20:23], v[172:175], v[214:217], v[20:23]
	v_mfma_f32_16x16x32_bf16 v[8:11], v[124:127], v[188:191], v[8:11]
	v_mfma_f32_16x16x32_bf16 v[12:15], v[180:183], v[188:191], v[12:15]
	v_mfma_f32_16x16x32_bf16 v[24:27], v[124:127], v[196:199], v[24:27]
	v_mfma_f32_16x16x32_bf16 v[28:31], v[180:183], v[196:199], v[28:31]
	v_mfma_f32_16x16x32_bf16 v[60:63], v[124:127], v[204:207], v[60:63]
	v_mfma_f32_16x16x32_bf16 v[100:103], v[180:183], v[204:207], v[100:103]
	v_mfma_f32_16x16x32_bf16 v[16:19], v[124:127], v[218:221], v[16:19]
	v_mfma_f32_16x16x32_bf16 v[20:23], v[180:183], v[218:221], v[20:23]
	s_setprio 1
	s_barrier
	ds_read_b128 v[104:107], v165
	ds_read_b128 v[108:111], v165 offset:1024
	ds_read_b128 v[112:115], v165 offset:2048
	ds_read_b128 v[116:119], v165 offset:3072
	ds_read_b128 v[120:123], v166
	ds_read_b128 v[124:127], v166 offset:1024
	ds_read_b128 v[172:175], v166 offset:2048
	ds_read_b128 v[180:183], v166 offset:3072
	s_add_u32 s28, s28, 0x40180
	s_addc_u32 s29, s29, 0
	s_mov_b32 m0, s60
	v_lshl_add_u64 v[150:151], s[28:29], 0, v[146:147]
	ds_read_b128 v[184:187], v167
	ds_read_b128 v[188:191], v167 offset:1024
	ds_read_b128 v[192:195], v167 offset:2048
	ds_read_b128 v[196:199], v167 offset:3072
	ds_read_b128 v[200:203], v167 offset:4096
	ds_read_b128 v[204:207], v167 offset:5120
	ds_read_b128 v[214:217], v167 offset:6144
	ds_read_b128 v[218:221], v167 offset:7168
	global_load_lds_dwordx4 v[150:151], off
	v_lshl_add_u64 v[150:151], s[28:29], 0, v[142:143]
	s_mov_b32 m0, s7
	s_nop 0
	global_load_lds_dwordx4 v[150:151], off
	s_waitcnt vmcnt(8)
	s_waitcnt lgkmcnt(0)
	s_barrier
	s_setprio 0
	s_waitcnt lgkmcnt(0)
	v_mfma_f32_16x16x32_bf16 v[64:67], v[104:107], v[184:187], v[64:67]
	v_mfma_f32_16x16x32_bf16 v[68:71], v[112:115], v[184:187], v[68:71]
	v_mfma_f32_16x16x32_bf16 v[72:75], v[104:107], v[192:195], v[72:75]
	v_mfma_f32_16x16x32_bf16 v[76:79], v[112:115], v[192:195], v[76:79]
	v_mfma_f32_16x16x32_bf16 v[80:83], v[104:107], v[200:203], v[80:83]
	v_mfma_f32_16x16x32_bf16 v[84:87], v[112:115], v[200:203], v[84:87]
	v_mfma_f32_16x16x32_bf16 v[88:91], v[104:107], v[214:217], v[88:91]
	v_mfma_f32_16x16x32_bf16 v[64:67], v[108:111], v[188:191], v[64:67]
	v_mfma_f32_16x16x32_bf16 v[68:71], v[116:119], v[188:191], v[68:71]
	v_mfma_f32_16x16x32_bf16 v[72:75], v[108:111], v[196:199], v[72:75]
	v_mfma_f32_16x16x32_bf16 v[76:79], v[116:119], v[196:199], v[76:79]
	v_mfma_f32_16x16x32_bf16 v[80:83], v[108:111], v[204:207], v[80:83]
	v_mfma_f32_16x16x32_bf16 v[84:87], v[116:119], v[204:207], v[84:87]
	v_mfma_f32_16x16x32_bf16 v[222:225], v[108:111], v[218:221], v[88:91]
	v_mfma_f32_16x16x32_bf16 v[88:91], v[112:115], v[214:217], v[92:95]
	v_mfma_f32_16x16x32_bf16 v[226:229], v[116:119], v[218:221], v[88:91]
	s_setprio 1
	s_setprio 0
	v_mfma_f32_16x16x32_bf16 v[88:91], v[120:123], v[184:187], v[96:99]
	v_mfma_f32_16x16x32_bf16 v[32:35], v[172:175], v[184:187], v[32:35]
	v_mfma_f32_16x16x32_bf16 v[36:39], v[120:123], v[192:195], v[36:39]
	v_mfma_f32_16x16x32_bf16 v[40:43], v[172:175], v[192:195], v[40:43]
	v_mfma_f32_16x16x32_bf16 v[44:47], v[120:123], v[200:203], v[44:47]
	v_mfma_f32_16x16x32_bf16 v[48:51], v[172:175], v[200:203], v[48:51]
	v_mfma_f32_16x16x32_bf16 v[52:55], v[120:123], v[214:217], v[52:55]
	v_mfma_f32_16x16x32_bf16 v[56:59], v[172:175], v[214:217], v[56:59]
	v_mfma_f32_16x16x32_bf16 v[96:99], v[124:127], v[188:191], v[88:91]
	v_mfma_f32_16x16x32_bf16 v[32:35], v[180:183], v[188:191], v[32:35]
	v_mfma_f32_16x16x32_bf16 v[36:39], v[124:127], v[196:199], v[36:39]
	v_mfma_f32_16x16x32_bf16 v[40:43], v[180:183], v[196:199], v[40:43]
	v_mfma_f32_16x16x32_bf16 v[44:47], v[124:127], v[204:207], v[44:47]
	v_mfma_f32_16x16x32_bf16 v[48:51], v[180:183], v[204:207], v[48:51]
	v_mfma_f32_16x16x32_bf16 v[52:55], v[124:127], v[218:221], v[52:55]
	v_mfma_f32_16x16x32_bf16 v[56:59], v[180:183], v[218:221], v[56:59]
	s_setprio 1
	s_barrier
	s_mov_b32 m0, s58
	v_lshl_add_u64 v[162:163], s[34:35], 0, v[144:145]
	s_add_u32 s28, s34, 0x10000
	ds_read_b128 v[88:91], v167 offset:16384
	ds_read_b128 v[92:95], v167 offset:17408
	ds_read_b128 v[184:187], v167 offset:18432
	ds_read_b128 v[188:191], v167 offset:19456
	ds_read_b128 v[192:195], v167 offset:20480
	ds_read_b128 v[196:199], v167 offset:21504
	ds_read_b128 v[200:203], v167 offset:22528
	ds_read_b128 v[204:207], v167 offset:23552
	global_load_lds_dwordx4 v[162:163], off
	v_lshl_add_u64 v[210:211], s[34:35], 0, v[140:141]
	s_mov_b32 m0, s21
	s_addc_u32 s29, s35, 0
	global_load_lds_dwordx4 v[210:211], off
	v_lshl_add_u64 v[150:151], s[28:29], 0, v[144:145]
	s_mov_b32 m0, s23
	v_lshl_add_u64 v[250:251], s[36:37], 0, v[146:147]
	global_load_lds_dwordx4 v[150:151], off
	v_lshl_add_u64 v[150:151], s[28:29], 0, v[140:141]
	s_mov_b32 m0, s57
	v_lshl_add_u64 v[212:213], s[36:37], 0, v[142:143]
	global_load_lds_dwordx4 v[150:151], off
	s_mov_b32 m0, s43
	s_nop 0
	global_load_lds_dwordx4 v[250:251], off
	s_mov_b32 m0, s44
	s_nop 0
	global_load_lds_dwordx4 v[212:213], off
	s_waitcnt vmcnt(8)
	s_waitcnt lgkmcnt(0)
	s_barrier
	s_setprio 0
	s_waitcnt lgkmcnt(0)
	v_mfma_f32_16x16x32_bf16 v[128:131], v[104:107], v[88:91], v[128:131]
	v_mfma_f32_16x16x32_bf16 v[214:217], v[108:111], v[92:95], v[128:131]
	v_mfma_f32_16x16x32_bf16 v[128:131], v[112:115], v[88:91], v[132:135]
	v_mfma_f32_16x16x32_bf16 v[132:135], v[116:119], v[92:95], v[128:131]
	v_mfma_f32_16x16x32_bf16 v[128:131], v[104:107], v[184:187], v[136:139]
	v_mfma_f32_16x16x32_bf16 v[136:139], v[108:111], v[188:191], v[128:131]
	v_mfma_f32_16x16x32_bf16 v[128:131], v[112:115], v[184:187], v[154:157]
	v_mfma_f32_16x16x32_bf16 v[154:157], v[116:119], v[188:191], v[128:131]
	v_mfma_f32_16x16x32_bf16 v[128:131], v[104:107], v[192:195], v[158:161]
	v_mfma_f32_16x16x32_bf16 v[0:3], v[104:107], v[200:203], v[0:3]
	v_mfma_f32_16x16x32_bf16 v[4:7], v[112:115], v[200:203], v[4:7]
	v_mfma_f32_16x16x32_bf16 v[158:161], v[108:111], v[196:199], v[128:131]
	v_mfma_f32_16x16x32_bf16 v[128:131], v[112:115], v[192:195], v[168:171]
	v_mfma_f32_16x16x32_bf16 v[0:3], v[108:111], v[204:207], v[0:3]
	v_mfma_f32_16x16x32_bf16 v[4:7], v[116:119], v[204:207], v[4:7]
	v_mfma_f32_16x16x32_bf16 v[168:171], v[116:119], v[196:199], v[128:131]
	s_setprio 1
	s_setprio 0
	v_mfma_f32_16x16x32_bf16 v[8:11], v[120:123], v[88:91], v[8:11]
	v_mfma_f32_16x16x32_bf16 v[218:221], v[124:127], v[92:95], v[8:11]
	v_mfma_f32_16x16x32_bf16 v[8:11], v[172:175], v[88:91], v[12:15]
	v_mfma_f32_16x16x32_bf16 v[230:233], v[180:183], v[92:95], v[8:11]
	v_mfma_f32_16x16x32_bf16 v[8:11], v[120:123], v[184:187], v[24:27]
	v_mfma_f32_16x16x32_bf16 v[234:237], v[124:127], v[188:191], v[8:11]
	v_mfma_f32_16x16x32_bf16 v[8:11], v[172:175], v[184:187], v[28:31]
	v_mfma_f32_16x16x32_bf16 v[184:187], v[180:183], v[188:191], v[8:11]
	v_mfma_f32_16x16x32_bf16 v[8:11], v[120:123], v[192:195], v[60:63]
	v_mfma_f32_16x16x32_bf16 v[188:191], v[124:127], v[196:199], v[8:11]
	v_mfma_f32_16x16x32_bf16 v[8:11], v[172:175], v[192:195], v[100:103]
	v_mfma_f32_16x16x32_bf16 v[192:195], v[180:183], v[196:199], v[8:11]
	v_mfma_f32_16x16x32_bf16 v[8:11], v[120:123], v[200:203], v[16:19]
	v_mfma_f32_16x16x32_bf16 v[124:127], v[124:127], v[204:207], v[8:11]
	v_mfma_f32_16x16x32_bf16 v[8:11], v[172:175], v[200:203], v[20:23]
	v_mfma_f32_16x16x32_bf16 v[172:175], v[180:183], v[204:207], v[8:11]
	s_setprio 1
	s_barrier
	s_nop 4
	ds_read_b128 v[8:11], v148
	ds_read_b128 v[12:15], v148 offset:1024
	ds_read_b128 v[16:19], v148 offset:2048
	ds_read_b128 v[20:23], v148 offset:3072
	ds_read_b128 v[180:183], v238
	ds_read_b128 v[196:199], v238 offset:1024
	ds_read_b128 v[200:203], v238 offset:2048
	ds_read_b128 v[204:207], v238 offset:3072
	s_add_u32 s28, s36, 0x40000
	s_addc_u32 s29, s37, 0
	s_mov_b32 m0, s45
	v_lshl_add_u64 v[88:89], s[28:29], 0, v[146:147]
	ds_read_b128 v[24:27], v167 offset:32768
	ds_read_b128 v[28:31], v167 offset:33792
	ds_read_b128 v[60:63], v167 offset:34816
	ds_read_b128 v[238:241], v167 offset:35840
	ds_read_b128 v[242:245], v167 offset:36864
	ds_read_b128 v[246:249], v167 offset:37888
	ds_read_b128 v[176:179], v167 offset:38912
	ds_read_b128 v[150:153], v167 offset:39936
	global_load_lds_dwordx4 v[88:89], off
	v_lshl_add_u64 v[88:89], s[28:29], 0, v[142:143]
	s_mov_b32 m0, s46
	s_nop 0
	global_load_lds_dwordx4 v[88:89], off
	s_waitcnt vmcnt(8)
	s_waitcnt lgkmcnt(0)
	s_barrier
	s_setprio 0
	s_waitcnt lgkmcnt(0)
	v_mfma_f32_16x16x32_bf16 v[64:67], v[8:11], v[24:27], v[64:67]
	v_mfma_f32_16x16x32_bf16 v[128:131], v[12:15], v[28:31], v[64:67]
	v_mfma_f32_16x16x32_bf16 v[64:67], v[16:19], v[24:27], v[68:71]
	v_mfma_f32_16x16x32_bf16 v[120:123], v[20:23], v[28:31], v[64:67]
	v_mfma_f32_16x16x32_bf16 v[64:67], v[8:11], v[60:63], v[72:75]
	v_mfma_f32_16x16x32_bf16 v[108:111], v[12:15], v[238:241], v[64:67]
	v_mfma_f32_16x16x32_bf16 v[64:67], v[16:19], v[60:63], v[76:79]
	v_mfma_f32_16x16x32_bf16 v[104:107], v[20:23], v[238:241], v[64:67]
	v_mfma_f32_16x16x32_bf16 v[64:67], v[8:11], v[242:245], v[80:83]
	v_mfma_f32_16x16x32_bf16 v[92:95], v[12:15], v[246:249], v[64:67]
	v_mfma_f32_16x16x32_bf16 v[64:67], v[16:19], v[242:245], v[84:87]
	v_mfma_f32_16x16x32_bf16 v[88:91], v[20:23], v[246:249], v[64:67]
	v_mfma_f32_16x16x32_bf16 v[64:67], v[8:11], v[176:179], v[222:225]
	v_mfma_f32_16x16x32_bf16 v[76:79], v[12:15], v[150:153], v[64:67]
	v_mfma_f32_16x16x32_bf16 v[64:67], v[16:19], v[176:179], v[226:229]
	v_mfma_f32_16x16x32_bf16 v[72:75], v[20:23], v[150:153], v[64:67]
	s_setprio 1
	s_setprio 0
	v_mfma_f32_16x16x32_bf16 v[64:67], v[180:183], v[24:27], v[96:99]
	v_mfma_f32_16x16x32_bf16 v[24:27], v[200:203], v[24:27], v[32:35]
	v_mfma_f32_16x16x32_bf16 v[112:115], v[204:207], v[28:31], v[24:27]
	v_mfma_f32_16x16x32_bf16 v[24:27], v[180:183], v[60:63], v[36:39]
	v_mfma_f32_16x16x32_bf16 v[100:103], v[196:199], v[238:241], v[24:27]
	v_mfma_f32_16x16x32_bf16 v[24:27], v[200:203], v[60:63], v[40:43]
	v_mfma_f32_16x16x32_bf16 v[96:99], v[204:207], v[238:241], v[24:27]
	v_mfma_f32_16x16x32_bf16 v[24:27], v[180:183], v[242:245], v[44:47]
	v_mfma_f32_16x16x32_bf16 v[84:87], v[196:199], v[246:249], v[24:27]
	v_mfma_f32_16x16x32_bf16 v[24:27], v[200:203], v[242:245], v[48:51]
	v_mfma_f32_16x16x32_bf16 v[80:83], v[204:207], v[246:249], v[24:27]
	v_mfma_f32_16x16x32_bf16 v[24:27], v[180:183], v[176:179], v[52:55]
	v_mfma_f32_16x16x32_bf16 v[68:71], v[196:199], v[150:153], v[24:27]
	v_mfma_f32_16x16x32_bf16 v[24:27], v[200:203], v[176:179], v[56:59]
	v_mfma_f32_16x16x32_bf16 v[116:119], v[196:199], v[28:31], v[64:67]
	v_mfma_f32_16x16x32_bf16 v[64:67], v[204:207], v[150:153], v[24:27]
	s_setprio 1
	s_barrier
	s_mov_b32 m0, s61
	s_nop 2
	v_lshl_add_u64 v[24:25], v[162:163], 0, s[10:11]
	s_add_u32 s28, s34, 0x10080
	ds_read_b128 v[32:35], v167 offset:49152
	ds_read_b128 v[36:39], v167 offset:50176
	ds_read_b128 v[150:153], v167 offset:51200
	ds_read_b128 v[176:179], v167 offset:52224
	ds_read_b128 v[222:225], v167 offset:53248
	ds_read_b128 v[226:229], v167 offset:54272
	ds_read_b128 v[238:241], v167 offset:55296
	ds_read_b128 v[242:245], v167 offset:56320
	global_load_lds_dwordx4 v[24:25], off
	v_lshl_add_u64 v[24:25], v[210:211], 0, s[10:11]
	s_mov_b32 m0, s59
	s_addc_u32 s29, s35, 0
	global_load_lds_dwordx4 v[24:25], off
	v_lshl_add_u64 v[24:25], s[28:29], 0, v[144:145]
	s_mov_b32 m0, s30
	s_nop 0
	global_load_lds_dwordx4 v[24:25], off
	v_lshl_add_u64 v[24:25], s[28:29], 0, v[140:141]
	s_mov_b32 m0, s31
	s_nop 0
	global_load_lds_dwordx4 v[24:25], off
	v_lshl_add_u64 v[24:25], v[250:251], 0, s[10:11]
	s_mov_b32 m0, s50
	s_nop 0
	global_load_lds_dwordx4 v[24:25], off
	v_lshl_add_u64 v[24:25], v[212:213], 0, s[10:11]
	s_mov_b32 m0, s51
	s_nop 0
	global_load_lds_dwordx4 v[24:25], off
	s_waitcnt vmcnt(8)
	s_waitcnt lgkmcnt(0)
	s_barrier
	s_setprio 0
	s_waitcnt lgkmcnt(0)
	v_mfma_f32_16x16x32_bf16 v[24:27], v[8:11], v[32:35], v[214:217]
	v_mfma_f32_16x16x32_bf16 v[60:63], v[12:15], v[36:39], v[24:27]
	v_mfma_f32_16x16x32_bf16 v[24:27], v[16:19], v[32:35], v[132:135]
	v_mfma_f32_16x16x32_bf16 v[56:59], v[20:23], v[36:39], v[24:27]
	v_mfma_f32_16x16x32_bf16 v[24:27], v[8:11], v[150:153], v[136:139]
	v_mfma_f32_16x16x32_bf16 v[44:47], v[12:15], v[176:179], v[24:27]
	v_mfma_f32_16x16x32_bf16 v[24:27], v[16:19], v[150:153], v[154:157]
	v_mfma_f32_16x16x32_bf16 v[40:43], v[20:23], v[176:179], v[24:27]
	v_mfma_f32_16x16x32_bf16 v[24:27], v[8:11], v[222:225], v[158:161]
	v_mfma_f32_16x16x32_bf16 v[0:3], v[8:11], v[238:241], v[0:3]
	v_mfma_f32_16x16x32_bf16 v[28:31], v[12:15], v[226:229], v[24:27]
	v_mfma_f32_16x16x32_bf16 v[24:27], v[16:19], v[222:225], v[168:171]
	v_mfma_f32_16x16x32_bf16 v[12:15], v[12:15], v[242:245], v[0:3]
	v_mfma_f32_16x16x32_bf16 v[0:3], v[16:19], v[238:241], v[4:7]
	v_mfma_f32_16x16x32_bf16 v[24:27], v[20:23], v[226:229], v[24:27]
	v_mfma_f32_16x16x32_bf16 v[8:11], v[20:23], v[242:245], v[0:3]
	s_setprio 1
	s_setprio 0
	v_mfma_f32_16x16x32_bf16 v[0:3], v[180:183], v[32:35], v[218:221]
	v_mfma_f32_16x16x32_bf16 v[52:55], v[196:199], v[36:39], v[0:3]
	v_mfma_f32_16x16x32_bf16 v[0:3], v[200:203], v[32:35], v[230:233]
	v_mfma_f32_16x16x32_bf16 v[48:51], v[204:207], v[36:39], v[0:3]
	v_mfma_f32_16x16x32_bf16 v[0:3], v[180:183], v[150:153], v[234:237]
	v_mfma_f32_16x16x32_bf16 v[36:39], v[196:199], v[176:179], v[0:3]
	v_mfma_f32_16x16x32_bf16 v[0:3], v[200:203], v[150:153], v[184:187]
	v_mfma_f32_16x16x32_bf16 v[32:35], v[204:207], v[176:179], v[0:3]
	v_mfma_f32_16x16x32_bf16 v[0:3], v[180:183], v[222:225], v[188:191]
	v_mfma_f32_16x16x32_bf16 v[20:23], v[196:199], v[226:229], v[0:3]
	v_mfma_f32_16x16x32_bf16 v[0:3], v[200:203], v[222:225], v[192:195]
	v_mfma_f32_16x16x32_bf16 v[16:19], v[204:207], v[226:229], v[0:3]
	v_mfma_f32_16x16x32_bf16 v[0:3], v[180:183], v[238:241], v[124:127]
	v_mfma_f32_16x16x32_bf16 v[4:7], v[196:199], v[242:245], v[0:3]
	v_mfma_f32_16x16x32_bf16 v[0:3], v[200:203], v[238:241], v[172:175]
	v_mfma_f32_16x16x32_bf16 v[0:3], v[204:207], v[242:245], v[0:3]
	s_setprio 1
	s_barrier
	s_andn2_b64 vcc, exec, s[12:13]
	s_cbranch_vccnz .LBB0_545
	s_barrier

.LBB0_620:
	s_add_u32 s4, s2, 0xfffc0080
	s_addc_u32 s5, s3, -1
	s_add_i32 s55, 0, 0x10000
	s_cmp_eq_u32 s54, 12
	s_cselect_b32 s9, s11, s5
	s_cselect_b32 s8, s25, s4
	v_add_u32_e32 v0, s55, v167
	s_cselect_b32 s5, s23, s53
	s_cselect_b32 s4, s51, s52
	s_add_i32 s58, 0, 0x14000
	ds_read_b128 v[106:109], v0
	ds_read_b128 v[110:113], v0 offset:1024
	ds_read_b128 v[114:117], v0 offset:2048
	ds_read_b128 v[118:121], v0 offset:3072
	v_add_u32_e32 v0, s58, v167
	ds_read_b128 v[146:149], v0
	ds_read_b128 v[150:153], v0 offset:1024
	ds_read_b128 v[170:173], v0 offset:2048
	ds_read_b128 v[174:177], v0 offset:3072
	v_lshl_add_u64 v[194:195], s[2:3], 0, v[162:163]
	s_add_i32 m0, s37, 0xc000
	ds_read_b128 v[178:181], v169
	ds_read_b128 v[182:185], v169 offset:1024
	ds_read_b128 v[186:189], v169 offset:2048
	ds_read_b128 v[190:193], v169 offset:3072
	ds_read_b128 v[202:205], v169 offset:4096
	ds_read_b128 v[214:217], v169 offset:5120
	ds_read_b128 v[224:227], v169 offset:6144
	ds_read_b128 v[228:231], v169 offset:7168
	global_load_lds_dwordx4 v[194:195], off
	v_lshl_add_u64 v[194:195], s[2:3], 0, v[164:165]
	s_add_i32 m0, s37, 0xe000
	s_nop 0
	global_load_lds_dwordx4 v[194:195], off
	s_waitcnt vmcnt(8)
	s_waitcnt lgkmcnt(0)
	s_barrier
	s_setprio 0
	s_waitcnt lgkmcnt(0)
	v_mfma_f32_16x16x32_bf16 v[62:65], v[106:109], v[178:181], v[62:65]
	v_mfma_f32_16x16x32_bf16 v[58:61], v[114:117], v[178:181], v[58:61]
	v_mfma_f32_16x16x32_bf16 v[54:57], v[106:109], v[186:189], v[54:57]
	v_mfma_f32_16x16x32_bf16 v[50:53], v[114:117], v[186:189], v[50:53]
	v_mfma_f32_16x16x32_bf16 v[46:49], v[106:109], v[202:205], v[46:49]
	v_mfma_f32_16x16x32_bf16 v[42:45], v[114:117], v[202:205], v[42:45]
	v_mfma_f32_16x16x32_bf16 v[38:41], v[106:109], v[224:227], v[38:41]
	v_mfma_f32_16x16x32_bf16 v[34:37], v[114:117], v[224:227], v[34:37]
	v_mfma_f32_16x16x32_bf16 v[62:65], v[110:113], v[182:185], v[62:65]
	v_mfma_f32_16x16x32_bf16 v[58:61], v[118:121], v[182:185], v[58:61]
	v_mfma_f32_16x16x32_bf16 v[54:57], v[110:113], v[190:193], v[54:57]
	v_mfma_f32_16x16x32_bf16 v[50:53], v[118:121], v[190:193], v[50:53]
	v_mfma_f32_16x16x32_bf16 v[46:49], v[110:113], v[214:217], v[46:49]
	v_mfma_f32_16x16x32_bf16 v[42:45], v[118:121], v[214:217], v[42:45]
	v_mfma_f32_16x16x32_bf16 v[38:41], v[110:113], v[228:231], v[38:41]
	v_mfma_f32_16x16x32_bf16 v[34:37], v[118:121], v[228:231], v[34:37]
	s_setprio 1
	s_setprio 0
	v_mfma_f32_16x16x32_bf16 v[142:145], v[146:149], v[178:181], v[142:145]
	v_mfma_f32_16x16x32_bf16 v[138:141], v[170:173], v[178:181], v[138:141]
	v_mfma_f32_16x16x32_bf16 v[134:137], v[146:149], v[186:189], v[134:137]
	v_mfma_f32_16x16x32_bf16 v[130:133], v[170:173], v[186:189], v[130:133]
	v_mfma_f32_16x16x32_bf16 v[126:129], v[146:149], v[202:205], v[126:129]
	v_mfma_f32_16x16x32_bf16 v[122:125], v[170:173], v[202:205], v[122:125]
	v_mfma_f32_16x16x32_bf16 v[102:105], v[146:149], v[224:227], v[102:105]
	v_mfma_f32_16x16x32_bf16 v[98:101], v[170:173], v[224:227], v[98:101]
	v_mfma_f32_16x16x32_bf16 v[142:145], v[150:153], v[182:185], v[142:145]
	v_mfma_f32_16x16x32_bf16 v[138:141], v[174:177], v[182:185], v[138:141]
	v_mfma_f32_16x16x32_bf16 v[134:137], v[150:153], v[190:193], v[134:137]
	v_mfma_f32_16x16x32_bf16 v[130:133], v[174:177], v[190:193], v[130:133]
	v_mfma_f32_16x16x32_bf16 v[126:129], v[150:153], v[214:217], v[126:129]
	v_mfma_f32_16x16x32_bf16 v[122:125], v[174:177], v[214:217], v[122:125]
	v_mfma_f32_16x16x32_bf16 v[102:105], v[150:153], v[228:231], v[102:105]
	v_mfma_f32_16x16x32_bf16 v[98:101], v[174:177], v[228:231], v[98:101]
	s_setprio 1
	s_barrier
	s_add_i32 s55, s55, s36
	v_lshl_add_u64 v[194:195], s[4:5], 0, v[158:159]
	s_mov_b32 m0, s55
	ds_read_b128 v[178:181], v169 offset:16384
	ds_read_b128 v[182:185], v169 offset:17408
	ds_read_b128 v[186:189], v169 offset:18432
	ds_read_b128 v[190:193], v169 offset:19456
	ds_read_b128 v[202:205], v169 offset:20480
	ds_read_b128 v[214:217], v169 offset:21504
	ds_read_b128 v[224:227], v169 offset:22528
	ds_read_b128 v[228:231], v169 offset:23552
	global_load_lds_dwordx4 v[194:195], off
	s_add_i32 m0, s55, 0x2000
	s_add_u32 s56, s4, 0x40000
	v_lshl_add_u64 v[196:197], s[4:5], 0, v[154:155]
	s_addc_u32 s57, s5, 0
	s_add_i32 s55, s58, s36
	global_load_lds_dwordx4 v[196:197], off
	v_lshl_add_u64 v[198:199], s[56:57], 0, v[158:159]
	s_mov_b32 m0, s55
	v_lshl_add_u64 v[200:201], s[8:9], 0, v[156:157]
	global_load_lds_dwordx4 v[198:199], off
	v_lshl_add_u64 v[198:199], s[56:57], 0, v[154:155]
	s_add_i32 m0, s55, 0x2000
	s_nop 0
	global_load_lds_dwordx4 v[198:199], off
	v_lshl_add_u64 v[198:199], s[8:9], 0, v[160:161]
	s_mov_b32 m0, s37
	s_nop 0
	global_load_lds_dwordx4 v[198:199], off
	s_mov_b32 m0, s38
	s_nop 0
	global_load_lds_dwordx4 v[200:201], off
	s_waitcnt vmcnt(8)
	s_waitcnt lgkmcnt(0)
	s_barrier
	s_setprio 0
	s_waitcnt lgkmcnt(0)
	v_mfma_f32_16x16x32_bf16 v[30:33], v[106:109], v[178:181], v[30:33]
	v_mfma_f32_16x16x32_bf16 v[26:29], v[114:117], v[178:181], v[26:29]
	v_mfma_f32_16x16x32_bf16 v[22:25], v[106:109], v[186:189], v[22:25]
	v_mfma_f32_16x16x32_bf16 v[18:21], v[114:117], v[186:189], v[18:21]
	v_mfma_f32_16x16x32_bf16 v[14:17], v[106:109], v[202:205], v[14:17]
	v_mfma_f32_16x16x32_bf16 v[10:13], v[114:117], v[202:205], v[10:13]
	v_mfma_f32_16x16x32_bf16 v[6:9], v[106:109], v[224:227], v[6:9]
	v_mfma_f32_16x16x32_bf16 v[2:5], v[114:117], v[224:227], v[2:5]
	v_mfma_f32_16x16x32_bf16 v[30:33], v[110:113], v[182:185], v[30:33]
	v_mfma_f32_16x16x32_bf16 v[26:29], v[118:121], v[182:185], v[26:29]
	v_mfma_f32_16x16x32_bf16 v[22:25], v[110:113], v[190:193], v[22:25]
	v_mfma_f32_16x16x32_bf16 v[18:21], v[118:121], v[190:193], v[18:21]
	v_mfma_f32_16x16x32_bf16 v[14:17], v[110:113], v[214:217], v[14:17]
	v_mfma_f32_16x16x32_bf16 v[10:13], v[118:121], v[214:217], v[10:13]
	v_mfma_f32_16x16x32_bf16 v[6:9], v[110:113], v[228:231], v[6:9]
	v_mfma_f32_16x16x32_bf16 v[2:5], v[118:121], v[228:231], v[2:5]
	s_setprio 1
	s_setprio 0
	v_mfma_f32_16x16x32_bf16 v[94:97], v[146:149], v[178:181], v[94:97]
	v_mfma_f32_16x16x32_bf16 v[90:93], v[170:173], v[178:181], v[90:93]
	v_mfma_f32_16x16x32_bf16 v[86:89], v[146:149], v[186:189], v[86:89]
	v_mfma_f32_16x16x32_bf16 v[82:85], v[170:173], v[186:189], v[82:85]
	v_mfma_f32_16x16x32_bf16 v[78:81], v[146:149], v[202:205], v[78:81]
	v_mfma_f32_16x16x32_bf16 v[74:77], v[170:173], v[202:205], v[74:77]
	v_mfma_f32_16x16x32_bf16 v[70:73], v[146:149], v[224:227], v[70:73]
	v_mfma_f32_16x16x32_bf16 v[66:69], v[170:173], v[224:227], v[66:69]
	v_mfma_f32_16x16x32_bf16 v[94:97], v[150:153], v[182:185], v[94:97]
	v_mfma_f32_16x16x32_bf16 v[90:93], v[174:177], v[182:185], v[90:93]
	v_mfma_f32_16x16x32_bf16 v[86:89], v[150:153], v[190:193], v[86:89]
	v_mfma_f32_16x16x32_bf16 v[82:85], v[174:177], v[190:193], v[82:85]
	v_mfma_f32_16x16x32_bf16 v[78:81], v[150:153], v[214:217], v[78:81]
	v_mfma_f32_16x16x32_bf16 v[74:77], v[174:177], v[214:217], v[74:77]
	v_mfma_f32_16x16x32_bf16 v[70:73], v[150:153], v[228:231], v[70:73]
	v_mfma_f32_16x16x32_bf16 v[66:69], v[174:177], v[228:231], v[66:69]
	s_setprio 1
	s_barrier
	s_add_i32 s55, 0, 0x18000
	v_add_u32_e32 v0, s55, v167
	s_add_i32 s56, 0, 0x1c000
	ds_read_b128 v[106:109], v0
	ds_read_b128 v[110:113], v0 offset:1024
	ds_read_b128 v[114:117], v0 offset:2048
	ds_read_b128 v[118:121], v0 offset:3072
	v_add_u32_e32 v0, s56, v167
	ds_read_b128 v[146:149], v0
	ds_read_b128 v[150:153], v0 offset:1024
	ds_read_b128 v[170:173], v0 offset:2048
	ds_read_b128 v[174:177], v0 offset:3072
	s_add_u32 s8, s8, 0x40000
	s_addc_u32 s9, s9, 0
	s_mov_b32 m0, s39
	v_lshl_add_u64 v[206:207], s[8:9], 0, v[160:161]
	ds_read_b128 v[178:181], v169 offset:32768
	ds_read_b128 v[182:185], v169 offset:33792
	ds_read_b128 v[186:189], v169 offset:34816
	ds_read_b128 v[190:193], v169 offset:35840
	ds_read_b128 v[202:205], v169 offset:36864
	ds_read_b128 v[214:217], v169 offset:37888
	ds_read_b128 v[224:227], v169 offset:38912
	ds_read_b128 v[228:231], v169 offset:39936
	global_load_lds_dwordx4 v[206:207], off
	v_lshl_add_u64 v[206:207], s[8:9], 0, v[156:157]
	s_mov_b32 m0, s40
	s_nop 0
	global_load_lds_dwordx4 v[206:207], off
	s_waitcnt vmcnt(8)
	s_waitcnt lgkmcnt(0)
	s_barrier
	s_setprio 0
	s_waitcnt lgkmcnt(0)
	v_mfma_f32_16x16x32_bf16 v[62:65], v[106:109], v[178:181], v[62:65]
	v_mfma_f32_16x16x32_bf16 v[58:61], v[114:117], v[178:181], v[58:61]
	v_mfma_f32_16x16x32_bf16 v[54:57], v[106:109], v[186:189], v[54:57]
	v_mfma_f32_16x16x32_bf16 v[50:53], v[114:117], v[186:189], v[50:53]
	v_mfma_f32_16x16x32_bf16 v[46:49], v[106:109], v[202:205], v[46:49]
	v_mfma_f32_16x16x32_bf16 v[42:45], v[114:117], v[202:205], v[42:45]
	v_mfma_f32_16x16x32_bf16 v[38:41], v[106:109], v[224:227], v[38:41]
	v_mfma_f32_16x16x32_bf16 v[34:37], v[114:117], v[224:227], v[34:37]
	v_mfma_f32_16x16x32_bf16 v[62:65], v[110:113], v[182:185], v[62:65]
	v_mfma_f32_16x16x32_bf16 v[58:61], v[118:121], v[182:185], v[58:61]
	v_mfma_f32_16x16x32_bf16 v[54:57], v[110:113], v[190:193], v[54:57]
	v_mfma_f32_16x16x32_bf16 v[50:53], v[118:121], v[190:193], v[50:53]
	v_mfma_f32_16x16x32_bf16 v[46:49], v[110:113], v[214:217], v[46:49]
	v_mfma_f32_16x16x32_bf16 v[42:45], v[118:121], v[214:217], v[42:45]
	v_mfma_f32_16x16x32_bf16 v[38:41], v[110:113], v[228:231], v[38:41]
	v_mfma_f32_16x16x32_bf16 v[34:37], v[118:121], v[228:231], v[34:37]
	s_setprio 1
	s_setprio 0
	v_mfma_f32_16x16x32_bf16 v[142:145], v[146:149], v[178:181], v[142:145]
	v_mfma_f32_16x16x32_bf16 v[138:141], v[170:173], v[178:181], v[138:141]
	v_mfma_f32_16x16x32_bf16 v[134:137], v[146:149], v[186:189], v[134:137]
	v_mfma_f32_16x16x32_bf16 v[130:133], v[170:173], v[186:189], v[130:133]
	v_mfma_f32_16x16x32_bf16 v[126:129], v[146:149], v[202:205], v[126:129]
	v_mfma_f32_16x16x32_bf16 v[122:125], v[170:173], v[202:205], v[122:125]
	v_mfma_f32_16x16x32_bf16 v[102:105], v[146:149], v[224:227], v[102:105]
	v_mfma_f32_16x16x32_bf16 v[98:101], v[170:173], v[224:227], v[98:101]
	v_mfma_f32_16x16x32_bf16 v[142:145], v[150:153], v[182:185], v[142:145]
	v_mfma_f32_16x16x32_bf16 v[138:141], v[174:177], v[182:185], v[138:141]
	v_mfma_f32_16x16x32_bf16 v[134:137], v[150:153], v[190:193], v[134:137]
	v_mfma_f32_16x16x32_bf16 v[130:133], v[174:177], v[190:193], v[130:133]
	v_mfma_f32_16x16x32_bf16 v[126:129], v[150:153], v[214:217], v[126:129]
	v_mfma_f32_16x16x32_bf16 v[122:125], v[174:177], v[214:217], v[122:125]
	v_mfma_f32_16x16x32_bf16 v[102:105], v[150:153], v[228:231], v[102:105]
	v_mfma_f32_16x16x32_bf16 v[98:101], v[174:177], v[228:231], v[98:101]
	s_setprio 1
	s_barrier
	s_add_i32 s8, s55, s36
	v_lshl_add_u64 v[194:195], v[194:195], 0, s[94:95]
	s_mov_b32 m0, s8
	ds_read_b128 v[178:181], v169 offset:49152
	ds_read_b128 v[182:185], v169 offset:50176
	ds_read_b128 v[186:189], v169 offset:51200
	ds_read_b128 v[190:193], v169 offset:52224
	ds_read_b128 v[202:205], v169 offset:53248
	ds_read_b128 v[214:217], v169 offset:54272
	ds_read_b128 v[224:227], v169 offset:55296
	ds_read_b128 v[228:231], v169 offset:56320
	global_load_lds_dwordx4 v[194:195], off
	s_add_i32 m0, s8, 0x2000
	s_add_u32 s4, s4, 0x40080
	v_lshl_add_u64 v[194:195], v[196:197], 0, s[94:95]
	s_addc_u32 s5, s5, 0
	s_add_i32 s8, s56, s36
	global_load_lds_dwordx4 v[194:195], off
	v_lshl_add_u64 v[194:195], s[4:5], 0, v[158:159]
	s_mov_b32 m0, s8
	s_nop 0
	global_load_lds_dwordx4 v[194:195], off
	v_lshl_add_u64 v[194:195], s[4:5], 0, v[154:155]
	s_add_i32 m0, s8, 0x2000
	s_nop 0
	global_load_lds_dwordx4 v[194:195], off
	v_lshl_add_u64 v[194:195], v[198:199], 0, s[94:95]
	s_mov_b32 m0, s46
	s_nop 0
	global_load_lds_dwordx4 v[194:195], off
	v_lshl_add_u64 v[194:195], v[200:201], 0, s[94:95]
	s_mov_b32 m0, s47
	s_nop 0
	global_load_lds_dwordx4 v[194:195], off
	s_waitcnt vmcnt(8)
	s_waitcnt lgkmcnt(0)
	s_barrier
	s_setprio 0
	s_waitcnt lgkmcnt(0)
	v_mfma_f32_16x16x32_bf16 v[30:33], v[106:109], v[178:181], v[30:33]
	v_mfma_f32_16x16x32_bf16 v[26:29], v[114:117], v[178:181], v[26:29]
	v_mfma_f32_16x16x32_bf16 v[22:25], v[106:109], v[186:189], v[22:25]
	v_mfma_f32_16x16x32_bf16 v[18:21], v[114:117], v[186:189], v[18:21]
	v_mfma_f32_16x16x32_bf16 v[14:17], v[106:109], v[202:205], v[14:17]
	v_mfma_f32_16x16x32_bf16 v[10:13], v[114:117], v[202:205], v[10:13]
	v_mfma_f32_16x16x32_bf16 v[6:9], v[106:109], v[224:227], v[6:9]
	v_mfma_f32_16x16x32_bf16 v[2:5], v[114:117], v[224:227], v[2:5]
	v_mfma_f32_16x16x32_bf16 v[30:33], v[110:113], v[182:185], v[30:33]
	v_mfma_f32_16x16x32_bf16 v[26:29], v[118:121], v[182:185], v[26:29]
	v_mfma_f32_16x16x32_bf16 v[22:25], v[110:113], v[190:193], v[22:25]
	v_mfma_f32_16x16x32_bf16 v[18:21], v[118:121], v[190:193], v[18:21]
	v_mfma_f32_16x16x32_bf16 v[14:17], v[110:113], v[214:217], v[14:17]
	v_mfma_f32_16x16x32_bf16 v[10:13], v[118:121], v[214:217], v[10:13]
	v_mfma_f32_16x16x32_bf16 v[6:9], v[110:113], v[228:231], v[6:9]
	v_mfma_f32_16x16x32_bf16 v[2:5], v[118:121], v[228:231], v[2:5]
	s_setprio 1
	s_setprio 0
	v_mfma_f32_16x16x32_bf16 v[94:97], v[146:149], v[178:181], v[94:97]
	v_mfma_f32_16x16x32_bf16 v[90:93], v[170:173], v[178:181], v[90:93]
	v_mfma_f32_16x16x32_bf16 v[86:89], v[146:149], v[186:189], v[86:89]
	v_mfma_f32_16x16x32_bf16 v[82:85], v[170:173], v[186:189], v[82:85]
	v_mfma_f32_16x16x32_bf16 v[78:81], v[146:149], v[202:205], v[78:81]
	v_mfma_f32_16x16x32_bf16 v[74:77], v[170:173], v[202:205], v[74:77]
	v_mfma_f32_16x16x32_bf16 v[70:73], v[146:149], v[224:227], v[70:73]
	v_mfma_f32_16x16x32_bf16 v[66:69], v[170:173], v[224:227], v[66:69]
	v_mfma_f32_16x16x32_bf16 v[94:97], v[150:153], v[182:185], v[94:97]
	v_mfma_f32_16x16x32_bf16 v[90:93], v[174:177], v[182:185], v[90:93]
	v_mfma_f32_16x16x32_bf16 v[86:89], v[150:153], v[190:193], v[86:89]
	v_mfma_f32_16x16x32_bf16 v[82:85], v[174:177], v[190:193], v[82:85]
	v_mfma_f32_16x16x32_bf16 v[78:81], v[150:153], v[214:217], v[78:81]
	v_mfma_f32_16x16x32_bf16 v[74:77], v[174:177], v[214:217], v[74:77]
	v_mfma_f32_16x16x32_bf16 v[70:73], v[150:153], v[228:231], v[70:73]
	v_mfma_f32_16x16x32_bf16 v[66:69], v[174:177], v[228:231], v[66:69]
	s_setprio 1
	s_barrier
	s_add_i32 s54, s54, 2
	s_add_u32 s2, s2, 0x100
	s_addc_u32 s3, s3, 0
	s_add_u32 s52, s52, 0x100
	s_addc_u32 s53, s53, 0
	s_cmp_gt_u32 s54, 13
	s_cbranch_scc0 .LBB0_620
	s_and_b64 vcc, exec, s[18:19]
	s_cbranch_vccz .LBB0_623
	s_barrier

.Lp8_j0:
	s_waitcnt lgkmcnt(0)
	s_barrier
	s_setprio 0
	s_waitcnt lgkmcnt(0)
	v_mfma_f32_16x16x32_bf16 v[126:129], v[136:139], v[172:175], v[126:129]
	v_mfma_f32_16x16x32_bf16 v[122:125], v[144:147], v[172:175], v[122:125]
	v_mfma_f32_16x16x32_bf16 v[114:117], v[136:139], v[180:183], v[114:117]
	v_mfma_f32_16x16x32_bf16 v[106:109], v[144:147], v[180:183], v[106:109]
	v_mfma_f32_16x16x32_bf16 v[98:101], v[136:139], v[188:191], v[98:101]
	v_mfma_f32_16x16x32_bf16 v[90:93], v[144:147], v[188:191], v[90:93]
	v_mfma_f32_16x16x32_bf16 v[82:85], v[136:139], v[202:205], v[82:85]
	v_mfma_f32_16x16x32_bf16 v[74:77], v[144:147], v[202:205], v[74:77]
	v_mfma_f32_16x16x32_bf16 v[126:129], v[140:143], v[176:179], v[126:129]
	v_mfma_f32_16x16x32_bf16 v[122:125], v[148:151], v[176:179], v[122:125]
	v_mfma_f32_16x16x32_bf16 v[114:117], v[140:143], v[184:187], v[114:117]
	v_mfma_f32_16x16x32_bf16 v[106:109], v[148:151], v[184:187], v[106:109]
	v_mfma_f32_16x16x32_bf16 v[98:101], v[140:143], v[192:195], v[98:101]
	v_mfma_f32_16x16x32_bf16 v[90:93], v[148:151], v[192:195], v[90:93]
	v_mfma_f32_16x16x32_bf16 v[82:85], v[140:143], v[214:217], v[82:85]
	v_mfma_f32_16x16x32_bf16 v[74:77], v[148:151], v[214:217], v[74:77]
	s_setprio 1
	s_setprio 0
	v_mfma_f32_16x16x32_bf16 v[118:121], v[152:155], v[172:175], v[118:121]
	v_mfma_f32_16x16x32_bf16 v[110:113], v[160:163], v[172:175], v[110:113]
	v_mfma_f32_16x16x32_bf16 v[102:105], v[152:155], v[180:183], v[102:105]
	v_mfma_f32_16x16x32_bf16 v[94:97], v[160:163], v[180:183], v[94:97]
	v_mfma_f32_16x16x32_bf16 v[86:89], v[152:155], v[188:191], v[86:89]
	v_mfma_f32_16x16x32_bf16 v[78:81], v[160:163], v[188:191], v[78:81]
	v_mfma_f32_16x16x32_bf16 v[70:73], v[152:155], v[202:205], v[70:73]
	v_mfma_f32_16x16x32_bf16 v[66:69], v[160:163], v[202:205], v[66:69]
	v_mfma_f32_16x16x32_bf16 v[118:121], v[156:159], v[176:179], v[118:121]
	v_mfma_f32_16x16x32_bf16 v[110:113], v[168:171], v[176:179], v[110:113]
	v_mfma_f32_16x16x32_bf16 v[102:105], v[156:159], v[184:187], v[102:105]
	v_mfma_f32_16x16x32_bf16 v[94:97], v[168:171], v[184:187], v[94:97]
	v_mfma_f32_16x16x32_bf16 v[86:89], v[156:159], v[192:195], v[86:89]
	v_mfma_f32_16x16x32_bf16 v[78:81], v[168:171], v[192:195], v[78:81]
	v_mfma_f32_16x16x32_bf16 v[70:73], v[156:159], v[214:217], v[70:73]
	v_mfma_f32_16x16x32_bf16 v[66:69], v[168:171], v[214:217], v[66:69]
	s_setprio 1
	s_barrier
	s_add_i32 s49, s49, s28
	v_lshl_add_u64 v[164:165], s[20:21], 0, v[0:1]
	s_mov_b32 m0, s49
	ds_read_b128 v[172:175], v167 offset:16384
	ds_read_b128 v[176:179], v167 offset:17408
	ds_read_b128 v[180:183], v167 offset:18432
	ds_read_b128 v[184:187], v167 offset:19456
	ds_read_b128 v[188:191], v167 offset:20480
	ds_read_b128 v[192:195], v167 offset:21504
	ds_read_b128 v[202:205], v167 offset:22528
	ds_read_b128 v[214:217], v167 offset:23552
	global_load_lds_dwordx4 v[164:165], off
	s_add_i32 m0, s49, 0x2000
	s_add_u32 s50, s20, 0x40000
	v_lshl_add_u64 v[196:197], s[20:21], 0, v[130:131]
	s_addc_u32 s51, s21, 0
	s_add_i32 s49, s52, s28
	global_load_lds_dwordx4 v[196:197], off
	v_lshl_add_u64 v[198:199], s[50:51], 0, v[0:1]
	s_mov_b32 m0, s49
	v_lshl_add_u64 v[200:201], s[22:23], 0, v[130:131]
	global_load_lds_dwordx4 v[198:199], off
	v_lshl_add_u64 v[198:199], s[50:51], 0, v[130:131]
	s_add_i32 m0, s49, 0x2000
	s_nop 0
	global_load_lds_dwordx4 v[198:199], off
	v_lshl_add_u64 v[198:199], s[22:23], 0, v[0:1]
	s_mov_b32 m0, s29
	s_nop 0
	global_load_lds_dwordx4 v[198:199], off
	s_mov_b32 m0, s30
	s_nop 0
	global_load_lds_dwordx4 v[200:201], off
	s_cmp_eq_u32 s48, -2
	s_cbranch_scc1 .Lp8_f1
	s_waitcnt vmcnt(8)
	s_branch .Lp8_j1

.Lp8_j1:
	s_waitcnt lgkmcnt(0)
	s_barrier
	s_setprio 0
	s_waitcnt lgkmcnt(0)
	v_mfma_f32_16x16x32_bf16 v[62:65], v[136:139], v[172:175], v[62:65]
	v_mfma_f32_16x16x32_bf16 v[58:61], v[144:147], v[172:175], v[58:61]
	v_mfma_f32_16x16x32_bf16 v[50:53], v[136:139], v[180:183], v[50:53]
	v_mfma_f32_16x16x32_bf16 v[42:45], v[144:147], v[180:183], v[42:45]
	v_mfma_f32_16x16x32_bf16 v[34:37], v[136:139], v[188:191], v[34:37]
	v_mfma_f32_16x16x32_bf16 v[26:29], v[144:147], v[188:191], v[26:29]
	v_mfma_f32_16x16x32_bf16 v[18:21], v[136:139], v[202:205], v[18:21]
	v_mfma_f32_16x16x32_bf16 v[10:13], v[144:147], v[202:205], v[10:13]
	v_mfma_f32_16x16x32_bf16 v[62:65], v[140:143], v[176:179], v[62:65]
	v_mfma_f32_16x16x32_bf16 v[58:61], v[148:151], v[176:179], v[58:61]
	v_mfma_f32_16x16x32_bf16 v[50:53], v[140:143], v[184:187], v[50:53]
	v_mfma_f32_16x16x32_bf16 v[42:45], v[148:151], v[184:187], v[42:45]
	v_mfma_f32_16x16x32_bf16 v[34:37], v[140:143], v[192:195], v[34:37]
	v_mfma_f32_16x16x32_bf16 v[26:29], v[148:151], v[192:195], v[26:29]
	v_mfma_f32_16x16x32_bf16 v[18:21], v[140:143], v[214:217], v[18:21]
	v_mfma_f32_16x16x32_bf16 v[10:13], v[148:151], v[214:217], v[10:13]
	s_setprio 1
	s_setprio 0
	v_mfma_f32_16x16x32_bf16 v[54:57], v[152:155], v[172:175], v[54:57]
	v_mfma_f32_16x16x32_bf16 v[46:49], v[160:163], v[172:175], v[46:49]
	v_mfma_f32_16x16x32_bf16 v[38:41], v[152:155], v[180:183], v[38:41]
	v_mfma_f32_16x16x32_bf16 v[30:33], v[160:163], v[180:183], v[30:33]
	v_mfma_f32_16x16x32_bf16 v[22:25], v[152:155], v[188:191], v[22:25]
	v_mfma_f32_16x16x32_bf16 v[14:17], v[160:163], v[188:191], v[14:17]
	v_mfma_f32_16x16x32_bf16 v[6:9], v[152:155], v[202:205], v[6:9]
	v_mfma_f32_16x16x32_bf16 v[2:5], v[160:163], v[202:205], v[2:5]
	v_mfma_f32_16x16x32_bf16 v[54:57], v[156:159], v[176:179], v[54:57]
	v_mfma_f32_16x16x32_bf16 v[46:49], v[168:171], v[176:179], v[46:49]
	v_mfma_f32_16x16x32_bf16 v[38:41], v[156:159], v[184:187], v[38:41]
	v_mfma_f32_16x16x32_bf16 v[30:33], v[168:171], v[184:187], v[30:33]
	v_mfma_f32_16x16x32_bf16 v[22:25], v[156:159], v[192:195], v[22:25]
	v_mfma_f32_16x16x32_bf16 v[14:17], v[168:171], v[192:195], v[14:17]
	v_mfma_f32_16x16x32_bf16 v[6:9], v[156:159], v[214:217], v[6:9]
	v_mfma_f32_16x16x32_bf16 v[2:5], v[168:171], v[214:217], v[2:5]
	s_setprio 1
	s_barrier
	s_add_i32 s49, 0, 0x18000
	s_add_i32 s50, 0, 0x1c000
	v_add_u32_e32 v148, s49, v166
	v_add_u32_e32 v168, s50, v166
	ds_read_b128 v[136:139], v148
	ds_read_b128 v[140:143], v148 offset:1024
	ds_read_b128 v[144:147], v148 offset:2048
	ds_read_b128 v[148:151], v148 offset:3072
	ds_read_b128 v[152:155], v168
	ds_read_b128 v[156:159], v168 offset:1024
	ds_read_b128 v[160:163], v168 offset:2048
	ds_read_b128 v[168:171], v168 offset:3072
	s_add_u32 s22, s22, 0x40000
	s_addc_u32 s23, s23, 0
	s_mov_b32 m0, s31
	v_lshl_add_u64 v[206:207], s[22:23], 0, v[0:1]
	ds_read_b128 v[172:175], v167 offset:32768
	ds_read_b128 v[176:179], v167 offset:33792
	ds_read_b128 v[180:183], v167 offset:34816
	ds_read_b128 v[184:187], v167 offset:35840
	ds_read_b128 v[188:191], v167 offset:36864
	ds_read_b128 v[192:195], v167 offset:37888
	ds_read_b128 v[202:205], v167 offset:38912
	ds_read_b128 v[214:217], v167 offset:39936
	global_load_lds_dwordx4 v[206:207], off
	v_lshl_add_u64 v[206:207], s[22:23], 0, v[130:131]
	s_mov_b32 m0, s34
	s_nop 0
	global_load_lds_dwordx4 v[206:207], off
	s_waitcnt vmcnt(8)
	s_waitcnt lgkmcnt(0)
	s_barrier
	s_setprio 0
	s_waitcnt lgkmcnt(0)
	v_mfma_f32_16x16x32_bf16 v[126:129], v[136:139], v[172:175], v[126:129]
	v_mfma_f32_16x16x32_bf16 v[122:125], v[144:147], v[172:175], v[122:125]
	v_mfma_f32_16x16x32_bf16 v[114:117], v[136:139], v[180:183], v[114:117]
	v_mfma_f32_16x16x32_bf16 v[106:109], v[144:147], v[180:183], v[106:109]
	v_mfma_f32_16x16x32_bf16 v[98:101], v[136:139], v[188:191], v[98:101]
	v_mfma_f32_16x16x32_bf16 v[90:93], v[144:147], v[188:191], v[90:93]
	v_mfma_f32_16x16x32_bf16 v[82:85], v[136:139], v[202:205], v[82:85]
	v_mfma_f32_16x16x32_bf16 v[74:77], v[144:147], v[202:205], v[74:77]
	v_mfma_f32_16x16x32_bf16 v[126:129], v[140:143], v[176:179], v[126:129]
	v_mfma_f32_16x16x32_bf16 v[122:125], v[148:151], v[176:179], v[122:125]
	v_mfma_f32_16x16x32_bf16 v[114:117], v[140:143], v[184:187], v[114:117]
	v_mfma_f32_16x16x32_bf16 v[106:109], v[148:151], v[184:187], v[106:109]
	v_mfma_f32_16x16x32_bf16 v[98:101], v[140:143], v[192:195], v[98:101]
	v_mfma_f32_16x16x32_bf16 v[90:93], v[148:151], v[192:195], v[90:93]
	v_mfma_f32_16x16x32_bf16 v[82:85], v[140:143], v[214:217], v[82:85]
	v_mfma_f32_16x16x32_bf16 v[74:77], v[148:151], v[214:217], v[74:77]
	s_setprio 1
	s_setprio 0
	v_mfma_f32_16x16x32_bf16 v[118:121], v[152:155], v[172:175], v[118:121]
	v_mfma_f32_16x16x32_bf16 v[110:113], v[160:163], v[172:175], v[110:113]
	v_mfma_f32_16x16x32_bf16 v[102:105], v[152:155], v[180:183], v[102:105]
	v_mfma_f32_16x16x32_bf16 v[94:97], v[160:163], v[180:183], v[94:97]
	v_mfma_f32_16x16x32_bf16 v[86:89], v[152:155], v[188:191], v[86:89]
	v_mfma_f32_16x16x32_bf16 v[78:81], v[160:163], v[188:191], v[78:81]
	v_mfma_f32_16x16x32_bf16 v[70:73], v[152:155], v[202:205], v[70:73]
	v_mfma_f32_16x16x32_bf16 v[66:69], v[160:163], v[202:205], v[66:69]
	v_mfma_f32_16x16x32_bf16 v[118:121], v[156:159], v[176:179], v[118:121]
	v_mfma_f32_16x16x32_bf16 v[110:113], v[168:171], v[176:179], v[110:113]
	v_mfma_f32_16x16x32_bf16 v[102:105], v[156:159], v[184:187], v[102:105]
	v_mfma_f32_16x16x32_bf16 v[94:97], v[168:171], v[184:187], v[94:97]
	v_mfma_f32_16x16x32_bf16 v[86:89], v[156:159], v[192:195], v[86:89]
	v_mfma_f32_16x16x32_bf16 v[78:81], v[168:171], v[192:195], v[78:81]
	v_mfma_f32_16x16x32_bf16 v[70:73], v[156:159], v[214:217], v[70:73]
	v_mfma_f32_16x16x32_bf16 v[66:69], v[168:171], v[214:217], v[66:69]
	s_setprio 1
	s_barrier
	s_add_i32 s22, s49, s28
	v_lshl_add_u64 v[164:165], v[164:165], 0, s[94:95]
	s_mov_b32 m0, s22
	ds_read_b128 v[172:175], v167 offset:49152
	ds_read_b128 v[176:179], v167 offset:50176
	ds_read_b128 v[180:183], v167 offset:51200
	ds_read_b128 v[184:187], v167 offset:52224
	ds_read_b128 v[188:191], v167 offset:53248
	ds_read_b128 v[192:195], v167 offset:54272
	ds_read_b128 v[202:205], v167 offset:55296
	ds_read_b128 v[214:217], v167 offset:56320
	global_load_lds_dwordx4 v[164:165], off
	s_add_i32 m0, s22, 0x2000
	s_add_u32 s20, s20, 0x40080
	v_lshl_add_u64 v[164:165], v[196:197], 0, s[94:95]
	s_addc_u32 s21, s21, 0
	s_add_i32 s22, s50, s28
	global_load_lds_dwordx4 v[164:165], off
	v_lshl_add_u64 v[164:165], s[20:21], 0, v[0:1]
	s_mov_b32 m0, s22
	s_nop 0
	global_load_lds_dwordx4 v[164:165], off
	v_lshl_add_u64 v[164:165], s[20:21], 0, v[130:131]
	s_add_i32 m0, s22, 0x2000
	s_nop 0
	global_load_lds_dwordx4 v[164:165], off
	v_lshl_add_u64 v[164:165], v[198:199], 0, s[94:95]
	s_mov_b32 m0, s37
	s_nop 0
	global_load_lds_dwordx4 v[164:165], off
	v_lshl_add_u64 v[164:165], v[200:201], 0, s[94:95]
	s_mov_b32 m0, s38
	s_nop 0
	global_load_lds_dwordx4 v[164:165], off
	s_waitcnt vmcnt(8)
	s_waitcnt lgkmcnt(0)
	s_barrier
	s_setprio 0
	s_waitcnt lgkmcnt(0)
	v_mfma_f32_16x16x32_bf16 v[62:65], v[136:139], v[172:175], v[62:65]
	v_mfma_f32_16x16x32_bf16 v[58:61], v[144:147], v[172:175], v[58:61]
	v_mfma_f32_16x16x32_bf16 v[50:53], v[136:139], v[180:183], v[50:53]
	v_mfma_f32_16x16x32_bf16 v[42:45], v[144:147], v[180:183], v[42:45]
	v_mfma_f32_16x16x32_bf16 v[34:37], v[136:139], v[188:191], v[34:37]
	v_mfma_f32_16x16x32_bf16 v[26:29], v[144:147], v[188:191], v[26:29]
	v_mfma_f32_16x16x32_bf16 v[18:21], v[136:139], v[202:205], v[18:21]
	v_mfma_f32_16x16x32_bf16 v[10:13], v[144:147], v[202:205], v[10:13]
	v_mfma_f32_16x16x32_bf16 v[62:65], v[140:143], v[176:179], v[62:65]
	v_mfma_f32_16x16x32_bf16 v[58:61], v[148:151], v[176:179], v[58:61]
	v_mfma_f32_16x16x32_bf16 v[50:53], v[140:143], v[184:187], v[50:53]
	v_mfma_f32_16x16x32_bf16 v[42:45], v[148:151], v[184:187], v[42:45]
	v_mfma_f32_16x16x32_bf16 v[34:37], v[140:143], v[192:195], v[34:37]
	v_mfma_f32_16x16x32_bf16 v[26:29], v[148:151], v[192:195], v[26:29]
	v_mfma_f32_16x16x32_bf16 v[18:21], v[140:143], v[214:217], v[18:21]
	v_mfma_f32_16x16x32_bf16 v[10:13], v[148:151], v[214:217], v[10:13]
	s_setprio 1
	s_setprio 0
	v_mfma_f32_16x16x32_bf16 v[54:57], v[152:155], v[172:175], v[54:57]
	v_mfma_f32_16x16x32_bf16 v[46:49], v[160:163], v[172:175], v[46:49]
	v_mfma_f32_16x16x32_bf16 v[38:41], v[152:155], v[180:183], v[38:41]
	v_mfma_f32_16x16x32_bf16 v[30:33], v[160:163], v[180:183], v[30:33]
	v_mfma_f32_16x16x32_bf16 v[22:25], v[152:155], v[188:191], v[22:25]
	v_mfma_f32_16x16x32_bf16 v[14:17], v[160:163], v[188:191], v[14:17]
	v_mfma_f32_16x16x32_bf16 v[6:9], v[152:155], v[202:205], v[6:9]
	v_mfma_f32_16x16x32_bf16 v[2:5], v[160:163], v[202:205], v[2:5]
	v_mfma_f32_16x16x32_bf16 v[54:57], v[156:159], v[176:179], v[54:57]
	v_mfma_f32_16x16x32_bf16 v[46:49], v[168:171], v[176:179], v[46:49]
	v_mfma_f32_16x16x32_bf16 v[38:41], v[156:159], v[184:187], v[38:41]
	v_mfma_f32_16x16x32_bf16 v[30:33], v[168:171], v[184:187], v[30:33]
	v_mfma_f32_16x16x32_bf16 v[22:25], v[156:159], v[192:195], v[22:25]
	v_mfma_f32_16x16x32_bf16 v[14:17], v[168:171], v[192:195], v[14:17]
	v_mfma_f32_16x16x32_bf16 v[6:9], v[156:159], v[214:217], v[6:9]
	v_mfma_f32_16x16x32_bf16 v[2:5], v[168:171], v[214:217], v[2:5]
	s_setprio 1
	s_barrier
	s_add_i32 s48, s48, 2
	s_add_u32 s18, s18, 0x100
	s_addc_u32 s19, s19, 0
	s_add_u32 s46, s46, 0x100
	s_addc_u32 s47, s47, 0
	s_cmp_gt_u32 s48, 13
	s_cbranch_scc0 .LBB0_1008
	s_and_b64 vcc, exec, s[8:9]
	s_cbranch_vccz .LBB0_1011
	s_barrier

.Lp3w_j0:
	s_waitcnt lgkmcnt(0)
	s_barrier
	s_setprio 0
	s_waitcnt lgkmcnt(0)
	v_mfma_f32_16x16x32_bf16 v[126:129], v[144:147], v[176:179], v[126:129]
	v_mfma_f32_16x16x32_bf16 v[118:121], v[152:155], v[176:179], v[118:121]
	v_mfma_f32_16x16x32_bf16 v[110:113], v[144:147], v[184:187], v[110:113]
	v_mfma_f32_16x16x32_bf16 v[102:105], v[152:155], v[184:187], v[102:105]
	v_mfma_f32_16x16x32_bf16 v[94:97], v[144:147], v[192:195], v[94:97]
	v_mfma_f32_16x16x32_bf16 v[86:89], v[152:155], v[192:195], v[86:89]
	v_mfma_f32_16x16x32_bf16 v[78:81], v[144:147], v[214:217], v[78:81]
	v_mfma_f32_16x16x32_bf16 v[70:73], v[152:155], v[214:217], v[70:73]
	v_mfma_f32_16x16x32_bf16 v[126:129], v[148:151], v[180:183], v[126:129]
	v_mfma_f32_16x16x32_bf16 v[118:121], v[156:159], v[180:183], v[118:121]
	v_mfma_f32_16x16x32_bf16 v[110:113], v[148:151], v[188:191], v[110:113]
	v_mfma_f32_16x16x32_bf16 v[102:105], v[156:159], v[188:191], v[102:105]
	v_mfma_f32_16x16x32_bf16 v[94:97], v[148:151], v[202:205], v[94:97]
	v_mfma_f32_16x16x32_bf16 v[86:89], v[156:159], v[202:205], v[86:89]
	v_mfma_f32_16x16x32_bf16 v[78:81], v[148:151], v[224:227], v[78:81]
	v_mfma_f32_16x16x32_bf16 v[70:73], v[156:159], v[224:227], v[70:73]
	s_setprio 1
	s_setprio 0
	v_mfma_f32_16x16x32_bf16 v[122:125], v[160:163], v[176:179], v[122:125]
	v_mfma_f32_16x16x32_bf16 v[114:117], v[168:171], v[176:179], v[114:117]
	v_mfma_f32_16x16x32_bf16 v[106:109], v[160:163], v[184:187], v[106:109]
	v_mfma_f32_16x16x32_bf16 v[98:101], v[168:171], v[184:187], v[98:101]
	v_mfma_f32_16x16x32_bf16 v[90:93], v[160:163], v[192:195], v[90:93]
	v_mfma_f32_16x16x32_bf16 v[82:85], v[168:171], v[192:195], v[82:85]
	v_mfma_f32_16x16x32_bf16 v[74:77], v[160:163], v[214:217], v[74:77]
	v_mfma_f32_16x16x32_bf16 v[66:69], v[168:171], v[214:217], v[66:69]
	v_mfma_f32_16x16x32_bf16 v[122:125], v[164:167], v[180:183], v[122:125]
	v_mfma_f32_16x16x32_bf16 v[114:117], v[172:175], v[180:183], v[114:117]
	v_mfma_f32_16x16x32_bf16 v[106:109], v[164:167], v[188:191], v[106:109]
	v_mfma_f32_16x16x32_bf16 v[98:101], v[172:175], v[188:191], v[98:101]
	v_mfma_f32_16x16x32_bf16 v[90:93], v[164:167], v[202:205], v[90:93]
	v_mfma_f32_16x16x32_bf16 v[82:85], v[172:175], v[202:205], v[82:85]
	v_mfma_f32_16x16x32_bf16 v[74:77], v[164:167], v[224:227], v[74:77]
	v_mfma_f32_16x16x32_bf16 v[66:69], v[172:175], v[224:227], v[66:69]
	s_setprio 1
	s_barrier
	s_add_i32 s54, s54, s37
	v_lshl_add_u64 v[196:197], s[24:25], 0, v[0:1]
	s_mov_b32 m0, s54
	ds_read_b128 v[176:179], v143 offset:16384
	ds_read_b128 v[180:183], v143 offset:17408
	ds_read_b128 v[184:187], v143 offset:18432
	ds_read_b128 v[188:191], v143 offset:19456
	ds_read_b128 v[192:195], v143 offset:20480
	ds_read_b128 v[202:205], v143 offset:21504
	ds_read_b128 v[214:217], v143 offset:22528
	ds_read_b128 v[224:227], v143 offset:23552
	global_load_lds_dwordx4 v[196:197], off
	s_add_i32 m0, s54, 0x2000
	s_add_u32 s54, s24, 0x40000
	v_lshl_add_u64 v[198:199], s[24:25], 0, v[130:131]
	s_addc_u32 s55, s25, 0
	s_add_i32 s56, s56, s37
	global_load_lds_dwordx4 v[198:199], off
	v_lshl_add_u64 v[200:201], s[54:55], 0, v[0:1]
	s_mov_b32 m0, s56
	v_lshl_add_u64 v[206:207], s[26:27], 0, v[132:133]
	global_load_lds_dwordx4 v[200:201], off
	v_lshl_add_u64 v[200:201], s[54:55], 0, v[130:131]
	s_add_i32 m0, s56, 0x2000
	s_nop 0
	global_load_lds_dwordx4 v[200:201], off
	v_lshl_add_u64 v[200:201], s[26:27], 0, v[134:135]
	s_mov_b32 m0, s38
	s_nop 0
	global_load_lds_dwordx4 v[200:201], off
	s_mov_b32 m0, s39
	s_nop 0
	global_load_lds_dwordx4 v[206:207], off
	s_cmp_lg_u32 s53, 12
	s_cbranch_scc1 .Lp3w_nlA
	s_lshl_b32 s56, s47, 8
	s_add_i32 s56, s56, s42
	v_and_b32_e32 v228, 15, v212
	v_lshrrev_b32_e32 v229, 4, v212
	v_or_b32_e32 v228, s56, v228
	v_lshlrev_b32_e32 v228, 6, v228
	v_lshl_add_u32 v230, v229, 4, v228
	v_mov_b32_e32 v231, 0
	v_lshl_add_u64 v[250:251], s[6:7], 0, v[230:231]
	v_mov_b32_e32 v230, 0x2000
	v_lshl_add_u64 v[248:249], v[250:251], 0, v[230:231]
	global_load_dwordx4 v[228:231], v[250:251], off
	global_load_dwordx4 v[232:235], v[250:251], off offset:1024
	global_load_dwordx4 v[236:239], v[250:251], off offset:2048
	global_load_dwordx4 v[240:243], v[250:251], off offset:3072
	global_load_dwordx4 v[244:247], v[248:249], off
	s_nop 0
	global_load_dwordx4 v[248:251], v[248:249], off offset:1024
	s_waitcnt vmcnt(14)
	s_branch .Lp3w_jA

.Lp3w_jA:
	s_waitcnt lgkmcnt(0)
	s_barrier
	s_setprio 0
	s_waitcnt lgkmcnt(0)
	v_mfma_f32_16x16x32_bf16 v[62:65], v[144:147], v[176:179], v[62:65]
	v_mfma_f32_16x16x32_bf16 v[54:57], v[152:155], v[176:179], v[54:57]
	v_mfma_f32_16x16x32_bf16 v[46:49], v[144:147], v[184:187], v[46:49]
	v_mfma_f32_16x16x32_bf16 v[38:41], v[152:155], v[184:187], v[38:41]
	v_mfma_f32_16x16x32_bf16 v[30:33], v[144:147], v[192:195], v[30:33]
	v_mfma_f32_16x16x32_bf16 v[22:25], v[152:155], v[192:195], v[22:25]
	v_mfma_f32_16x16x32_bf16 v[14:17], v[144:147], v[214:217], v[14:17]
	v_mfma_f32_16x16x32_bf16 v[6:9], v[152:155], v[214:217], v[6:9]
	v_mfma_f32_16x16x32_bf16 v[62:65], v[148:151], v[180:183], v[62:65]
	v_mfma_f32_16x16x32_bf16 v[54:57], v[156:159], v[180:183], v[54:57]
	v_mfma_f32_16x16x32_bf16 v[46:49], v[148:151], v[188:191], v[46:49]
	v_mfma_f32_16x16x32_bf16 v[38:41], v[156:159], v[188:191], v[38:41]
	v_mfma_f32_16x16x32_bf16 v[30:33], v[148:151], v[202:205], v[30:33]
	v_mfma_f32_16x16x32_bf16 v[22:25], v[156:159], v[202:205], v[22:25]
	v_mfma_f32_16x16x32_bf16 v[14:17], v[148:151], v[224:227], v[14:17]
	v_mfma_f32_16x16x32_bf16 v[6:9], v[156:159], v[224:227], v[6:9]
	s_setprio 1
	s_setprio 0
	v_mfma_f32_16x16x32_bf16 v[58:61], v[160:163], v[176:179], v[58:61]
	v_mfma_f32_16x16x32_bf16 v[50:53], v[168:171], v[176:179], v[50:53]
	v_mfma_f32_16x16x32_bf16 v[42:45], v[160:163], v[184:187], v[42:45]
	v_mfma_f32_16x16x32_bf16 v[34:37], v[168:171], v[184:187], v[34:37]
	v_mfma_f32_16x16x32_bf16 v[26:29], v[160:163], v[192:195], v[26:29]
	v_mfma_f32_16x16x32_bf16 v[18:21], v[168:171], v[192:195], v[18:21]
	v_mfma_f32_16x16x32_bf16 v[10:13], v[160:163], v[214:217], v[10:13]
	v_mfma_f32_16x16x32_bf16 v[2:5], v[168:171], v[214:217], v[2:5]
	v_mfma_f32_16x16x32_bf16 v[58:61], v[164:167], v[180:183], v[58:61]
	v_mfma_f32_16x16x32_bf16 v[50:53], v[172:175], v[180:183], v[50:53]
	v_mfma_f32_16x16x32_bf16 v[42:45], v[164:167], v[188:191], v[42:45]
	v_mfma_f32_16x16x32_bf16 v[34:37], v[172:175], v[188:191], v[34:37]
	v_mfma_f32_16x16x32_bf16 v[26:29], v[164:167], v[202:205], v[26:29]
	v_mfma_f32_16x16x32_bf16 v[18:21], v[172:175], v[202:205], v[18:21]
	v_mfma_f32_16x16x32_bf16 v[10:13], v[164:167], v[224:227], v[10:13]
	v_mfma_f32_16x16x32_bf16 v[2:5], v[172:175], v[224:227], v[2:5]
	s_setprio 1
	s_barrier
	s_add_i32 s54, 0, 0x18000
	v_add_u32_e32 v140, s54, v141
	s_add_i32 s55, 0, 0x1c000
	ds_read_b128 v[144:147], v140
	ds_read_b128 v[148:151], v140 offset:1024
	ds_read_b128 v[152:155], v140 offset:2048
	ds_read_b128 v[156:159], v140 offset:3072
	v_add_u32_e32 v140, s55, v141
	ds_read_b128 v[160:163], v140
	ds_read_b128 v[164:167], v140 offset:1024
	ds_read_b128 v[168:171], v140 offset:2048
	ds_read_b128 v[172:175], v140 offset:3072
	s_add_u32 s26, s26, 0x40000
	s_addc_u32 s27, s27, 0
	s_mov_b32 m0, s40
	v_lshl_add_u64 v[210:211], s[26:27], 0, v[134:135]
	ds_read_b128 v[176:179], v143 offset:32768
	ds_read_b128 v[180:183], v143 offset:33792
	ds_read_b128 v[184:187], v143 offset:34816
	ds_read_b128 v[188:191], v143 offset:35840
	ds_read_b128 v[192:195], v143 offset:36864
	ds_read_b128 v[202:205], v143 offset:37888
	ds_read_b128 v[214:217], v143 offset:38912
	ds_read_b128 v[224:227], v143 offset:39936
	global_load_lds_dwordx4 v[210:211], off
	v_lshl_add_u64 v[210:211], s[26:27], 0, v[132:133]
	s_mov_b32 m0, s41
	s_nop 0
	global_load_lds_dwordx4 v[210:211], off
	s_cmp_lg_u32 s53, 12
	s_cbranch_scc1 .Lp3w_nlB
	s_waitcnt vmcnt(14)
	s_branch .Lp3w_jB

.Lp3w_jB:
	s_waitcnt lgkmcnt(0)
	s_barrier
	s_setprio 0
	s_waitcnt lgkmcnt(0)
	v_mfma_f32_16x16x32_bf16 v[126:129], v[144:147], v[176:179], v[126:129]
	v_mfma_f32_16x16x32_bf16 v[118:121], v[152:155], v[176:179], v[118:121]
	v_mfma_f32_16x16x32_bf16 v[110:113], v[144:147], v[184:187], v[110:113]
	v_mfma_f32_16x16x32_bf16 v[102:105], v[152:155], v[184:187], v[102:105]
	v_mfma_f32_16x16x32_bf16 v[94:97], v[144:147], v[192:195], v[94:97]
	v_mfma_f32_16x16x32_bf16 v[86:89], v[152:155], v[192:195], v[86:89]
	v_mfma_f32_16x16x32_bf16 v[78:81], v[144:147], v[214:217], v[78:81]
	v_mfma_f32_16x16x32_bf16 v[70:73], v[152:155], v[214:217], v[70:73]
	v_mfma_f32_16x16x32_bf16 v[126:129], v[148:151], v[180:183], v[126:129]
	v_mfma_f32_16x16x32_bf16 v[118:121], v[156:159], v[180:183], v[118:121]
	v_mfma_f32_16x16x32_bf16 v[110:113], v[148:151], v[188:191], v[110:113]
	v_mfma_f32_16x16x32_bf16 v[102:105], v[156:159], v[188:191], v[102:105]
	v_mfma_f32_16x16x32_bf16 v[94:97], v[148:151], v[202:205], v[94:97]
	v_mfma_f32_16x16x32_bf16 v[86:89], v[156:159], v[202:205], v[86:89]
	v_mfma_f32_16x16x32_bf16 v[78:81], v[148:151], v[224:227], v[78:81]
	v_mfma_f32_16x16x32_bf16 v[70:73], v[156:159], v[224:227], v[70:73]
	s_setprio 1
	s_setprio 0
	v_mfma_f32_16x16x32_bf16 v[122:125], v[160:163], v[176:179], v[122:125]
	v_mfma_f32_16x16x32_bf16 v[114:117], v[168:171], v[176:179], v[114:117]
	v_mfma_f32_16x16x32_bf16 v[106:109], v[160:163], v[184:187], v[106:109]
	v_mfma_f32_16x16x32_bf16 v[98:101], v[168:171], v[184:187], v[98:101]
	v_mfma_f32_16x16x32_bf16 v[90:93], v[160:163], v[192:195], v[90:93]
	v_mfma_f32_16x16x32_bf16 v[82:85], v[168:171], v[192:195], v[82:85]
	v_mfma_f32_16x16x32_bf16 v[74:77], v[160:163], v[214:217], v[74:77]
	v_mfma_f32_16x16x32_bf16 v[66:69], v[168:171], v[214:217], v[66:69]
	v_mfma_f32_16x16x32_bf16 v[122:125], v[164:167], v[180:183], v[122:125]
	v_mfma_f32_16x16x32_bf16 v[114:117], v[172:175], v[180:183], v[114:117]
	v_mfma_f32_16x16x32_bf16 v[106:109], v[164:167], v[188:191], v[106:109]
	v_mfma_f32_16x16x32_bf16 v[98:101], v[172:175], v[188:191], v[98:101]
	v_mfma_f32_16x16x32_bf16 v[90:93], v[164:167], v[202:205], v[90:93]
	v_mfma_f32_16x16x32_bf16 v[82:85], v[172:175], v[202:205], v[82:85]
	v_mfma_f32_16x16x32_bf16 v[74:77], v[164:167], v[224:227], v[74:77]
	v_mfma_f32_16x16x32_bf16 v[66:69], v[172:175], v[224:227], v[66:69]
	s_setprio 1
	s_barrier
	s_add_i32 s26, s54, s37
	v_lshl_add_u64 v[196:197], v[196:197], 0, s[94:95]
	s_mov_b32 m0, s26
	ds_read_b128 v[176:179], v143 offset:49152
	ds_read_b128 v[180:183], v143 offset:50176
	ds_read_b128 v[184:187], v143 offset:51200
	ds_read_b128 v[188:191], v143 offset:52224
	ds_read_b128 v[192:195], v143 offset:53248
	ds_read_b128 v[202:205], v143 offset:54272
	ds_read_b128 v[214:217], v143 offset:55296
	ds_read_b128 v[224:227], v143 offset:56320
	global_load_lds_dwordx4 v[196:197], off
	s_add_i32 m0, s26, 0x2000
	s_add_u32 s24, s24, 0x40080
	v_lshl_add_u64 v[196:197], v[198:199], 0, s[94:95]
	s_addc_u32 s25, s25, 0
	s_add_i32 s26, s55, s37
	global_load_lds_dwordx4 v[196:197], off
	v_lshl_add_u64 v[196:197], s[24:25], 0, v[0:1]
	s_mov_b32 m0, s26
	s_nop 0
	global_load_lds_dwordx4 v[196:197], off
	v_lshl_add_u64 v[196:197], s[24:25], 0, v[130:131]
	s_add_i32 m0, s26, 0x2000
	s_nop 0
	global_load_lds_dwordx4 v[196:197], off
	v_lshl_add_u64 v[196:197], v[200:201], 0, s[94:95]
	s_mov_b32 m0, s44
	s_nop 0
	global_load_lds_dwordx4 v[196:197], off
	v_lshl_add_u64 v[196:197], v[206:207], 0, s[94:95]
	s_mov_b32 m0, s45
	s_nop 0
	global_load_lds_dwordx4 v[196:197], off
	s_cmp_lg_u32 s53, 12
	s_cbranch_scc1 .Lp3w_nlC
	s_lshl_b32 s56, s47, 8
	s_add_i32 s56, s56, s42
	v_and_b32_e32 v196, 15, v212
	v_lshrrev_b32_e32 v197, 4, v212
	v_or_b32_e32 v196, s56, v196
	v_lshlrev_b32_e32 v196, 6, v196
	v_lshl_add_u32 v196, v197, 4, v196
	v_add_u32_e32 v196, 0x2800, v196
	v_mov_b32_e32 v197, 0
	v_lshl_add_u64 v[210:211], s[6:7], 0, v[196:197]
	global_load_dwordx4 v[196:199], v[210:211], off
	global_load_dwordx2 v[200:201], v[210:211], off offset:1024
	global_load_dwordx2 v[206:207], v[210:211], off offset:1032
	s_waitcnt vmcnt(17)
	s_branch .Lp3w_jC

.Lp3w_jC:
	s_waitcnt lgkmcnt(0)
	s_barrier
	s_setprio 0
	s_waitcnt lgkmcnt(0)
	v_mfma_f32_16x16x32_bf16 v[62:65], v[144:147], v[176:179], v[62:65]
	v_mfma_f32_16x16x32_bf16 v[54:57], v[152:155], v[176:179], v[54:57]
	v_mfma_f32_16x16x32_bf16 v[46:49], v[144:147], v[184:187], v[46:49]
	v_mfma_f32_16x16x32_bf16 v[38:41], v[152:155], v[184:187], v[38:41]
	v_mfma_f32_16x16x32_bf16 v[30:33], v[144:147], v[192:195], v[30:33]
	v_mfma_f32_16x16x32_bf16 v[22:25], v[152:155], v[192:195], v[22:25]
	v_mfma_f32_16x16x32_bf16 v[14:17], v[144:147], v[214:217], v[14:17]
	v_mfma_f32_16x16x32_bf16 v[6:9], v[152:155], v[214:217], v[6:9]
	v_mfma_f32_16x16x32_bf16 v[62:65], v[148:151], v[180:183], v[62:65]
	v_mfma_f32_16x16x32_bf16 v[54:57], v[156:159], v[180:183], v[54:57]
	v_mfma_f32_16x16x32_bf16 v[46:49], v[148:151], v[188:191], v[46:49]
	v_mfma_f32_16x16x32_bf16 v[38:41], v[156:159], v[188:191], v[38:41]
	v_mfma_f32_16x16x32_bf16 v[30:33], v[148:151], v[202:205], v[30:33]
	v_mfma_f32_16x16x32_bf16 v[22:25], v[156:159], v[202:205], v[22:25]
	v_mfma_f32_16x16x32_bf16 v[14:17], v[148:151], v[224:227], v[14:17]
	v_mfma_f32_16x16x32_bf16 v[6:9], v[156:159], v[224:227], v[6:9]
	s_setprio 1
	s_setprio 0
	v_mfma_f32_16x16x32_bf16 v[58:61], v[160:163], v[176:179], v[58:61]
	v_mfma_f32_16x16x32_bf16 v[50:53], v[168:171], v[176:179], v[50:53]
	v_mfma_f32_16x16x32_bf16 v[42:45], v[160:163], v[184:187], v[42:45]
	v_mfma_f32_16x16x32_bf16 v[34:37], v[168:171], v[184:187], v[34:37]
	v_mfma_f32_16x16x32_bf16 v[26:29], v[160:163], v[192:195], v[26:29]
	v_mfma_f32_16x16x32_bf16 v[18:21], v[168:171], v[192:195], v[18:21]
	v_mfma_f32_16x16x32_bf16 v[10:13], v[160:163], v[214:217], v[10:13]
	v_mfma_f32_16x16x32_bf16 v[2:5], v[168:171], v[214:217], v[2:5]
	v_mfma_f32_16x16x32_bf16 v[58:61], v[164:167], v[180:183], v[58:61]
	v_mfma_f32_16x16x32_bf16 v[50:53], v[172:175], v[180:183], v[50:53]
	v_mfma_f32_16x16x32_bf16 v[42:45], v[164:167], v[188:191], v[42:45]
	v_mfma_f32_16x16x32_bf16 v[34:37], v[172:175], v[188:191], v[34:37]
	v_mfma_f32_16x16x32_bf16 v[26:29], v[164:167], v[202:205], v[26:29]
	v_mfma_f32_16x16x32_bf16 v[18:21], v[172:175], v[202:205], v[18:21]
	v_mfma_f32_16x16x32_bf16 v[10:13], v[164:167], v[224:227], v[10:13]
	v_mfma_f32_16x16x32_bf16 v[2:5], v[172:175], v[224:227], v[2:5]
	s_setprio 1
	s_barrier
	s_add_i32 s53, s53, 2
	s_add_u32 s22, s22, 0x100
	s_addc_u32 s23, s23, 0
	s_add_u32 s51, s51, 0x100
	s_addc_u32 s52, s52, 0
	s_cmp_gt_u32 s53, 13
	s_cbranch_scc0 .LBB0_1083
	v_mov_b32_e32 v140, v212
	s_lshl_b32 s13, s48, 7
	v_and_b32_e32 v153, 15, v140
	v_ashrrev_i32_e32 v140, 4, v140
	s_or_b32 s13, s13, s43
	v_lshl_add_u32 v152, v140, 3, s13
	s_lshl_b32 s13, s47, 8
	s_movk_i32 s15, 0x2000
	v_readlane_b32 s26, v252, 55
	s_and_b64 vcc, exec, s[10:11]
	s_cbranch_vccz .LBB0_1086
	s_barrier

.LBB0_1115:
	s_add_u32 s28, s46, s26
	s_addc_u32 s29, s47, s27
	s_add_u32 s28, s28, 0xc000100
	s_addc_u32 s29, s29, 0
	s_add_u32 s51, s48, s26
	s_addc_u32 s52, s49, s27
	s_add_i32 s53, 0, 0x10000
	s_cmpk_eq_i32 s26, 0x700
	s_cselect_b32 s31, s9, s29
	s_cselect_b32 s30, s8, s28
	s_cselect_b32 s29, s7, s52
	s_cselect_b32 s28, s6, s51
	s_add_i32 s51, 0, 0x14000
	v_add_u32_e32 v154, s53, v116
	v_add_u32_e32 v170, s51, v116
	ds_read_b128 v[118:121], v154
	ds_read_b128 v[146:149], v154 offset:1024
	ds_read_b128 v[150:153], v154 offset:2048
	ds_read_b128 v[154:157], v154 offset:3072
	ds_read_b128 v[158:161], v170
	ds_read_b128 v[162:165], v170 offset:1024
	ds_read_b128 v[166:169], v170 offset:2048
	ds_read_b128 v[170:173], v170 offset:3072
	v_lshl_add_u64 v[182:183], v[112:113], 0, s[26:27]
	s_add_i32 m0, s5, 0xc000
	ds_read_b128 v[174:177], v117
	ds_read_b128 v[178:181], v117 offset:1024
	ds_read_b128 v[186:189], v117 offset:2048
	ds_read_b128 v[190:193], v117 offset:3072
	ds_read_b128 v[194:197], v117 offset:4096
	ds_read_b128 v[198:201], v117 offset:5120
	ds_read_b128 v[202:205], v117 offset:6144
	ds_read_b128 v[214:217], v117 offset:7168
	global_load_lds_dwordx4 v[182:183], off
	v_lshl_add_u64 v[182:183], v[114:115], 0, s[26:27]
	s_add_i32 m0, s5, 0xe000
	s_nop 0
	global_load_lds_dwordx4 v[182:183], off
	s_waitcnt vmcnt(8)
	s_waitcnt lgkmcnt(0)
	s_barrier
	s_setprio 0
	s_waitcnt lgkmcnt(0)
	v_mfma_f32_16x16x32_bf16 v[62:65], v[118:121], v[174:177], v[62:65]
	v_mfma_f32_16x16x32_bf16 v[58:61], v[150:153], v[174:177], v[58:61]
	v_mfma_f32_16x16x32_bf16 v[54:57], v[118:121], v[186:189], v[54:57]
	v_mfma_f32_16x16x32_bf16 v[50:53], v[150:153], v[186:189], v[50:53]
	v_mfma_f32_16x16x32_bf16 v[46:49], v[118:121], v[194:197], v[46:49]
	v_mfma_f32_16x16x32_bf16 v[42:45], v[150:153], v[194:197], v[42:45]
	v_mfma_f32_16x16x32_bf16 v[38:41], v[118:121], v[202:205], v[38:41]
	v_mfma_f32_16x16x32_bf16 v[34:37], v[150:153], v[202:205], v[34:37]
	v_mfma_f32_16x16x32_bf16 v[62:65], v[146:149], v[178:181], v[62:65]
	v_mfma_f32_16x16x32_bf16 v[58:61], v[154:157], v[178:181], v[58:61]
	v_mfma_f32_16x16x32_bf16 v[54:57], v[146:149], v[190:193], v[54:57]
	v_mfma_f32_16x16x32_bf16 v[50:53], v[154:157], v[190:193], v[50:53]
	v_mfma_f32_16x16x32_bf16 v[46:49], v[146:149], v[198:201], v[46:49]
	v_mfma_f32_16x16x32_bf16 v[42:45], v[154:157], v[198:201], v[42:45]
	v_mfma_f32_16x16x32_bf16 v[38:41], v[146:149], v[214:217], v[38:41]
	v_mfma_f32_16x16x32_bf16 v[34:37], v[154:157], v[214:217], v[34:37]
	s_setprio 1
	s_setprio 0
	v_mfma_f32_16x16x32_bf16 v[142:145], v[158:161], v[174:177], v[142:145]
	v_mfma_f32_16x16x32_bf16 v[138:141], v[166:169], v[174:177], v[138:141]
	v_mfma_f32_16x16x32_bf16 v[134:137], v[158:161], v[186:189], v[134:137]
	v_mfma_f32_16x16x32_bf16 v[130:133], v[166:169], v[186:189], v[130:133]
	v_mfma_f32_16x16x32_bf16 v[126:129], v[158:161], v[194:197], v[126:129]
	v_mfma_f32_16x16x32_bf16 v[122:125], v[166:169], v[194:197], v[122:125]
	v_mfma_f32_16x16x32_bf16 v[102:105], v[158:161], v[202:205], v[102:105]
	v_mfma_f32_16x16x32_bf16 v[98:101], v[166:169], v[202:205], v[98:101]
	v_mfma_f32_16x16x32_bf16 v[142:145], v[162:165], v[178:181], v[142:145]
	v_mfma_f32_16x16x32_bf16 v[138:141], v[170:173], v[178:181], v[138:141]
	v_mfma_f32_16x16x32_bf16 v[134:137], v[162:165], v[190:193], v[134:137]
	v_mfma_f32_16x16x32_bf16 v[130:133], v[170:173], v[190:193], v[130:133]
	v_mfma_f32_16x16x32_bf16 v[126:129], v[162:165], v[198:201], v[126:129]
	v_mfma_f32_16x16x32_bf16 v[122:125], v[170:173], v[198:201], v[122:125]
	v_mfma_f32_16x16x32_bf16 v[102:105], v[162:165], v[214:217], v[102:105]
	v_mfma_f32_16x16x32_bf16 v[98:101], v[170:173], v[214:217], v[98:101]
	s_setprio 1
	s_barrier
	s_add_i32 s52, s53, s40
	v_lshl_add_u64 v[182:183], s[28:29], 0, v[0:1]
	s_mov_b32 m0, s52
	ds_read_b128 v[174:177], v117 offset:16384
	ds_read_b128 v[178:181], v117 offset:17408
	ds_read_b128 v[186:189], v117 offset:18432
	ds_read_b128 v[190:193], v117 offset:19456
	ds_read_b128 v[194:197], v117 offset:20480
	ds_read_b128 v[198:201], v117 offset:21504
	ds_read_b128 v[202:205], v117 offset:22528
	ds_read_b128 v[214:217], v117 offset:23552
	global_load_lds_dwordx4 v[182:183], off
	s_add_i32 m0, s52, 0x2000
	s_add_u32 s52, s28, 0x40000
	v_lshl_add_u64 v[206:207], s[28:29], 0, v[110:111]
	s_addc_u32 s53, s29, 0
	s_add_i32 s51, s51, s40
	global_load_lds_dwordx4 v[206:207], off
	v_lshl_add_u64 v[210:211], s[52:53], 0, v[0:1]
	s_mov_b32 m0, s51
	v_lshl_add_u64 v[224:225], s[30:31], 0, v[108:109]
	global_load_lds_dwordx4 v[210:211], off
	v_lshl_add_u64 v[210:211], s[52:53], 0, v[110:111]
	s_add_i32 m0, s51, 0x2000
	s_nop 0
	global_load_lds_dwordx4 v[210:211], off
	v_lshl_add_u64 v[210:211], s[30:31], 0, v[106:107]
	s_mov_b32 m0, s5
	s_nop 0
	global_load_lds_dwordx4 v[210:211], off
	s_mov_b32 m0, s41
	s_nop 0
	global_load_lds_dwordx4 v[224:225], off
	s_waitcnt vmcnt(8)
	s_waitcnt lgkmcnt(0)
	s_barrier
	s_setprio 0
	s_waitcnt lgkmcnt(0)
	v_mfma_f32_16x16x32_bf16 v[30:33], v[118:121], v[174:177], v[30:33]
	v_mfma_f32_16x16x32_bf16 v[26:29], v[150:153], v[174:177], v[26:29]
	v_mfma_f32_16x16x32_bf16 v[22:25], v[118:121], v[186:189], v[22:25]
	v_mfma_f32_16x16x32_bf16 v[18:21], v[150:153], v[186:189], v[18:21]
	v_mfma_f32_16x16x32_bf16 v[14:17], v[118:121], v[194:197], v[14:17]
	v_mfma_f32_16x16x32_bf16 v[10:13], v[150:153], v[194:197], v[10:13]
	v_mfma_f32_16x16x32_bf16 v[6:9], v[118:121], v[202:205], v[6:9]
	v_mfma_f32_16x16x32_bf16 v[2:5], v[150:153], v[202:205], v[2:5]
	v_mfma_f32_16x16x32_bf16 v[30:33], v[146:149], v[178:181], v[30:33]
	v_mfma_f32_16x16x32_bf16 v[26:29], v[154:157], v[178:181], v[26:29]
	v_mfma_f32_16x16x32_bf16 v[22:25], v[146:149], v[190:193], v[22:25]
	v_mfma_f32_16x16x32_bf16 v[18:21], v[154:157], v[190:193], v[18:21]
	v_mfma_f32_16x16x32_bf16 v[14:17], v[146:149], v[198:201], v[14:17]
	v_mfma_f32_16x16x32_bf16 v[10:13], v[154:157], v[198:201], v[10:13]
	v_mfma_f32_16x16x32_bf16 v[6:9], v[146:149], v[214:217], v[6:9]
	v_mfma_f32_16x16x32_bf16 v[2:5], v[154:157], v[214:217], v[2:5]
	s_setprio 1
	s_setprio 0
	v_mfma_f32_16x16x32_bf16 v[94:97], v[158:161], v[174:177], v[94:97]
	v_mfma_f32_16x16x32_bf16 v[90:93], v[166:169], v[174:177], v[90:93]
	v_mfma_f32_16x16x32_bf16 v[86:89], v[158:161], v[186:189], v[86:89]
	v_mfma_f32_16x16x32_bf16 v[82:85], v[166:169], v[186:189], v[82:85]
	v_mfma_f32_16x16x32_bf16 v[78:81], v[158:161], v[194:197], v[78:81]
	v_mfma_f32_16x16x32_bf16 v[74:77], v[166:169], v[194:197], v[74:77]
	v_mfma_f32_16x16x32_bf16 v[70:73], v[158:161], v[202:205], v[70:73]
	v_mfma_f32_16x16x32_bf16 v[66:69], v[166:169], v[202:205], v[66:69]
	v_mfma_f32_16x16x32_bf16 v[94:97], v[162:165], v[178:181], v[94:97]
	v_mfma_f32_16x16x32_bf16 v[90:93], v[170:173], v[178:181], v[90:93]
	v_mfma_f32_16x16x32_bf16 v[86:89], v[162:165], v[190:193], v[86:89]
	v_mfma_f32_16x16x32_bf16 v[82:85], v[170:173], v[190:193], v[82:85]
	v_mfma_f32_16x16x32_bf16 v[78:81], v[162:165], v[198:201], v[78:81]
	v_mfma_f32_16x16x32_bf16 v[74:77], v[170:173], v[198:201], v[74:77]
	v_mfma_f32_16x16x32_bf16 v[70:73], v[162:165], v[214:217], v[70:73]
	v_mfma_f32_16x16x32_bf16 v[66:69], v[170:173], v[214:217], v[66:69]
	s_setprio 1
	s_barrier
	s_add_i32 s51, 0, 0x18000
	s_add_i32 s52, 0, 0x1c000
	v_add_u32_e32 v154, s51, v116
	v_add_u32_e32 v170, s52, v116
	ds_read_b128 v[118:121], v154
	ds_read_b128 v[146:149], v154 offset:1024
	ds_read_b128 v[150:153], v154 offset:2048
	ds_read_b128 v[154:157], v154 offset:3072
	ds_read_b128 v[158:161], v170
	ds_read_b128 v[162:165], v170 offset:1024
	ds_read_b128 v[166:169], v170 offset:2048
	ds_read_b128 v[170:173], v170 offset:3072
	s_add_u32 s30, s30, 0x40000
	s_addc_u32 s31, s31, 0
	s_mov_b32 m0, s42
	v_lshl_add_u64 v[226:227], s[30:31], 0, v[106:107]
	ds_read_b128 v[174:177], v117 offset:32768
	ds_read_b128 v[178:181], v117 offset:33792
	ds_read_b128 v[186:189], v117 offset:34816
	ds_read_b128 v[190:193], v117 offset:35840
	ds_read_b128 v[194:197], v117 offset:36864
	ds_read_b128 v[198:201], v117 offset:37888
	ds_read_b128 v[202:205], v117 offset:38912
	ds_read_b128 v[214:217], v117 offset:39936
	global_load_lds_dwordx4 v[226:227], off
	v_lshl_add_u64 v[226:227], s[30:31], 0, v[108:109]
	s_mov_b32 m0, s43
	s_nop 0
	global_load_lds_dwordx4 v[226:227], off
	s_waitcnt vmcnt(8)
	s_waitcnt lgkmcnt(0)
	s_barrier
	s_setprio 0
	s_waitcnt lgkmcnt(0)
	v_mfma_f32_16x16x32_bf16 v[62:65], v[118:121], v[174:177], v[62:65]
	v_mfma_f32_16x16x32_bf16 v[58:61], v[150:153], v[174:177], v[58:61]
	v_mfma_f32_16x16x32_bf16 v[54:57], v[118:121], v[186:189], v[54:57]
	v_mfma_f32_16x16x32_bf16 v[50:53], v[150:153], v[186:189], v[50:53]
	v_mfma_f32_16x16x32_bf16 v[46:49], v[118:121], v[194:197], v[46:49]
	v_mfma_f32_16x16x32_bf16 v[42:45], v[150:153], v[194:197], v[42:45]
	v_mfma_f32_16x16x32_bf16 v[38:41], v[118:121], v[202:205], v[38:41]
	v_mfma_f32_16x16x32_bf16 v[34:37], v[150:153], v[202:205], v[34:37]
	v_mfma_f32_16x16x32_bf16 v[62:65], v[146:149], v[178:181], v[62:65]
	v_mfma_f32_16x16x32_bf16 v[58:61], v[154:157], v[178:181], v[58:61]
	v_mfma_f32_16x16x32_bf16 v[54:57], v[146:149], v[190:193], v[54:57]
	v_mfma_f32_16x16x32_bf16 v[50:53], v[154:157], v[190:193], v[50:53]
	v_mfma_f32_16x16x32_bf16 v[46:49], v[146:149], v[198:201], v[46:49]
	v_mfma_f32_16x16x32_bf16 v[42:45], v[154:157], v[198:201], v[42:45]
	v_mfma_f32_16x16x32_bf16 v[38:41], v[146:149], v[214:217], v[38:41]
	v_mfma_f32_16x16x32_bf16 v[34:37], v[154:157], v[214:217], v[34:37]
	s_setprio 1
	s_setprio 0
	v_mfma_f32_16x16x32_bf16 v[142:145], v[158:161], v[174:177], v[142:145]
	v_mfma_f32_16x16x32_bf16 v[138:141], v[166:169], v[174:177], v[138:141]
	v_mfma_f32_16x16x32_bf16 v[134:137], v[158:161], v[186:189], v[134:137]
	v_mfma_f32_16x16x32_bf16 v[130:133], v[166:169], v[186:189], v[130:133]
	v_mfma_f32_16x16x32_bf16 v[126:129], v[158:161], v[194:197], v[126:129]
	v_mfma_f32_16x16x32_bf16 v[122:125], v[166:169], v[194:197], v[122:125]
	v_mfma_f32_16x16x32_bf16 v[102:105], v[158:161], v[202:205], v[102:105]
	v_mfma_f32_16x16x32_bf16 v[98:101], v[166:169], v[202:205], v[98:101]
	v_mfma_f32_16x16x32_bf16 v[142:145], v[162:165], v[178:181], v[142:145]
	v_mfma_f32_16x16x32_bf16 v[138:141], v[170:173], v[178:181], v[138:141]
	v_mfma_f32_16x16x32_bf16 v[134:137], v[162:165], v[190:193], v[134:137]
	v_mfma_f32_16x16x32_bf16 v[130:133], v[170:173], v[190:193], v[130:133]
	v_mfma_f32_16x16x32_bf16 v[126:129], v[162:165], v[198:201], v[126:129]
	v_mfma_f32_16x16x32_bf16 v[122:125], v[170:173], v[198:201], v[122:125]
	v_mfma_f32_16x16x32_bf16 v[102:105], v[162:165], v[214:217], v[102:105]
	v_mfma_f32_16x16x32_bf16 v[98:101], v[170:173], v[214:217], v[98:101]
	s_setprio 1
	s_barrier
	s_add_i32 s30, s51, s40
	v_lshl_add_u64 v[182:183], v[182:183], 0, s[94:95]
	s_mov_b32 m0, s30
	ds_read_b128 v[174:177], v117 offset:49152
	ds_read_b128 v[178:181], v117 offset:50176
	ds_read_b128 v[186:189], v117 offset:51200
	ds_read_b128 v[190:193], v117 offset:52224
	ds_read_b128 v[194:197], v117 offset:53248
	ds_read_b128 v[198:201], v117 offset:54272
	ds_read_b128 v[202:205], v117 offset:55296
	ds_read_b128 v[214:217], v117 offset:56320
	global_load_lds_dwordx4 v[182:183], off
	s_add_i32 m0, s30, 0x2000
	s_add_u32 s28, s28, 0x40080
	v_lshl_add_u64 v[182:183], v[206:207], 0, s[94:95]
	s_addc_u32 s29, s29, 0
	s_add_i32 s30, s52, s40
	global_load_lds_dwordx4 v[182:183], off
	v_lshl_add_u64 v[182:183], s[28:29], 0, v[0:1]
	s_mov_b32 m0, s30
	s_nop 0
	global_load_lds_dwordx4 v[182:183], off
	v_lshl_add_u64 v[182:183], s[28:29], 0, v[110:111]
	s_add_i32 m0, s30, 0x2000
	s_nop 0
	global_load_lds_dwordx4 v[182:183], off
	v_lshl_add_u64 v[182:183], v[210:211], 0, s[94:95]
	s_mov_b32 m0, s44
	s_nop 0
	global_load_lds_dwordx4 v[182:183], off
	v_lshl_add_u64 v[182:183], v[224:225], 0, s[94:95]
	s_mov_b32 m0, s45
	s_nop 0
	global_load_lds_dwordx4 v[182:183], off
	s_waitcnt vmcnt(8)
	s_waitcnt lgkmcnt(0)
	s_barrier
	s_setprio 0
	s_waitcnt lgkmcnt(0)
	v_mfma_f32_16x16x32_bf16 v[30:33], v[118:121], v[174:177], v[30:33]
	v_mfma_f32_16x16x32_bf16 v[26:29], v[150:153], v[174:177], v[26:29]
	v_mfma_f32_16x16x32_bf16 v[22:25], v[118:121], v[186:189], v[22:25]
	v_mfma_f32_16x16x32_bf16 v[18:21], v[150:153], v[186:189], v[18:21]
	v_mfma_f32_16x16x32_bf16 v[14:17], v[118:121], v[194:197], v[14:17]
	v_mfma_f32_16x16x32_bf16 v[10:13], v[150:153], v[194:197], v[10:13]
	v_mfma_f32_16x16x32_bf16 v[6:9], v[118:121], v[202:205], v[6:9]
	v_mfma_f32_16x16x32_bf16 v[2:5], v[150:153], v[202:205], v[2:5]
	v_mfma_f32_16x16x32_bf16 v[30:33], v[146:149], v[178:181], v[30:33]
	v_mfma_f32_16x16x32_bf16 v[26:29], v[154:157], v[178:181], v[26:29]
	v_mfma_f32_16x16x32_bf16 v[22:25], v[146:149], v[190:193], v[22:25]
	v_mfma_f32_16x16x32_bf16 v[18:21], v[154:157], v[190:193], v[18:21]
	v_mfma_f32_16x16x32_bf16 v[14:17], v[146:149], v[198:201], v[14:17]
	v_mfma_f32_16x16x32_bf16 v[10:13], v[154:157], v[198:201], v[10:13]
	v_mfma_f32_16x16x32_bf16 v[6:9], v[146:149], v[214:217], v[6:9]
	v_mfma_f32_16x16x32_bf16 v[2:5], v[154:157], v[214:217], v[2:5]
	s_setprio 1
	s_setprio 0
	v_mfma_f32_16x16x32_bf16 v[94:97], v[158:161], v[174:177], v[94:97]
	v_mfma_f32_16x16x32_bf16 v[90:93], v[166:169], v[174:177], v[90:93]
	v_mfma_f32_16x16x32_bf16 v[86:89], v[158:161], v[186:189], v[86:89]
	v_mfma_f32_16x16x32_bf16 v[82:85], v[166:169], v[186:189], v[82:85]
	v_mfma_f32_16x16x32_bf16 v[78:81], v[158:161], v[194:197], v[78:81]
	v_mfma_f32_16x16x32_bf16 v[74:77], v[166:169], v[194:197], v[74:77]
	v_mfma_f32_16x16x32_bf16 v[70:73], v[158:161], v[202:205], v[70:73]
	v_mfma_f32_16x16x32_bf16 v[66:69], v[166:169], v[202:205], v[66:69]
	v_mfma_f32_16x16x32_bf16 v[94:97], v[162:165], v[178:181], v[94:97]
	v_mfma_f32_16x16x32_bf16 v[90:93], v[170:173], v[178:181], v[90:93]
	v_mfma_f32_16x16x32_bf16 v[86:89], v[162:165], v[190:193], v[86:89]
	v_mfma_f32_16x16x32_bf16 v[82:85], v[170:173], v[190:193], v[82:85]
	v_mfma_f32_16x16x32_bf16 v[78:81], v[162:165], v[198:201], v[78:81]
	v_mfma_f32_16x16x32_bf16 v[74:77], v[170:173], v[198:201], v[74:77]
	v_mfma_f32_16x16x32_bf16 v[70:73], v[162:165], v[214:217], v[70:73]
	v_mfma_f32_16x16x32_bf16 v[66:69], v[170:173], v[214:217], v[66:69]
	s_setprio 1
	s_barrier
	s_add_i32 s50, s50, 2
	s_add_u32 s26, s26, 0x100
	s_addc_u32 s27, s27, 0
	s_cmp_gt_u32 s50, 13
	s_cbranch_scc0 .LBB0_1115
	s_cmpk_lt_u32 s39, 0x100
	s_cbranch_scc0 .LBB0_1118
	s_barrier

.LBB0_1180:
	s_add_u32 s8, s46, s6
	s_addc_u32 s9, s47, s7
	s_add_u32 s8, s8, 0x2a400100
	s_addc_u32 s9, s9, 0
	s_add_u32 s51, s48, s6
	s_addc_u32 s52, s49, s7
	s_add_i32 s53, 0, 0x10000
	s_cmpk_eq_i32 s6, 0x1500
	s_cselect_b32 s27, s5, s9
	s_cselect_b32 s26, s4, s8
	s_cselect_b32 s9, s3, s52
	s_cselect_b32 s8, s2, s51
	s_add_i32 s51, 0, 0x14000
	v_add_u32_e32 v150, s53, v136
	v_add_u32_e32 v166, s51, v136
	ds_read_b128 v[138:141], v150
	ds_read_b128 v[142:145], v150 offset:1024
	ds_read_b128 v[146:149], v150 offset:2048
	ds_read_b128 v[150:153], v150 offset:3072
	ds_read_b128 v[154:157], v166
	ds_read_b128 v[158:161], v166 offset:1024
	ds_read_b128 v[162:165], v166 offset:2048
	ds_read_b128 v[166:169], v166 offset:3072
	v_lshl_add_u64 v[182:183], v[132:133], 0, s[6:7]
	s_add_i32 m0, s39, 0xc000
	ds_read_b128 v[170:173], v137
	ds_read_b128 v[174:177], v137 offset:1024
	ds_read_b128 v[178:181], v137 offset:2048
	ds_read_b128 v[186:189], v137 offset:3072
	ds_read_b128 v[190:193], v137 offset:4096
	ds_read_b128 v[194:197], v137 offset:5120
	ds_read_b128 v[198:201], v137 offset:6144
	ds_read_b128 v[202:205], v137 offset:7168
	global_load_lds_dwordx4 v[182:183], off
	v_lshl_add_u64 v[182:183], v[134:135], 0, s[6:7]
	s_add_i32 m0, s39, 0xe000
	s_nop 0
	global_load_lds_dwordx4 v[182:183], off
	s_waitcnt vmcnt(8)
	s_waitcnt lgkmcnt(0)
	s_barrier
	s_setprio 0
	s_waitcnt lgkmcnt(0)
	v_mfma_f32_16x16x32_bf16 v[126:129], v[138:141], v[170:173], v[126:129]
	v_mfma_f32_16x16x32_bf16 v[122:125], v[146:149], v[170:173], v[122:125]
	v_mfma_f32_16x16x32_bf16 v[110:113], v[138:141], v[178:181], v[110:113]
	v_mfma_f32_16x16x32_bf16 v[106:109], v[146:149], v[178:181], v[106:109]
	v_mfma_f32_16x16x32_bf16 v[94:97], v[138:141], v[190:193], v[94:97]
	v_mfma_f32_16x16x32_bf16 v[90:93], v[146:149], v[190:193], v[90:93]
	v_mfma_f32_16x16x32_bf16 v[78:81], v[138:141], v[198:201], v[78:81]
	v_mfma_f32_16x16x32_bf16 v[74:77], v[146:149], v[198:201], v[74:77]
	v_mfma_f32_16x16x32_bf16 v[126:129], v[142:145], v[174:177], v[126:129]
	v_mfma_f32_16x16x32_bf16 v[122:125], v[150:153], v[174:177], v[122:125]
	v_mfma_f32_16x16x32_bf16 v[110:113], v[142:145], v[186:189], v[110:113]
	v_mfma_f32_16x16x32_bf16 v[106:109], v[150:153], v[186:189], v[106:109]
	v_mfma_f32_16x16x32_bf16 v[94:97], v[142:145], v[194:197], v[94:97]
	v_mfma_f32_16x16x32_bf16 v[90:93], v[150:153], v[194:197], v[90:93]
	v_mfma_f32_16x16x32_bf16 v[78:81], v[142:145], v[202:205], v[78:81]
	v_mfma_f32_16x16x32_bf16 v[74:77], v[150:153], v[202:205], v[74:77]
	s_setprio 1
	s_setprio 0
	v_mfma_f32_16x16x32_bf16 v[118:121], v[154:157], v[170:173], v[118:121]
	v_mfma_f32_16x16x32_bf16 v[114:117], v[162:165], v[170:173], v[114:117]
	v_mfma_f32_16x16x32_bf16 v[102:105], v[154:157], v[178:181], v[102:105]
	v_mfma_f32_16x16x32_bf16 v[98:101], v[162:165], v[178:181], v[98:101]
	v_mfma_f32_16x16x32_bf16 v[86:89], v[154:157], v[190:193], v[86:89]
	v_mfma_f32_16x16x32_bf16 v[82:85], v[162:165], v[190:193], v[82:85]
	v_mfma_f32_16x16x32_bf16 v[70:73], v[154:157], v[198:201], v[70:73]
	v_mfma_f32_16x16x32_bf16 v[66:69], v[162:165], v[198:201], v[66:69]
	v_mfma_f32_16x16x32_bf16 v[118:121], v[158:161], v[174:177], v[118:121]
	v_mfma_f32_16x16x32_bf16 v[114:117], v[166:169], v[174:177], v[114:117]
	v_mfma_f32_16x16x32_bf16 v[102:105], v[158:161], v[186:189], v[102:105]
	v_mfma_f32_16x16x32_bf16 v[98:101], v[166:169], v[186:189], v[98:101]
	v_mfma_f32_16x16x32_bf16 v[86:89], v[158:161], v[194:197], v[86:89]
	v_mfma_f32_16x16x32_bf16 v[82:85], v[166:169], v[194:197], v[82:85]
	v_mfma_f32_16x16x32_bf16 v[70:73], v[158:161], v[202:205], v[70:73]
	v_mfma_f32_16x16x32_bf16 v[66:69], v[166:169], v[202:205], v[66:69]
	s_setprio 1
	s_barrier
	s_add_i32 s52, s53, s38
	v_lshl_add_u64 v[182:183], s[8:9], 0, v[0:1]
	s_mov_b32 m0, s52
	ds_read_b128 v[170:173], v137 offset:16384
	ds_read_b128 v[174:177], v137 offset:17408
	ds_read_b128 v[178:181], v137 offset:18432
	ds_read_b128 v[186:189], v137 offset:19456
	ds_read_b128 v[190:193], v137 offset:20480
	ds_read_b128 v[194:197], v137 offset:21504
	ds_read_b128 v[198:201], v137 offset:22528
	ds_read_b128 v[202:205], v137 offset:23552
	global_load_lds_dwordx4 v[182:183], off
	s_add_i32 m0, s52, 0x2000
	s_add_u32 s52, s8, 0xb0000
	v_lshl_add_u64 v[206:207], s[8:9], 0, v[130:131]
	s_addc_u32 s53, s9, 0
	s_add_i32 s51, s51, s38
	global_load_lds_dwordx4 v[206:207], off
	v_lshl_add_u64 v[210:211], s[52:53], 0, v[0:1]
	s_mov_b32 m0, s51
	v_lshl_add_u64 v[214:215], s[26:27], 0, v[130:131]
	global_load_lds_dwordx4 v[210:211], off
	v_lshl_add_u64 v[210:211], s[52:53], 0, v[130:131]
	s_add_i32 m0, s51, 0x2000
	s_nop 0
	global_load_lds_dwordx4 v[210:211], off
	v_lshl_add_u64 v[210:211], s[26:27], 0, v[0:1]
	s_mov_b32 m0, s39
	s_nop 0
	global_load_lds_dwordx4 v[210:211], off
	s_mov_b32 m0, s40
	s_nop 0
	global_load_lds_dwordx4 v[214:215], off
	s_waitcnt vmcnt(8)
	s_waitcnt lgkmcnt(0)
	s_barrier
	s_setprio 0
	s_waitcnt lgkmcnt(0)
	v_mfma_f32_16x16x32_bf16 v[62:65], v[138:141], v[170:173], v[62:65]
	v_mfma_f32_16x16x32_bf16 v[58:61], v[146:149], v[170:173], v[58:61]
	v_mfma_f32_16x16x32_bf16 v[46:49], v[138:141], v[178:181], v[46:49]
	v_mfma_f32_16x16x32_bf16 v[42:45], v[146:149], v[178:181], v[42:45]
	v_mfma_f32_16x16x32_bf16 v[30:33], v[138:141], v[190:193], v[30:33]
	v_mfma_f32_16x16x32_bf16 v[26:29], v[146:149], v[190:193], v[26:29]
	v_mfma_f32_16x16x32_bf16 v[14:17], v[138:141], v[198:201], v[14:17]
	v_mfma_f32_16x16x32_bf16 v[10:13], v[146:149], v[198:201], v[10:13]
	v_mfma_f32_16x16x32_bf16 v[62:65], v[142:145], v[174:177], v[62:65]
	v_mfma_f32_16x16x32_bf16 v[58:61], v[150:153], v[174:177], v[58:61]
	v_mfma_f32_16x16x32_bf16 v[46:49], v[142:145], v[186:189], v[46:49]
	v_mfma_f32_16x16x32_bf16 v[42:45], v[150:153], v[186:189], v[42:45]
	v_mfma_f32_16x16x32_bf16 v[30:33], v[142:145], v[194:197], v[30:33]
	v_mfma_f32_16x16x32_bf16 v[26:29], v[150:153], v[194:197], v[26:29]
	v_mfma_f32_16x16x32_bf16 v[14:17], v[142:145], v[202:205], v[14:17]
	v_mfma_f32_16x16x32_bf16 v[10:13], v[150:153], v[202:205], v[10:13]
	s_setprio 1
	s_setprio 0
	v_mfma_f32_16x16x32_bf16 v[54:57], v[154:157], v[170:173], v[54:57]
	v_mfma_f32_16x16x32_bf16 v[50:53], v[162:165], v[170:173], v[50:53]
	v_mfma_f32_16x16x32_bf16 v[38:41], v[154:157], v[178:181], v[38:41]
	v_mfma_f32_16x16x32_bf16 v[34:37], v[162:165], v[178:181], v[34:37]
	v_mfma_f32_16x16x32_bf16 v[22:25], v[154:157], v[190:193], v[22:25]
	v_mfma_f32_16x16x32_bf16 v[18:21], v[162:165], v[190:193], v[18:21]
	v_mfma_f32_16x16x32_bf16 v[6:9], v[154:157], v[198:201], v[6:9]
	v_mfma_f32_16x16x32_bf16 v[2:5], v[162:165], v[198:201], v[2:5]
	v_mfma_f32_16x16x32_bf16 v[54:57], v[158:161], v[174:177], v[54:57]
	v_mfma_f32_16x16x32_bf16 v[50:53], v[166:169], v[174:177], v[50:53]
	v_mfma_f32_16x16x32_bf16 v[38:41], v[158:161], v[186:189], v[38:41]
	v_mfma_f32_16x16x32_bf16 v[34:37], v[166:169], v[186:189], v[34:37]
	v_mfma_f32_16x16x32_bf16 v[22:25], v[158:161], v[194:197], v[22:25]
	v_mfma_f32_16x16x32_bf16 v[18:21], v[166:169], v[194:197], v[18:21]
	v_mfma_f32_16x16x32_bf16 v[6:9], v[158:161], v[202:205], v[6:9]
	v_mfma_f32_16x16x32_bf16 v[2:5], v[166:169], v[202:205], v[2:5]
	s_setprio 1
	s_barrier
	s_add_i32 s51, 0, 0x18000
	s_add_i32 s52, 0, 0x1c000
	v_add_u32_e32 v150, s51, v136
	v_add_u32_e32 v166, s52, v136
	ds_read_b128 v[138:141], v150
	ds_read_b128 v[142:145], v150 offset:1024
	ds_read_b128 v[146:149], v150 offset:2048
	ds_read_b128 v[150:153], v150 offset:3072
	ds_read_b128 v[154:157], v166
	ds_read_b128 v[158:161], v166 offset:1024
	ds_read_b128 v[162:165], v166 offset:2048
	ds_read_b128 v[166:169], v166 offset:3072
	s_add_u32 s26, s26, 0xb0000
	s_addc_u32 s27, s27, 0
	s_mov_b32 m0, s41
	v_lshl_add_u64 v[216:217], s[26:27], 0, v[0:1]
	ds_read_b128 v[170:173], v137 offset:32768
	ds_read_b128 v[174:177], v137 offset:33792
	ds_read_b128 v[178:181], v137 offset:34816
	ds_read_b128 v[186:189], v137 offset:35840
	ds_read_b128 v[190:193], v137 offset:36864
	ds_read_b128 v[194:197], v137 offset:37888
	ds_read_b128 v[198:201], v137 offset:38912
	ds_read_b128 v[202:205], v137 offset:39936
	global_load_lds_dwordx4 v[216:217], off
	v_lshl_add_u64 v[216:217], s[26:27], 0, v[130:131]
	s_mov_b32 m0, s43
	s_nop 0
	global_load_lds_dwordx4 v[216:217], off
	s_waitcnt vmcnt(8)
	s_waitcnt lgkmcnt(0)
	s_barrier
	s_setprio 0
	s_waitcnt lgkmcnt(0)
	v_mfma_f32_16x16x32_bf16 v[126:129], v[138:141], v[170:173], v[126:129]
	v_mfma_f32_16x16x32_bf16 v[122:125], v[146:149], v[170:173], v[122:125]
	v_mfma_f32_16x16x32_bf16 v[110:113], v[138:141], v[178:181], v[110:113]
	v_mfma_f32_16x16x32_bf16 v[106:109], v[146:149], v[178:181], v[106:109]
	v_mfma_f32_16x16x32_bf16 v[94:97], v[138:141], v[190:193], v[94:97]
	v_mfma_f32_16x16x32_bf16 v[90:93], v[146:149], v[190:193], v[90:93]
	v_mfma_f32_16x16x32_bf16 v[78:81], v[138:141], v[198:201], v[78:81]
	v_mfma_f32_16x16x32_bf16 v[74:77], v[146:149], v[198:201], v[74:77]
	v_mfma_f32_16x16x32_bf16 v[126:129], v[142:145], v[174:177], v[126:129]
	v_mfma_f32_16x16x32_bf16 v[122:125], v[150:153], v[174:177], v[122:125]
	v_mfma_f32_16x16x32_bf16 v[110:113], v[142:145], v[186:189], v[110:113]
	v_mfma_f32_16x16x32_bf16 v[106:109], v[150:153], v[186:189], v[106:109]
	v_mfma_f32_16x16x32_bf16 v[94:97], v[142:145], v[194:197], v[94:97]
	v_mfma_f32_16x16x32_bf16 v[90:93], v[150:153], v[194:197], v[90:93]
	v_mfma_f32_16x16x32_bf16 v[78:81], v[142:145], v[202:205], v[78:81]
	v_mfma_f32_16x16x32_bf16 v[74:77], v[150:153], v[202:205], v[74:77]
	s_setprio 1
	s_setprio 0
	v_mfma_f32_16x16x32_bf16 v[118:121], v[154:157], v[170:173], v[118:121]
	v_mfma_f32_16x16x32_bf16 v[114:117], v[162:165], v[170:173], v[114:117]
	v_mfma_f32_16x16x32_bf16 v[102:105], v[154:157], v[178:181], v[102:105]
	v_mfma_f32_16x16x32_bf16 v[98:101], v[162:165], v[178:181], v[98:101]
	v_mfma_f32_16x16x32_bf16 v[86:89], v[154:157], v[190:193], v[86:89]
	v_mfma_f32_16x16x32_bf16 v[82:85], v[162:165], v[190:193], v[82:85]
	v_mfma_f32_16x16x32_bf16 v[70:73], v[154:157], v[198:201], v[70:73]
	v_mfma_f32_16x16x32_bf16 v[66:69], v[162:165], v[198:201], v[66:69]
	v_mfma_f32_16x16x32_bf16 v[118:121], v[158:161], v[174:177], v[118:121]
	v_mfma_f32_16x16x32_bf16 v[114:117], v[166:169], v[174:177], v[114:117]
	v_mfma_f32_16x16x32_bf16 v[102:105], v[158:161], v[186:189], v[102:105]
	v_mfma_f32_16x16x32_bf16 v[98:101], v[166:169], v[186:189], v[98:101]
	v_mfma_f32_16x16x32_bf16 v[86:89], v[158:161], v[194:197], v[86:89]
	v_mfma_f32_16x16x32_bf16 v[82:85], v[166:169], v[194:197], v[82:85]
	v_mfma_f32_16x16x32_bf16 v[70:73], v[158:161], v[202:205], v[70:73]
	v_mfma_f32_16x16x32_bf16 v[66:69], v[166:169], v[202:205], v[66:69]
	s_setprio 1
	s_barrier
	s_add_i32 s26, s51, s38
	v_lshl_add_u64 v[182:183], v[182:183], 0, s[94:95]
	s_mov_b32 m0, s26
	ds_read_b128 v[170:173], v137 offset:49152
	ds_read_b128 v[174:177], v137 offset:50176
	ds_read_b128 v[178:181], v137 offset:51200
	ds_read_b128 v[186:189], v137 offset:52224
	ds_read_b128 v[190:193], v137 offset:53248
	ds_read_b128 v[194:197], v137 offset:54272
	ds_read_b128 v[198:201], v137 offset:55296
	ds_read_b128 v[202:205], v137 offset:56320
	global_load_lds_dwordx4 v[182:183], off
	s_add_i32 m0, s26, 0x2000
	s_add_u32 s8, s8, 0xb0080
	v_lshl_add_u64 v[182:183], v[206:207], 0, s[94:95]
	s_addc_u32 s9, s9, 0
	s_add_i32 s26, s52, s38
	global_load_lds_dwordx4 v[182:183], off
	v_lshl_add_u64 v[182:183], s[8:9], 0, v[0:1]
	s_mov_b32 m0, s26
	s_nop 0
	global_load_lds_dwordx4 v[182:183], off
	v_lshl_add_u64 v[182:183], s[8:9], 0, v[130:131]
	s_add_i32 m0, s26, 0x2000
	s_nop 0
	global_load_lds_dwordx4 v[182:183], off
	v_lshl_add_u64 v[182:183], v[210:211], 0, s[94:95]
	s_mov_b32 m0, s44
	s_nop 0
	global_load_lds_dwordx4 v[182:183], off
	v_lshl_add_u64 v[182:183], v[214:215], 0, s[94:95]
	s_mov_b32 m0, s45
	s_nop 0
	global_load_lds_dwordx4 v[182:183], off
	s_waitcnt vmcnt(8)
	s_waitcnt lgkmcnt(0)
	s_barrier
	s_setprio 0
	s_waitcnt lgkmcnt(0)
	v_mfma_f32_16x16x32_bf16 v[62:65], v[138:141], v[170:173], v[62:65]
	v_mfma_f32_16x16x32_bf16 v[58:61], v[146:149], v[170:173], v[58:61]
	v_mfma_f32_16x16x32_bf16 v[46:49], v[138:141], v[178:181], v[46:49]
	v_mfma_f32_16x16x32_bf16 v[42:45], v[146:149], v[178:181], v[42:45]
	v_mfma_f32_16x16x32_bf16 v[30:33], v[138:141], v[190:193], v[30:33]
	v_mfma_f32_16x16x32_bf16 v[26:29], v[146:149], v[190:193], v[26:29]
	v_mfma_f32_16x16x32_bf16 v[14:17], v[138:141], v[198:201], v[14:17]
	v_mfma_f32_16x16x32_bf16 v[10:13], v[146:149], v[198:201], v[10:13]
	v_mfma_f32_16x16x32_bf16 v[62:65], v[142:145], v[174:177], v[62:65]
	v_mfma_f32_16x16x32_bf16 v[58:61], v[150:153], v[174:177], v[58:61]
	v_mfma_f32_16x16x32_bf16 v[46:49], v[142:145], v[186:189], v[46:49]
	v_mfma_f32_16x16x32_bf16 v[42:45], v[150:153], v[186:189], v[42:45]
	v_mfma_f32_16x16x32_bf16 v[30:33], v[142:145], v[194:197], v[30:33]
	v_mfma_f32_16x16x32_bf16 v[26:29], v[150:153], v[194:197], v[26:29]
	v_mfma_f32_16x16x32_bf16 v[14:17], v[142:145], v[202:205], v[14:17]
	v_mfma_f32_16x16x32_bf16 v[10:13], v[150:153], v[202:205], v[10:13]
	s_setprio 1
	s_setprio 0
	v_mfma_f32_16x16x32_bf16 v[54:57], v[154:157], v[170:173], v[54:57]
	v_mfma_f32_16x16x32_bf16 v[50:53], v[162:165], v[170:173], v[50:53]
	v_mfma_f32_16x16x32_bf16 v[38:41], v[154:157], v[178:181], v[38:41]
	v_mfma_f32_16x16x32_bf16 v[34:37], v[162:165], v[178:181], v[34:37]
	v_mfma_f32_16x16x32_bf16 v[22:25], v[154:157], v[190:193], v[22:25]
	v_mfma_f32_16x16x32_bf16 v[18:21], v[162:165], v[190:193], v[18:21]
	v_mfma_f32_16x16x32_bf16 v[6:9], v[154:157], v[198:201], v[6:9]
	v_mfma_f32_16x16x32_bf16 v[2:5], v[162:165], v[198:201], v[2:5]
	v_mfma_f32_16x16x32_bf16 v[54:57], v[158:161], v[174:177], v[54:57]
	v_mfma_f32_16x16x32_bf16 v[50:53], v[166:169], v[174:177], v[50:53]
	v_mfma_f32_16x16x32_bf16 v[38:41], v[158:161], v[186:189], v[38:41]
	v_mfma_f32_16x16x32_bf16 v[34:37], v[166:169], v[186:189], v[34:37]
	v_mfma_f32_16x16x32_bf16 v[22:25], v[158:161], v[194:197], v[22:25]
	v_mfma_f32_16x16x32_bf16 v[18:21], v[166:169], v[194:197], v[18:21]
	v_mfma_f32_16x16x32_bf16 v[6:9], v[158:161], v[202:205], v[6:9]
	v_mfma_f32_16x16x32_bf16 v[2:5], v[166:169], v[202:205], v[2:5]
	s_setprio 1
	s_barrier
	s_add_i32 s50, s50, 2
	s_add_u32 s6, s6, 0x100
	s_addc_u32 s7, s7, 0
	s_cmp_gt_u32 s50, 41
	s_cbranch_scc0 .LBB0_1180
	s_cmpk_lt_u32 s31, 0x100
	s_cbranch_scc0 .LBB0_1183
	s_barrier

.LBB0_1192:
	s_add_u32 s26, s44, s24
	s_addc_u32 s27, s45, s25
	s_add_u32 s26, s26, 0xc000100
	s_addc_u32 s27, s27, 0
	s_add_u32 s49, s46, s24
	s_addc_u32 s50, s47, s25
	s_add_i32 s51, 0, 0x10000
	s_cmpk_eq_i32 s24, 0x700
	s_cselect_b32 s29, s9, s27
	s_cselect_b32 s28, s8, s26
	s_cselect_b32 s27, s7, s50
	s_cselect_b32 s26, s6, s49
	s_add_i32 s49, 0, 0x14000
	v_add_u32_e32 v154, s51, v140
	v_add_u32_e32 v170, s49, v140
	ds_read_b128 v[142:145], v154
	ds_read_b128 v[146:149], v154 offset:1024
	ds_read_b128 v[150:153], v154 offset:2048
	ds_read_b128 v[154:157], v154 offset:3072
	ds_read_b128 v[158:161], v170
	ds_read_b128 v[162:165], v170 offset:1024
	ds_read_b128 v[166:169], v170 offset:2048
	ds_read_b128 v[170:173], v170 offset:3072
	v_lshl_add_u64 v[182:183], v[136:137], 0, s[24:25]
	s_add_i32 m0, s5, 0xc000
	ds_read_b128 v[174:177], v141
	ds_read_b128 v[178:181], v141 offset:1024
	ds_read_b128 v[186:189], v141 offset:2048
	ds_read_b128 v[190:193], v141 offset:3072
	ds_read_b128 v[194:197], v141 offset:4096
	ds_read_b128 v[198:201], v141 offset:5120
	ds_read_b128 v[202:205], v141 offset:6144
	ds_read_b128 v[214:217], v141 offset:7168
	global_load_lds_dwordx4 v[182:183], off
	v_lshl_add_u64 v[182:183], v[138:139], 0, s[24:25]
	s_add_i32 m0, s5, 0xe000
	s_nop 0
	global_load_lds_dwordx4 v[182:183], off
	s_waitcnt vmcnt(8)
	s_waitcnt lgkmcnt(0)
	s_barrier
	s_setprio 0
	s_waitcnt lgkmcnt(0)
	v_mfma_f32_16x16x32_bf16 v[126:129], v[142:145], v[174:177], v[126:129]
	v_mfma_f32_16x16x32_bf16 v[118:121], v[150:153], v[174:177], v[118:121]
	v_mfma_f32_16x16x32_bf16 v[110:113], v[142:145], v[186:189], v[110:113]
	v_mfma_f32_16x16x32_bf16 v[102:105], v[150:153], v[186:189], v[102:105]
	v_mfma_f32_16x16x32_bf16 v[94:97], v[142:145], v[194:197], v[94:97]
	v_mfma_f32_16x16x32_bf16 v[86:89], v[150:153], v[194:197], v[86:89]
	v_mfma_f32_16x16x32_bf16 v[78:81], v[142:145], v[202:205], v[78:81]
	v_mfma_f32_16x16x32_bf16 v[70:73], v[150:153], v[202:205], v[70:73]
	v_mfma_f32_16x16x32_bf16 v[126:129], v[146:149], v[178:181], v[126:129]
	v_mfma_f32_16x16x32_bf16 v[118:121], v[154:157], v[178:181], v[118:121]
	v_mfma_f32_16x16x32_bf16 v[110:113], v[146:149], v[190:193], v[110:113]
	v_mfma_f32_16x16x32_bf16 v[102:105], v[154:157], v[190:193], v[102:105]
	v_mfma_f32_16x16x32_bf16 v[94:97], v[146:149], v[198:201], v[94:97]
	v_mfma_f32_16x16x32_bf16 v[86:89], v[154:157], v[198:201], v[86:89]
	v_mfma_f32_16x16x32_bf16 v[78:81], v[146:149], v[214:217], v[78:81]
	v_mfma_f32_16x16x32_bf16 v[70:73], v[154:157], v[214:217], v[70:73]
	s_setprio 1
	s_setprio 0
	v_mfma_f32_16x16x32_bf16 v[122:125], v[158:161], v[174:177], v[122:125]
	v_mfma_f32_16x16x32_bf16 v[114:117], v[166:169], v[174:177], v[114:117]
	v_mfma_f32_16x16x32_bf16 v[106:109], v[158:161], v[186:189], v[106:109]
	v_mfma_f32_16x16x32_bf16 v[98:101], v[166:169], v[186:189], v[98:101]
	v_mfma_f32_16x16x32_bf16 v[90:93], v[158:161], v[194:197], v[90:93]
	v_mfma_f32_16x16x32_bf16 v[82:85], v[166:169], v[194:197], v[82:85]
	v_mfma_f32_16x16x32_bf16 v[74:77], v[158:161], v[202:205], v[74:77]
	v_mfma_f32_16x16x32_bf16 v[66:69], v[166:169], v[202:205], v[66:69]
	v_mfma_f32_16x16x32_bf16 v[122:125], v[162:165], v[178:181], v[122:125]
	v_mfma_f32_16x16x32_bf16 v[114:117], v[170:173], v[178:181], v[114:117]
	v_mfma_f32_16x16x32_bf16 v[106:109], v[162:165], v[190:193], v[106:109]
	v_mfma_f32_16x16x32_bf16 v[98:101], v[170:173], v[190:193], v[98:101]
	v_mfma_f32_16x16x32_bf16 v[90:93], v[162:165], v[198:201], v[90:93]
	v_mfma_f32_16x16x32_bf16 v[82:85], v[170:173], v[198:201], v[82:85]
	v_mfma_f32_16x16x32_bf16 v[74:77], v[162:165], v[214:217], v[74:77]
	v_mfma_f32_16x16x32_bf16 v[66:69], v[170:173], v[214:217], v[66:69]
	s_setprio 1
	s_barrier
	s_add_i32 s50, s51, s31
	v_lshl_add_u64 v[182:183], s[26:27], 0, v[0:1]
	s_mov_b32 m0, s50
	ds_read_b128 v[174:177], v141 offset:16384
	ds_read_b128 v[178:181], v141 offset:17408
	ds_read_b128 v[186:189], v141 offset:18432
	ds_read_b128 v[190:193], v141 offset:19456
	ds_read_b128 v[194:197], v141 offset:20480
	ds_read_b128 v[198:201], v141 offset:21504
	ds_read_b128 v[202:205], v141 offset:22528
	ds_read_b128 v[214:217], v141 offset:23552
	global_load_lds_dwordx4 v[182:183], off
	s_add_i32 m0, s50, 0x2000
	s_add_u32 s50, s26, 0x40000
	v_lshl_add_u64 v[206:207], s[26:27], 0, v[134:135]
	s_addc_u32 s51, s27, 0
	s_add_i32 s49, s49, s31
	global_load_lds_dwordx4 v[206:207], off
	v_lshl_add_u64 v[210:211], s[50:51], 0, v[0:1]
	s_mov_b32 m0, s49
	v_lshl_add_u64 v[224:225], s[28:29], 0, v[132:133]
	global_load_lds_dwordx4 v[210:211], off
	v_lshl_add_u64 v[210:211], s[50:51], 0, v[134:135]
	s_add_i32 m0, s49, 0x2000
	s_nop 0
	global_load_lds_dwordx4 v[210:211], off
	v_lshl_add_u64 v[210:211], s[28:29], 0, v[130:131]
	s_mov_b32 m0, s5
	s_nop 0
	global_load_lds_dwordx4 v[210:211], off
	s_mov_b32 m0, s38
	s_nop 0
	global_load_lds_dwordx4 v[224:225], off
	s_waitcnt vmcnt(8)
	s_waitcnt lgkmcnt(0)
	s_barrier
	s_setprio 0
	s_waitcnt lgkmcnt(0)
	v_mfma_f32_16x16x32_bf16 v[62:65], v[142:145], v[174:177], v[62:65]
	v_mfma_f32_16x16x32_bf16 v[54:57], v[150:153], v[174:177], v[54:57]
	v_mfma_f32_16x16x32_bf16 v[46:49], v[142:145], v[186:189], v[46:49]
	v_mfma_f32_16x16x32_bf16 v[38:41], v[150:153], v[186:189], v[38:41]
	v_mfma_f32_16x16x32_bf16 v[30:33], v[142:145], v[194:197], v[30:33]
	v_mfma_f32_16x16x32_bf16 v[22:25], v[150:153], v[194:197], v[22:25]
	v_mfma_f32_16x16x32_bf16 v[14:17], v[142:145], v[202:205], v[14:17]
	v_mfma_f32_16x16x32_bf16 v[6:9], v[150:153], v[202:205], v[6:9]
	v_mfma_f32_16x16x32_bf16 v[62:65], v[146:149], v[178:181], v[62:65]
	v_mfma_f32_16x16x32_bf16 v[54:57], v[154:157], v[178:181], v[54:57]
	v_mfma_f32_16x16x32_bf16 v[46:49], v[146:149], v[190:193], v[46:49]
	v_mfma_f32_16x16x32_bf16 v[38:41], v[154:157], v[190:193], v[38:41]
	v_mfma_f32_16x16x32_bf16 v[30:33], v[146:149], v[198:201], v[30:33]
	v_mfma_f32_16x16x32_bf16 v[22:25], v[154:157], v[198:201], v[22:25]
	v_mfma_f32_16x16x32_bf16 v[14:17], v[146:149], v[214:217], v[14:17]
	v_mfma_f32_16x16x32_bf16 v[6:9], v[154:157], v[214:217], v[6:9]
	s_setprio 1
	s_setprio 0
	v_mfma_f32_16x16x32_bf16 v[58:61], v[158:161], v[174:177], v[58:61]
	v_mfma_f32_16x16x32_bf16 v[50:53], v[166:169], v[174:177], v[50:53]
	v_mfma_f32_16x16x32_bf16 v[42:45], v[158:161], v[186:189], v[42:45]
	v_mfma_f32_16x16x32_bf16 v[34:37], v[166:169], v[186:189], v[34:37]
	v_mfma_f32_16x16x32_bf16 v[26:29], v[158:161], v[194:197], v[26:29]
	v_mfma_f32_16x16x32_bf16 v[18:21], v[166:169], v[194:197], v[18:21]
	v_mfma_f32_16x16x32_bf16 v[10:13], v[158:161], v[202:205], v[10:13]
	v_mfma_f32_16x16x32_bf16 v[2:5], v[166:169], v[202:205], v[2:5]
	v_mfma_f32_16x16x32_bf16 v[58:61], v[162:165], v[178:181], v[58:61]
	v_mfma_f32_16x16x32_bf16 v[50:53], v[170:173], v[178:181], v[50:53]
	v_mfma_f32_16x16x32_bf16 v[42:45], v[162:165], v[190:193], v[42:45]
	v_mfma_f32_16x16x32_bf16 v[34:37], v[170:173], v[190:193], v[34:37]
	v_mfma_f32_16x16x32_bf16 v[26:29], v[162:165], v[198:201], v[26:29]
	v_mfma_f32_16x16x32_bf16 v[18:21], v[170:173], v[198:201], v[18:21]
	v_mfma_f32_16x16x32_bf16 v[10:13], v[162:165], v[214:217], v[10:13]
	v_mfma_f32_16x16x32_bf16 v[2:5], v[170:173], v[214:217], v[2:5]
	s_setprio 1
	s_barrier
	s_add_i32 s49, 0, 0x18000
	s_add_i32 s50, 0, 0x1c000
	v_add_u32_e32 v154, s49, v140
	v_add_u32_e32 v170, s50, v140
	ds_read_b128 v[142:145], v154
	ds_read_b128 v[146:149], v154 offset:1024
	ds_read_b128 v[150:153], v154 offset:2048
	ds_read_b128 v[154:157], v154 offset:3072
	ds_read_b128 v[158:161], v170
	ds_read_b128 v[162:165], v170 offset:1024
	ds_read_b128 v[166:169], v170 offset:2048
	ds_read_b128 v[170:173], v170 offset:3072
	s_add_u32 s28, s28, 0x40000
	s_addc_u32 s29, s29, 0
	s_mov_b32 m0, s39
	v_lshl_add_u64 v[226:227], s[28:29], 0, v[130:131]
	ds_read_b128 v[174:177], v141 offset:32768
	ds_read_b128 v[178:181], v141 offset:33792
	ds_read_b128 v[186:189], v141 offset:34816
	ds_read_b128 v[190:193], v141 offset:35840
	ds_read_b128 v[194:197], v141 offset:36864
	ds_read_b128 v[198:201], v141 offset:37888
	ds_read_b128 v[202:205], v141 offset:38912
	ds_read_b128 v[214:217], v141 offset:39936
	global_load_lds_dwordx4 v[226:227], off
	v_lshl_add_u64 v[226:227], s[28:29], 0, v[132:133]
	s_mov_b32 m0, s40
	s_nop 0
	global_load_lds_dwordx4 v[226:227], off
	s_waitcnt vmcnt(8)
	s_waitcnt lgkmcnt(0)
	s_barrier
	s_setprio 0
	s_waitcnt lgkmcnt(0)
	v_mfma_f32_16x16x32_bf16 v[126:129], v[142:145], v[174:177], v[126:129]
	v_mfma_f32_16x16x32_bf16 v[118:121], v[150:153], v[174:177], v[118:121]
	v_mfma_f32_16x16x32_bf16 v[110:113], v[142:145], v[186:189], v[110:113]
	v_mfma_f32_16x16x32_bf16 v[102:105], v[150:153], v[186:189], v[102:105]
	v_mfma_f32_16x16x32_bf16 v[94:97], v[142:145], v[194:197], v[94:97]
	v_mfma_f32_16x16x32_bf16 v[86:89], v[150:153], v[194:197], v[86:89]
	v_mfma_f32_16x16x32_bf16 v[78:81], v[142:145], v[202:205], v[78:81]
	v_mfma_f32_16x16x32_bf16 v[70:73], v[150:153], v[202:205], v[70:73]
	v_mfma_f32_16x16x32_bf16 v[126:129], v[146:149], v[178:181], v[126:129]
	v_mfma_f32_16x16x32_bf16 v[118:121], v[154:157], v[178:181], v[118:121]
	v_mfma_f32_16x16x32_bf16 v[110:113], v[146:149], v[190:193], v[110:113]
	v_mfma_f32_16x16x32_bf16 v[102:105], v[154:157], v[190:193], v[102:105]
	v_mfma_f32_16x16x32_bf16 v[94:97], v[146:149], v[198:201], v[94:97]
	v_mfma_f32_16x16x32_bf16 v[86:89], v[154:157], v[198:201], v[86:89]
	v_mfma_f32_16x16x32_bf16 v[78:81], v[146:149], v[214:217], v[78:81]
	v_mfma_f32_16x16x32_bf16 v[70:73], v[154:157], v[214:217], v[70:73]
	s_setprio 1
	s_setprio 0
	v_mfma_f32_16x16x32_bf16 v[122:125], v[158:161], v[174:177], v[122:125]
	v_mfma_f32_16x16x32_bf16 v[114:117], v[166:169], v[174:177], v[114:117]
	v_mfma_f32_16x16x32_bf16 v[106:109], v[158:161], v[186:189], v[106:109]
	v_mfma_f32_16x16x32_bf16 v[98:101], v[166:169], v[186:189], v[98:101]
	v_mfma_f32_16x16x32_bf16 v[90:93], v[158:161], v[194:197], v[90:93]
	v_mfma_f32_16x16x32_bf16 v[82:85], v[166:169], v[194:197], v[82:85]
	v_mfma_f32_16x16x32_bf16 v[74:77], v[158:161], v[202:205], v[74:77]
	v_mfma_f32_16x16x32_bf16 v[66:69], v[166:169], v[202:205], v[66:69]
	v_mfma_f32_16x16x32_bf16 v[122:125], v[162:165], v[178:181], v[122:125]
	v_mfma_f32_16x16x32_bf16 v[114:117], v[170:173], v[178:181], v[114:117]
	v_mfma_f32_16x16x32_bf16 v[106:109], v[162:165], v[190:193], v[106:109]
	v_mfma_f32_16x16x32_bf16 v[98:101], v[170:173], v[190:193], v[98:101]
	v_mfma_f32_16x16x32_bf16 v[90:93], v[162:165], v[198:201], v[90:93]
	v_mfma_f32_16x16x32_bf16 v[82:85], v[170:173], v[198:201], v[82:85]
	v_mfma_f32_16x16x32_bf16 v[74:77], v[162:165], v[214:217], v[74:77]
	v_mfma_f32_16x16x32_bf16 v[66:69], v[170:173], v[214:217], v[66:69]
	s_setprio 1
	s_barrier
	s_add_i32 s28, s49, s31
	v_lshl_add_u64 v[182:183], v[182:183], 0, s[94:95]
	s_mov_b32 m0, s28
	ds_read_b128 v[174:177], v141 offset:49152
	ds_read_b128 v[178:181], v141 offset:50176
	ds_read_b128 v[186:189], v141 offset:51200
	ds_read_b128 v[190:193], v141 offset:52224
	ds_read_b128 v[194:197], v141 offset:53248
	ds_read_b128 v[198:201], v141 offset:54272
	ds_read_b128 v[202:205], v141 offset:55296
	ds_read_b128 v[214:217], v141 offset:56320
	global_load_lds_dwordx4 v[182:183], off
	s_add_i32 m0, s28, 0x2000
	s_add_u32 s26, s26, 0x40080
	v_lshl_add_u64 v[182:183], v[206:207], 0, s[94:95]
	s_addc_u32 s27, s27, 0
	s_add_i32 s28, s50, s31
	global_load_lds_dwordx4 v[182:183], off
	v_lshl_add_u64 v[182:183], s[26:27], 0, v[0:1]
	s_mov_b32 m0, s28
	s_nop 0
	global_load_lds_dwordx4 v[182:183], off
	v_lshl_add_u64 v[182:183], s[26:27], 0, v[134:135]
	s_add_i32 m0, s28, 0x2000
	s_nop 0
	global_load_lds_dwordx4 v[182:183], off
	v_lshl_add_u64 v[182:183], v[210:211], 0, s[94:95]
	s_mov_b32 m0, s42
	s_nop 0
	global_load_lds_dwordx4 v[182:183], off
	v_lshl_add_u64 v[182:183], v[224:225], 0, s[94:95]
	s_mov_b32 m0, s43
	s_nop 0
	global_load_lds_dwordx4 v[182:183], off
	s_waitcnt vmcnt(8)
	s_waitcnt lgkmcnt(0)
	s_barrier
	s_setprio 0
	s_waitcnt lgkmcnt(0)
	v_mfma_f32_16x16x32_bf16 v[62:65], v[142:145], v[174:177], v[62:65]
	v_mfma_f32_16x16x32_bf16 v[54:57], v[150:153], v[174:177], v[54:57]
	v_mfma_f32_16x16x32_bf16 v[46:49], v[142:145], v[186:189], v[46:49]
	v_mfma_f32_16x16x32_bf16 v[38:41], v[150:153], v[186:189], v[38:41]
	v_mfma_f32_16x16x32_bf16 v[30:33], v[142:145], v[194:197], v[30:33]
	v_mfma_f32_16x16x32_bf16 v[22:25], v[150:153], v[194:197], v[22:25]
	v_mfma_f32_16x16x32_bf16 v[14:17], v[142:145], v[202:205], v[14:17]
	v_mfma_f32_16x16x32_bf16 v[6:9], v[150:153], v[202:205], v[6:9]
	v_mfma_f32_16x16x32_bf16 v[62:65], v[146:149], v[178:181], v[62:65]
	v_mfma_f32_16x16x32_bf16 v[54:57], v[154:157], v[178:181], v[54:57]
	v_mfma_f32_16x16x32_bf16 v[46:49], v[146:149], v[190:193], v[46:49]
	v_mfma_f32_16x16x32_bf16 v[38:41], v[154:157], v[190:193], v[38:41]
	v_mfma_f32_16x16x32_bf16 v[30:33], v[146:149], v[198:201], v[30:33]
	v_mfma_f32_16x16x32_bf16 v[22:25], v[154:157], v[198:201], v[22:25]
	v_mfma_f32_16x16x32_bf16 v[14:17], v[146:149], v[214:217], v[14:17]
	v_mfma_f32_16x16x32_bf16 v[6:9], v[154:157], v[214:217], v[6:9]
	s_setprio 1
	s_setprio 0
	v_mfma_f32_16x16x32_bf16 v[58:61], v[158:161], v[174:177], v[58:61]
	v_mfma_f32_16x16x32_bf16 v[50:53], v[166:169], v[174:177], v[50:53]
	v_mfma_f32_16x16x32_bf16 v[42:45], v[158:161], v[186:189], v[42:45]
	v_mfma_f32_16x16x32_bf16 v[34:37], v[166:169], v[186:189], v[34:37]
	v_mfma_f32_16x16x32_bf16 v[26:29], v[158:161], v[194:197], v[26:29]
	v_mfma_f32_16x16x32_bf16 v[18:21], v[166:169], v[194:197], v[18:21]
	v_mfma_f32_16x16x32_bf16 v[10:13], v[158:161], v[202:205], v[10:13]
	v_mfma_f32_16x16x32_bf16 v[2:5], v[166:169], v[202:205], v[2:5]
	v_mfma_f32_16x16x32_bf16 v[58:61], v[162:165], v[178:181], v[58:61]
	v_mfma_f32_16x16x32_bf16 v[50:53], v[170:173], v[178:181], v[50:53]
	v_mfma_f32_16x16x32_bf16 v[42:45], v[162:165], v[190:193], v[42:45]
	v_mfma_f32_16x16x32_bf16 v[34:37], v[170:173], v[190:193], v[34:37]
	v_mfma_f32_16x16x32_bf16 v[26:29], v[162:165], v[198:201], v[26:29]
	v_mfma_f32_16x16x32_bf16 v[18:21], v[170:173], v[198:201], v[18:21]
	v_mfma_f32_16x16x32_bf16 v[10:13], v[162:165], v[214:217], v[10:13]
	v_mfma_f32_16x16x32_bf16 v[2:5], v[170:173], v[214:217], v[2:5]
	s_setprio 1
	s_barrier
	s_add_i32 s48, s48, 2
	s_add_u32 s24, s24, 0x100
	s_addc_u32 s25, s25, 0
	s_cmp_gt_u32 s48, 13
	s_cbranch_scc0 .LBB0_1192
	s_cmpk_lt_u32 s30, 0x100
	s_cbranch_scc0 .LBB0_1195
	s_barrier

.LBB0_1202:
	s_add_u32 s20, s41, s8
	s_addc_u32 s21, s42, s9
	s_add_u32 s20, s20, 0x14200100
	s_addc_u32 s21, s21, 0
	s_add_u32 s46, s43, s8
	s_addc_u32 s47, s44, s9
	s_add_i32 s48, 0, 0x10000
	s_cmpk_eq_i32 s8, 0x700
	s_cselect_b32 s23, s7, s21
	s_cselect_b32 s22, s6, s20
	s_cselect_b32 s21, s5, s47
	s_cselect_b32 s20, s4, s46
	s_add_i32 s49, 0, 0x14000
	v_add_u32_e32 v150, s48, v136
	v_add_u32_e32 v166, s49, v136
	ds_read_b128 v[138:141], v150
	ds_read_b128 v[142:145], v150 offset:1024
	ds_read_b128 v[146:149], v150 offset:2048
	ds_read_b128 v[150:153], v150 offset:3072
	ds_read_b128 v[154:157], v166
	ds_read_b128 v[158:161], v166 offset:1024
	ds_read_b128 v[162:165], v166 offset:2048
	ds_read_b128 v[166:169], v166 offset:3072
	v_lshl_add_u64 v[182:183], v[132:133], 0, s[8:9]
	s_add_i32 m0, s29, 0xc000
	ds_read_b128 v[170:173], v137
	ds_read_b128 v[174:177], v137 offset:1024
	ds_read_b128 v[178:181], v137 offset:2048
	ds_read_b128 v[186:189], v137 offset:3072
	ds_read_b128 v[190:193], v137 offset:4096
	ds_read_b128 v[202:205], v137 offset:5120
	ds_read_b128 v[214:217], v137 offset:6144
	ds_read_b128 v[224:227], v137 offset:7168
	global_load_lds_dwordx4 v[182:183], off
	v_lshl_add_u64 v[182:183], v[134:135], 0, s[8:9]
	s_add_i32 m0, s29, 0xe000
	s_nop 0
	global_load_lds_dwordx4 v[182:183], off
	s_waitcnt vmcnt(8)
	s_waitcnt lgkmcnt(0)
	s_barrier
	s_setprio 0
	s_waitcnt lgkmcnt(0)
	v_mfma_f32_16x16x32_bf16 v[126:129], v[138:141], v[170:173], v[126:129]
	v_mfma_f32_16x16x32_bf16 v[122:125], v[146:149], v[170:173], v[122:125]
	v_mfma_f32_16x16x32_bf16 v[114:117], v[138:141], v[178:181], v[114:117]
	v_mfma_f32_16x16x32_bf16 v[106:109], v[146:149], v[178:181], v[106:109]
	v_mfma_f32_16x16x32_bf16 v[98:101], v[138:141], v[190:193], v[98:101]
	v_mfma_f32_16x16x32_bf16 v[90:93], v[146:149], v[190:193], v[90:93]
	v_mfma_f32_16x16x32_bf16 v[82:85], v[138:141], v[214:217], v[82:85]
	v_mfma_f32_16x16x32_bf16 v[74:77], v[146:149], v[214:217], v[74:77]
	v_mfma_f32_16x16x32_bf16 v[126:129], v[142:145], v[174:177], v[126:129]
	v_mfma_f32_16x16x32_bf16 v[122:125], v[150:153], v[174:177], v[122:125]
	v_mfma_f32_16x16x32_bf16 v[114:117], v[142:145], v[186:189], v[114:117]
	v_mfma_f32_16x16x32_bf16 v[106:109], v[150:153], v[186:189], v[106:109]
	v_mfma_f32_16x16x32_bf16 v[98:101], v[142:145], v[202:205], v[98:101]
	v_mfma_f32_16x16x32_bf16 v[90:93], v[150:153], v[202:205], v[90:93]
	v_mfma_f32_16x16x32_bf16 v[82:85], v[142:145], v[224:227], v[82:85]
	v_mfma_f32_16x16x32_bf16 v[74:77], v[150:153], v[224:227], v[74:77]
	s_setprio 1
	s_setprio 0
	v_mfma_f32_16x16x32_bf16 v[118:121], v[154:157], v[170:173], v[118:121]
	v_mfma_f32_16x16x32_bf16 v[110:113], v[162:165], v[170:173], v[110:113]
	v_mfma_f32_16x16x32_bf16 v[102:105], v[154:157], v[178:181], v[102:105]
	v_mfma_f32_16x16x32_bf16 v[94:97], v[162:165], v[178:181], v[94:97]
	v_mfma_f32_16x16x32_bf16 v[86:89], v[154:157], v[190:193], v[86:89]
	v_mfma_f32_16x16x32_bf16 v[78:81], v[162:165], v[190:193], v[78:81]
	v_mfma_f32_16x16x32_bf16 v[70:73], v[154:157], v[214:217], v[70:73]
	v_mfma_f32_16x16x32_bf16 v[66:69], v[162:165], v[214:217], v[66:69]
	v_mfma_f32_16x16x32_bf16 v[118:121], v[158:161], v[174:177], v[118:121]
	v_mfma_f32_16x16x32_bf16 v[110:113], v[166:169], v[174:177], v[110:113]
	v_mfma_f32_16x16x32_bf16 v[102:105], v[158:161], v[186:189], v[102:105]
	v_mfma_f32_16x16x32_bf16 v[94:97], v[166:169], v[186:189], v[94:97]
	v_mfma_f32_16x16x32_bf16 v[86:89], v[158:161], v[202:205], v[86:89]
	v_mfma_f32_16x16x32_bf16 v[78:81], v[166:169], v[202:205], v[78:81]
	v_mfma_f32_16x16x32_bf16 v[70:73], v[158:161], v[224:227], v[70:73]
	v_mfma_f32_16x16x32_bf16 v[66:69], v[166:169], v[224:227], v[66:69]
	s_setprio 1
	s_barrier
	s_add_i32 s46, s48, s28
	v_lshl_add_u64 v[182:183], s[20:21], 0, v[0:1]
	s_mov_b32 m0, s46
	ds_read_b128 v[170:173], v137 offset:16384
	ds_read_b128 v[174:177], v137 offset:17408
	ds_read_b128 v[178:181], v137 offset:18432
	ds_read_b128 v[186:189], v137 offset:19456
	ds_read_b128 v[190:193], v137 offset:20480
	ds_read_b128 v[202:205], v137 offset:21504
	ds_read_b128 v[214:217], v137 offset:22528
	ds_read_b128 v[224:227], v137 offset:23552
	global_load_lds_dwordx4 v[182:183], off
	s_add_i32 m0, s46, 0x2000
	s_add_u32 s46, s20, 0x40000
	v_lshl_add_u64 v[194:195], s[20:21], 0, v[130:131]
	s_addc_u32 s47, s21, 0
	s_add_i32 s48, s49, s28
	global_load_lds_dwordx4 v[194:195], off
	v_lshl_add_u64 v[196:197], s[46:47], 0, v[0:1]
	s_mov_b32 m0, s48
	v_lshl_add_u64 v[198:199], s[22:23], 0, v[130:131]
	global_load_lds_dwordx4 v[196:197], off
	v_lshl_add_u64 v[196:197], s[46:47], 0, v[130:131]
	s_add_i32 m0, s48, 0x2000
	s_nop 0
	global_load_lds_dwordx4 v[196:197], off
	v_lshl_add_u64 v[196:197], s[22:23], 0, v[0:1]
	s_mov_b32 m0, s29
	s_nop 0
	global_load_lds_dwordx4 v[196:197], off
	s_mov_b32 m0, s30
	s_nop 0
	global_load_lds_dwordx4 v[198:199], off
	s_waitcnt vmcnt(8)
	s_waitcnt lgkmcnt(0)
	s_barrier
	s_setprio 0
	s_waitcnt lgkmcnt(0)
	v_mfma_f32_16x16x32_bf16 v[62:65], v[138:141], v[170:173], v[62:65]
	v_mfma_f32_16x16x32_bf16 v[58:61], v[146:149], v[170:173], v[58:61]
	v_mfma_f32_16x16x32_bf16 v[50:53], v[138:141], v[178:181], v[50:53]
	v_mfma_f32_16x16x32_bf16 v[42:45], v[146:149], v[178:181], v[42:45]
	v_mfma_f32_16x16x32_bf16 v[34:37], v[138:141], v[190:193], v[34:37]
	v_mfma_f32_16x16x32_bf16 v[26:29], v[146:149], v[190:193], v[26:29]
	v_mfma_f32_16x16x32_bf16 v[18:21], v[138:141], v[214:217], v[18:21]
	v_mfma_f32_16x16x32_bf16 v[10:13], v[146:149], v[214:217], v[10:13]
	v_mfma_f32_16x16x32_bf16 v[62:65], v[142:145], v[174:177], v[62:65]
	v_mfma_f32_16x16x32_bf16 v[58:61], v[150:153], v[174:177], v[58:61]
	v_mfma_f32_16x16x32_bf16 v[50:53], v[142:145], v[186:189], v[50:53]
	v_mfma_f32_16x16x32_bf16 v[42:45], v[150:153], v[186:189], v[42:45]
	v_mfma_f32_16x16x32_bf16 v[34:37], v[142:145], v[202:205], v[34:37]
	v_mfma_f32_16x16x32_bf16 v[26:29], v[150:153], v[202:205], v[26:29]
	v_mfma_f32_16x16x32_bf16 v[18:21], v[142:145], v[224:227], v[18:21]
	v_mfma_f32_16x16x32_bf16 v[10:13], v[150:153], v[224:227], v[10:13]
	s_setprio 1
	s_setprio 0
	v_mfma_f32_16x16x32_bf16 v[54:57], v[154:157], v[170:173], v[54:57]
	v_mfma_f32_16x16x32_bf16 v[46:49], v[162:165], v[170:173], v[46:49]
	v_mfma_f32_16x16x32_bf16 v[38:41], v[154:157], v[178:181], v[38:41]
	v_mfma_f32_16x16x32_bf16 v[30:33], v[162:165], v[178:181], v[30:33]
	v_mfma_f32_16x16x32_bf16 v[22:25], v[154:157], v[190:193], v[22:25]
	v_mfma_f32_16x16x32_bf16 v[14:17], v[162:165], v[190:193], v[14:17]
	v_mfma_f32_16x16x32_bf16 v[6:9], v[154:157], v[214:217], v[6:9]
	v_mfma_f32_16x16x32_bf16 v[2:5], v[162:165], v[214:217], v[2:5]
	v_mfma_f32_16x16x32_bf16 v[54:57], v[158:161], v[174:177], v[54:57]
	v_mfma_f32_16x16x32_bf16 v[46:49], v[166:169], v[174:177], v[46:49]
	v_mfma_f32_16x16x32_bf16 v[38:41], v[158:161], v[186:189], v[38:41]
	v_mfma_f32_16x16x32_bf16 v[30:33], v[166:169], v[186:189], v[30:33]
	v_mfma_f32_16x16x32_bf16 v[22:25], v[158:161], v[202:205], v[22:25]
	v_mfma_f32_16x16x32_bf16 v[14:17], v[166:169], v[202:205], v[14:17]
	v_mfma_f32_16x16x32_bf16 v[6:9], v[158:161], v[224:227], v[6:9]
	v_mfma_f32_16x16x32_bf16 v[2:5], v[166:169], v[224:227], v[2:5]
	s_setprio 1
	s_barrier
	s_add_i32 s46, 0, 0x18000
	s_add_i32 s47, 0, 0x1c000
	v_add_u32_e32 v150, s46, v136
	v_add_u32_e32 v166, s47, v136
	ds_read_b128 v[138:141], v150
	ds_read_b128 v[142:145], v150 offset:1024
	ds_read_b128 v[146:149], v150 offset:2048
	ds_read_b128 v[150:153], v150 offset:3072
	ds_read_b128 v[154:157], v166
	ds_read_b128 v[158:161], v166 offset:1024
	ds_read_b128 v[162:165], v166 offset:2048
	ds_read_b128 v[166:169], v166 offset:3072
	s_add_u32 s22, s22, 0x40000
	s_addc_u32 s23, s23, 0
	s_mov_b32 m0, s31
	v_lshl_add_u64 v[200:201], s[22:23], 0, v[0:1]
	ds_read_b128 v[170:173], v137 offset:32768
	ds_read_b128 v[174:177], v137 offset:33792
	ds_read_b128 v[178:181], v137 offset:34816
	ds_read_b128 v[186:189], v137 offset:35840
	ds_read_b128 v[190:193], v137 offset:36864
	ds_read_b128 v[202:205], v137 offset:37888
	ds_read_b128 v[214:217], v137 offset:38912
	ds_read_b128 v[224:227], v137 offset:39936
	global_load_lds_dwordx4 v[200:201], off
	v_lshl_add_u64 v[200:201], s[22:23], 0, v[130:131]
	s_mov_b32 m0, s37
	s_nop 0
	global_load_lds_dwordx4 v[200:201], off
	s_waitcnt vmcnt(8)
	s_waitcnt lgkmcnt(0)
	s_barrier
	s_setprio 0
	s_waitcnt lgkmcnt(0)
	v_mfma_f32_16x16x32_bf16 v[126:129], v[138:141], v[170:173], v[126:129]
	v_mfma_f32_16x16x32_bf16 v[122:125], v[146:149], v[170:173], v[122:125]
	v_mfma_f32_16x16x32_bf16 v[114:117], v[138:141], v[178:181], v[114:117]
	v_mfma_f32_16x16x32_bf16 v[106:109], v[146:149], v[178:181], v[106:109]
	v_mfma_f32_16x16x32_bf16 v[98:101], v[138:141], v[190:193], v[98:101]
	v_mfma_f32_16x16x32_bf16 v[90:93], v[146:149], v[190:193], v[90:93]
	v_mfma_f32_16x16x32_bf16 v[82:85], v[138:141], v[214:217], v[82:85]
	v_mfma_f32_16x16x32_bf16 v[74:77], v[146:149], v[214:217], v[74:77]
	v_mfma_f32_16x16x32_bf16 v[126:129], v[142:145], v[174:177], v[126:129]
	v_mfma_f32_16x16x32_bf16 v[122:125], v[150:153], v[174:177], v[122:125]
	v_mfma_f32_16x16x32_bf16 v[114:117], v[142:145], v[186:189], v[114:117]
	v_mfma_f32_16x16x32_bf16 v[106:109], v[150:153], v[186:189], v[106:109]
	v_mfma_f32_16x16x32_bf16 v[98:101], v[142:145], v[202:205], v[98:101]
	v_mfma_f32_16x16x32_bf16 v[90:93], v[150:153], v[202:205], v[90:93]
	v_mfma_f32_16x16x32_bf16 v[82:85], v[142:145], v[224:227], v[82:85]
	v_mfma_f32_16x16x32_bf16 v[74:77], v[150:153], v[224:227], v[74:77]
	s_setprio 1
	s_setprio 0
	v_mfma_f32_16x16x32_bf16 v[118:121], v[154:157], v[170:173], v[118:121]
	v_mfma_f32_16x16x32_bf16 v[110:113], v[162:165], v[170:173], v[110:113]
	v_mfma_f32_16x16x32_bf16 v[102:105], v[154:157], v[178:181], v[102:105]
	v_mfma_f32_16x16x32_bf16 v[94:97], v[162:165], v[178:181], v[94:97]
	v_mfma_f32_16x16x32_bf16 v[86:89], v[154:157], v[190:193], v[86:89]
	v_mfma_f32_16x16x32_bf16 v[78:81], v[162:165], v[190:193], v[78:81]
	v_mfma_f32_16x16x32_bf16 v[70:73], v[154:157], v[214:217], v[70:73]
	v_mfma_f32_16x16x32_bf16 v[66:69], v[162:165], v[214:217], v[66:69]
	v_mfma_f32_16x16x32_bf16 v[118:121], v[158:161], v[174:177], v[118:121]
	v_mfma_f32_16x16x32_bf16 v[110:113], v[166:169], v[174:177], v[110:113]
	v_mfma_f32_16x16x32_bf16 v[102:105], v[158:161], v[186:189], v[102:105]
	v_mfma_f32_16x16x32_bf16 v[94:97], v[166:169], v[186:189], v[94:97]
	v_mfma_f32_16x16x32_bf16 v[86:89], v[158:161], v[202:205], v[86:89]
	v_mfma_f32_16x16x32_bf16 v[78:81], v[166:169], v[202:205], v[78:81]
	v_mfma_f32_16x16x32_bf16 v[70:73], v[158:161], v[224:227], v[70:73]
	v_mfma_f32_16x16x32_bf16 v[66:69], v[166:169], v[224:227], v[66:69]
	s_setprio 1
	s_barrier
	s_add_i32 s22, s46, s28
	v_lshl_add_u64 v[182:183], v[182:183], 0, s[94:95]
	s_mov_b32 m0, s22
	ds_read_b128 v[170:173], v137 offset:49152
	ds_read_b128 v[174:177], v137 offset:50176
	ds_read_b128 v[178:181], v137 offset:51200
	ds_read_b128 v[186:189], v137 offset:52224
	ds_read_b128 v[190:193], v137 offset:53248
	ds_read_b128 v[202:205], v137 offset:54272
	ds_read_b128 v[214:217], v137 offset:55296
	ds_read_b128 v[224:227], v137 offset:56320
	global_load_lds_dwordx4 v[182:183], off
	s_add_i32 m0, s22, 0x2000
	s_add_u32 s20, s20, 0x40080
	v_lshl_add_u64 v[182:183], v[194:195], 0, s[94:95]
	s_addc_u32 s21, s21, 0
	s_add_i32 s22, s47, s28
	global_load_lds_dwordx4 v[182:183], off
	v_lshl_add_u64 v[182:183], s[20:21], 0, v[0:1]
	s_mov_b32 m0, s22
	s_nop 0
	global_load_lds_dwordx4 v[182:183], off
	v_lshl_add_u64 v[182:183], s[20:21], 0, v[130:131]
	s_add_i32 m0, s22, 0x2000
	s_nop 0
	global_load_lds_dwordx4 v[182:183], off
	v_lshl_add_u64 v[182:183], v[196:197], 0, s[94:95]
	s_mov_b32 m0, s39
	s_nop 0
	global_load_lds_dwordx4 v[182:183], off
	v_lshl_add_u64 v[182:183], v[198:199], 0, s[94:95]
	s_mov_b32 m0, s40
	s_nop 0
	global_load_lds_dwordx4 v[182:183], off
	s_waitcnt vmcnt(8)
	s_waitcnt lgkmcnt(0)
	s_barrier
	s_setprio 0
	s_waitcnt lgkmcnt(0)
	v_mfma_f32_16x16x32_bf16 v[62:65], v[138:141], v[170:173], v[62:65]
	v_mfma_f32_16x16x32_bf16 v[58:61], v[146:149], v[170:173], v[58:61]
	v_mfma_f32_16x16x32_bf16 v[50:53], v[138:141], v[178:181], v[50:53]
	v_mfma_f32_16x16x32_bf16 v[42:45], v[146:149], v[178:181], v[42:45]
	v_mfma_f32_16x16x32_bf16 v[34:37], v[138:141], v[190:193], v[34:37]
	v_mfma_f32_16x16x32_bf16 v[26:29], v[146:149], v[190:193], v[26:29]
	v_mfma_f32_16x16x32_bf16 v[18:21], v[138:141], v[214:217], v[18:21]
	v_mfma_f32_16x16x32_bf16 v[10:13], v[146:149], v[214:217], v[10:13]
	v_mfma_f32_16x16x32_bf16 v[62:65], v[142:145], v[174:177], v[62:65]
	v_mfma_f32_16x16x32_bf16 v[58:61], v[150:153], v[174:177], v[58:61]
	v_mfma_f32_16x16x32_bf16 v[50:53], v[142:145], v[186:189], v[50:53]
	v_mfma_f32_16x16x32_bf16 v[42:45], v[150:153], v[186:189], v[42:45]
	v_mfma_f32_16x16x32_bf16 v[34:37], v[142:145], v[202:205], v[34:37]
	v_mfma_f32_16x16x32_bf16 v[26:29], v[150:153], v[202:205], v[26:29]
	v_mfma_f32_16x16x32_bf16 v[18:21], v[142:145], v[224:227], v[18:21]
	v_mfma_f32_16x16x32_bf16 v[10:13], v[150:153], v[224:227], v[10:13]
	s_setprio 1
	s_setprio 0
	v_mfma_f32_16x16x32_bf16 v[54:57], v[154:157], v[170:173], v[54:57]
	v_mfma_f32_16x16x32_bf16 v[46:49], v[162:165], v[170:173], v[46:49]
	v_mfma_f32_16x16x32_bf16 v[38:41], v[154:157], v[178:181], v[38:41]
	v_mfma_f32_16x16x32_bf16 v[30:33], v[162:165], v[178:181], v[30:33]
	v_mfma_f32_16x16x32_bf16 v[22:25], v[154:157], v[190:193], v[22:25]
	v_mfma_f32_16x16x32_bf16 v[14:17], v[162:165], v[190:193], v[14:17]
	v_mfma_f32_16x16x32_bf16 v[6:9], v[154:157], v[214:217], v[6:9]
	v_mfma_f32_16x16x32_bf16 v[2:5], v[162:165], v[214:217], v[2:5]
	v_mfma_f32_16x16x32_bf16 v[54:57], v[158:161], v[174:177], v[54:57]
	v_mfma_f32_16x16x32_bf16 v[46:49], v[166:169], v[174:177], v[46:49]
	v_mfma_f32_16x16x32_bf16 v[38:41], v[158:161], v[186:189], v[38:41]
	v_mfma_f32_16x16x32_bf16 v[30:33], v[166:169], v[186:189], v[30:33]
	v_mfma_f32_16x16x32_bf16 v[22:25], v[158:161], v[202:205], v[22:25]
	v_mfma_f32_16x16x32_bf16 v[14:17], v[166:169], v[202:205], v[14:17]
	v_mfma_f32_16x16x32_bf16 v[6:9], v[158:161], v[224:227], v[6:9]
	v_mfma_f32_16x16x32_bf16 v[2:5], v[166:169], v[224:227], v[2:5]
	s_setprio 1
	s_barrier
	s_add_i32 s45, s45, 2
	s_add_u32 s8, s8, 0x100
	s_addc_u32 s9, s9, 0
	s_cmp_gt_u32 s45, 13
	s_cbranch_scc0 .LBB0_1202
	s_cmpk_lt_u32 s27, 0x100
	s_cbranch_scc0 .LBB0_1205
	s_barrier

.LBB0_1213:
	s_add_i32 s23, 0, 0x18000
	s_and_b32 s13, s7, 3
	s_add_i32 s28, s23, s6
	s_lshl_b32 s7, s27, 13
	s_lshl_b32 s22, s13, 12
	v_lshl_add_u64 v[22:23], v[2:3], 0, s[94:95]
	s_mov_b32 m0, s28
	s_add_i32 s30, s28, 0x2000
	s_add_i32 s29, s3, 0x8000
	s_add_i32 s31, s3, 0xa000
	s_waitcnt vmcnt(2)
	s_barrier
	global_load_lds_dwordx4 v[22:23], off
	v_lshl_add_u64 v[24:25], v[6:7], 0, s[94:95]
	s_mov_b32 m0, s30
	s_add_u32 s20, s4, 0x10080
	global_load_lds_dwordx4 v[24:25], off
	v_lshl_add_u64 v[20:21], v[18:19], 0, s[94:95]
	s_mov_b32 m0, s29
	s_addc_u32 s21, s5, 0
	s_add_i32 s39, 0, 0x1c000
	global_load_lds_dwordx4 v[20:21], off
	v_lshl_add_u64 v[26:27], v[28:29], 0, s[94:95]
	s_mov_b32 m0, s31
	s_add_i32 s36, s39, s6
	global_load_lds_dwordx4 v[26:27], off
	v_lshl_add_u64 v[30:31], s[20:21], 0, v[0:1]
	s_mov_b32 m0, s36
	s_add_i32 s37, s36, 0x2000
	global_load_lds_dwordx4 v[30:31], off
	v_lshl_add_u64 v[32:33], s[20:21], 0, v[34:35]
	s_mov_b32 m0, s37
	v_and_b32_e32 v8, 48, v36
	global_load_lds_dwordx4 v[32:33], off
	v_lshlrev_b32_e32 v9, 6, v36
	s_movk_i32 s20, 0x3c0
	v_and_or_b32 v8, v9, s20, v8
	v_lshlrev_b32_e32 v9, 2, v36
	v_and_b32_e32 v9, 32, v9
	v_bitop3_b32 v10, v8, s7, v9 bitop3:0xde
	v_bitop3_b32 v8, v8, s22, v9 bitop3:0xde
	s_add_i32 s40, 0, 0x10000
	s_add_i32 s42, 0, 0x14000
	v_add_u32_e32 v11, s40, v8
	s_add_u32 s46, s8, 0x40080
	s_waitcnt vmcnt(6)
	s_barrier
	v_add_u32_e32 v184, s42, v8
	s_addc_u32 s47, s9, 0
	s_add_i32 s40, s40, s6
	ds_read_b128 v[36:39], v11
	ds_read_b128 v[40:43], v11 offset:1024
	ds_read_b128 v[44:47], v11 offset:2048
	ds_read_b128 v[48:51], v11 offset:3072
	ds_read_b128 v[52:55], v184
	ds_read_b128 v[56:59], v184 offset:1024
	ds_read_b128 v[60:63], v184 offset:2048
	ds_read_b128 v[64:67], v184 offset:3072
	v_add_u32_e32 v218, s39, v8
	s_add_i32 s45, s3, 0xc000
	s_add_i32 s44, s3, 0xe000
	s_add_i32 s39, s40, 0x2000
	s_add_u32 s22, s4, 0x10100
	v_add_u32_e32 v212, s23, v8
	s_addc_u32 s23, s5, 0
	s_add_i32 s42, s42, s6
	s_add_i32 s41, s42, 0x2000
	s_add_u32 s20, s8, 0x40100
	s_addc_u32 s21, s9, 0
	s_add_u32 s6, s4, 0x10180
	s_addc_u32 s7, s5, 0
	s_add_u32 s4, s8, 0x40180
	s_addc_u32 s5, s9, 0
	v_add_u32_e32 v208, 0, v10
	s_cmpk_gt_u32 s43, 0xff
	s_mov_b32 m0, s45
	v_lshl_add_u64 v[8:9], s[46:47], 0, v[4:5]
	ds_read_b128 v[68:71], v208
	ds_read_b128 v[72:75], v208 offset:1024
	ds_read_b128 v[76:79], v208 offset:2048
	ds_read_b128 v[80:83], v208 offset:3072
	ds_read_b128 v[84:87], v208 offset:4096
	ds_read_b128 v[88:91], v208 offset:5120
	ds_read_b128 v[92:95], v208 offset:6144
	ds_read_b128 v[96:99], v208 offset:7168
	global_load_lds_dwordx4 v[8:9], off
	v_lshl_add_u64 v[8:9], s[46:47], 0, v[16:17]
	s_mov_b32 m0, s44
	s_nop 0
	global_load_lds_dwordx4 v[8:9], off
	s_waitcnt vmcnt(8)
	s_waitcnt lgkmcnt(0)
	s_barrier
	s_setprio 0
	s_waitcnt lgkmcnt(0)
	v_mfma_f32_16x16x32_bf16 v[100:103], v[36:39], v[68:71], 0
	v_mfma_f32_16x16x32_bf16 v[104:107], v[44:47], v[68:71], 0
	v_mfma_f32_16x16x32_bf16 v[108:111], v[36:39], v[76:79], 0
	s_waitcnt vmcnt(0)
	v_mfma_f32_16x16x32_bf16 v[112:115], v[44:47], v[76:79], 0
	v_mfma_f32_16x16x32_bf16 v[116:119], v[36:39], v[84:87], 0
	v_mfma_f32_16x16x32_bf16 v[120:123], v[44:47], v[84:87], 0
	v_mfma_f32_16x16x32_bf16 v[124:127], v[36:39], v[92:95], 0
	v_mfma_f32_16x16x32_bf16 v[128:131], v[44:47], v[92:95], 0
	v_mfma_f32_16x16x32_bf16 v[100:103], v[40:43], v[72:75], v[100:103]
	v_mfma_f32_16x16x32_bf16 v[104:107], v[48:51], v[72:75], v[104:107]
	v_mfma_f32_16x16x32_bf16 v[108:111], v[40:43], v[80:83], v[108:111]
	v_mfma_f32_16x16x32_bf16 v[112:115], v[48:51], v[80:83], v[112:115]
	v_mfma_f32_16x16x32_bf16 v[116:119], v[40:43], v[88:91], v[116:119]
	v_mfma_f32_16x16x32_bf16 v[120:123], v[48:51], v[88:91], v[120:123]
	v_mfma_f32_16x16x32_bf16 v[124:127], v[40:43], v[96:99], v[124:127]
	v_mfma_f32_16x16x32_bf16 v[128:131], v[48:51], v[96:99], v[128:131]
	s_setprio 1
	s_setprio 0
	v_mfma_f32_16x16x32_bf16 v[132:135], v[52:55], v[68:71], 0
	v_mfma_f32_16x16x32_bf16 v[68:71], v[60:63], v[68:71], 0
	v_mfma_f32_16x16x32_bf16 v[132:135], v[56:59], v[72:75], v[132:135]
	v_mfma_f32_16x16x32_bf16 v[68:71], v[64:67], v[72:75], v[68:71]
	v_mfma_f32_16x16x32_bf16 v[72:75], v[52:55], v[76:79], 0
	v_mfma_f32_16x16x32_bf16 v[76:79], v[60:63], v[76:79], 0
	v_mfma_f32_16x16x32_bf16 v[72:75], v[56:59], v[80:83], v[72:75]
	v_mfma_f32_16x16x32_bf16 v[76:79], v[64:67], v[80:83], v[76:79]
	v_mfma_f32_16x16x32_bf16 v[80:83], v[52:55], v[84:87], 0
	v_mfma_f32_16x16x32_bf16 v[84:87], v[60:63], v[84:87], 0
	v_mfma_f32_16x16x32_bf16 v[80:83], v[56:59], v[88:91], v[80:83]
	v_mfma_f32_16x16x32_bf16 v[84:87], v[64:67], v[88:91], v[84:87]
	v_mfma_f32_16x16x32_bf16 v[88:91], v[52:55], v[92:95], 0
	v_mfma_f32_16x16x32_bf16 v[92:95], v[60:63], v[92:95], 0
	v_mfma_f32_16x16x32_bf16 v[88:91], v[56:59], v[96:99], v[88:91]
	v_mfma_f32_16x16x32_bf16 v[92:95], v[64:67], v[96:99], v[92:95]
	s_setprio 1
	s_barrier
	s_mov_b64 s[8:9], 0x100
	s_mov_b32 m0, s40
	v_lshl_add_u64 v[8:9], v[2:3], 0, s[8:9]
	ds_read_b128 v[96:99], v208 offset:16384
	ds_read_b128 v[136:139], v208 offset:17408
	ds_read_b128 v[140:143], v208 offset:18432
	ds_read_b128 v[144:147], v208 offset:19456
	ds_read_b128 v[148:151], v208 offset:20480
	ds_read_b128 v[152:155], v208 offset:21504
	ds_read_b128 v[156:159], v208 offset:22528
	ds_read_b128 v[160:163], v208 offset:23552
	global_load_lds_dwordx4 v[8:9], off
	v_lshl_add_u64 v[8:9], v[6:7], 0, s[8:9]
	s_mov_b32 m0, s39
	s_nop 0
	global_load_lds_dwordx4 v[8:9], off
	v_lshl_add_u64 v[8:9], s[22:23], 0, v[0:1]
	s_mov_b32 m0, s42
	s_nop 0
	global_load_lds_dwordx4 v[8:9], off
	v_lshl_add_u64 v[8:9], s[22:23], 0, v[34:35]
	s_mov_b32 m0, s41
	s_nop 0
	global_load_lds_dwordx4 v[8:9], off
	v_lshl_add_u64 v[8:9], v[18:19], 0, s[8:9]
	s_mov_b32 m0, s3
	s_nop 0
	global_load_lds_dwordx4 v[8:9], off
	v_lshl_add_u64 v[8:9], v[28:29], 0, s[8:9]
	s_mov_b32 m0, s38
	s_nop 0
	global_load_lds_dwordx4 v[8:9], off
	s_waitcnt vmcnt(8)
	s_waitcnt lgkmcnt(0)
	s_barrier
	s_setprio 0
	s_waitcnt lgkmcnt(0)
	v_mfma_f32_16x16x32_bf16 v[164:167], v[36:39], v[96:99], 0
	v_mfma_f32_16x16x32_bf16 v[172:175], v[36:39], v[140:143], 0
	v_mfma_f32_16x16x32_bf16 v[180:183], v[36:39], v[148:151], 0
	v_mfma_f32_16x16x32_bf16 v[36:39], v[36:39], v[156:159], 0
	v_mfma_f32_16x16x32_bf16 v[164:167], v[40:43], v[136:139], v[164:167]
	v_mfma_f32_16x16x32_bf16 v[172:175], v[40:43], v[144:147], v[172:175]
	v_mfma_f32_16x16x32_bf16 v[180:183], v[40:43], v[152:155], v[180:183]
	v_mfma_f32_16x16x32_bf16 v[36:39], v[40:43], v[160:163], v[36:39]
	v_mfma_f32_16x16x32_bf16 v[40:43], v[44:47], v[156:159], 0
	v_mfma_f32_16x16x32_bf16 v[168:171], v[44:47], v[96:99], 0
	v_mfma_f32_16x16x32_bf16 v[176:179], v[44:47], v[140:143], 0
	v_mfma_f32_16x16x32_bf16 v[186:189], v[44:47], v[148:151], 0
	v_mfma_f32_16x16x32_bf16 v[40:43], v[48:51], v[160:163], v[40:43]
	v_mfma_f32_16x16x32_bf16 v[168:171], v[48:51], v[136:139], v[168:171]
	v_mfma_f32_16x16x32_bf16 v[176:179], v[48:51], v[144:147], v[176:179]
	v_mfma_f32_16x16x32_bf16 v[186:189], v[48:51], v[152:155], v[186:189]
	s_setprio 1
	s_setprio 0
	v_mfma_f32_16x16x32_bf16 v[44:47], v[52:55], v[96:99], 0
	v_mfma_f32_16x16x32_bf16 v[48:51], v[60:63], v[96:99], 0
	v_mfma_f32_16x16x32_bf16 v[44:47], v[56:59], v[136:139], v[44:47]
	v_mfma_f32_16x16x32_bf16 v[48:51], v[64:67], v[136:139], v[48:51]
	v_mfma_f32_16x16x32_bf16 v[96:99], v[52:55], v[140:143], 0
	v_mfma_f32_16x16x32_bf16 v[136:139], v[60:63], v[140:143], 0
	v_mfma_f32_16x16x32_bf16 v[140:143], v[52:55], v[148:151], 0
	v_mfma_f32_16x16x32_bf16 v[52:55], v[52:55], v[156:159], 0
	v_mfma_f32_16x16x32_bf16 v[96:99], v[56:59], v[144:147], v[96:99]
	v_mfma_f32_16x16x32_bf16 v[140:143], v[56:59], v[152:155], v[140:143]
	v_mfma_f32_16x16x32_bf16 v[52:55], v[56:59], v[160:163], v[52:55]
	v_mfma_f32_16x16x32_bf16 v[56:59], v[60:63], v[156:159], 0
	v_mfma_f32_16x16x32_bf16 v[136:139], v[64:67], v[144:147], v[136:139]
	v_mfma_f32_16x16x32_bf16 v[144:147], v[60:63], v[148:151], 0
	v_mfma_f32_16x16x32_bf16 v[56:59], v[64:67], v[160:163], v[56:59]
	v_mfma_f32_16x16x32_bf16 v[144:147], v[64:67], v[152:155], v[144:147]
	s_setprio 1
	s_barrier
	ds_read_b128 v[60:63], v212
	ds_read_b128 v[64:67], v212 offset:1024
	ds_read_b128 v[148:151], v212 offset:2048
	ds_read_b128 v[152:155], v212 offset:3072
	ds_read_b128 v[156:159], v218
	ds_read_b128 v[160:163], v218 offset:1024
	ds_read_b128 v[190:193], v218 offset:2048
	ds_read_b128 v[202:205], v218 offset:3072
	s_mov_b32 m0, s25
	v_lshl_add_u64 v[8:9], s[20:21], 0, v[4:5]
	ds_read_b128 v[214:217], v208 offset:32768
	ds_read_b128 v[224:227], v208 offset:33792
	ds_read_b128 v[228:231], v208 offset:34816
	ds_read_b128 v[232:235], v208 offset:35840
	ds_read_b128 v[236:239], v208 offset:36864
	ds_read_b128 v[240:243], v208 offset:37888
	ds_read_b128 v[244:247], v208 offset:38912
	ds_read_b128 v[248:251], v208 offset:39936
	global_load_lds_dwordx4 v[8:9], off
	v_lshl_add_u64 v[8:9], s[20:21], 0, v[16:17]
	s_mov_b32 m0, s26
	s_nop 0
	global_load_lds_dwordx4 v[8:9], off
	s_waitcnt vmcnt(8)
	s_waitcnt lgkmcnt(0)
	s_barrier
	s_setprio 0
	s_waitcnt lgkmcnt(0)
	v_mfma_f32_16x16x32_bf16 v[100:103], v[60:63], v[214:217], v[100:103]
	v_mfma_f32_16x16x32_bf16 v[104:107], v[148:151], v[214:217], v[104:107]
	v_mfma_f32_16x16x32_bf16 v[108:111], v[60:63], v[228:231], v[108:111]
	v_mfma_f32_16x16x32_bf16 v[112:115], v[148:151], v[228:231], v[112:115]
	v_mfma_f32_16x16x32_bf16 v[116:119], v[60:63], v[236:239], v[116:119]
	v_mfma_f32_16x16x32_bf16 v[120:123], v[148:151], v[236:239], v[120:123]
	v_mfma_f32_16x16x32_bf16 v[124:127], v[60:63], v[244:247], v[124:127]
	v_mfma_f32_16x16x32_bf16 v[128:131], v[148:151], v[244:247], v[128:131]
	v_mfma_f32_16x16x32_bf16 v[100:103], v[64:67], v[224:227], v[100:103]
	v_mfma_f32_16x16x32_bf16 v[104:107], v[152:155], v[224:227], v[104:107]
	v_mfma_f32_16x16x32_bf16 v[108:111], v[64:67], v[232:235], v[108:111]
	v_mfma_f32_16x16x32_bf16 v[112:115], v[152:155], v[232:235], v[112:115]
	v_mfma_f32_16x16x32_bf16 v[116:119], v[64:67], v[240:243], v[116:119]
	v_mfma_f32_16x16x32_bf16 v[120:123], v[152:155], v[240:243], v[120:123]
	v_mfma_f32_16x16x32_bf16 v[124:127], v[64:67], v[248:251], v[124:127]
	v_mfma_f32_16x16x32_bf16 v[128:131], v[152:155], v[248:251], v[128:131]
	s_setprio 1
	s_setprio 0
	v_mfma_f32_16x16x32_bf16 v[68:71], v[190:193], v[214:217], v[68:71]
	v_mfma_f32_16x16x32_bf16 v[72:75], v[156:159], v[228:231], v[72:75]
	v_mfma_f32_16x16x32_bf16 v[80:83], v[156:159], v[236:239], v[80:83]
	v_mfma_f32_16x16x32_bf16 v[84:87], v[190:193], v[236:239], v[84:87]
	v_mfma_f32_16x16x32_bf16 v[88:91], v[156:159], v[244:247], v[88:91]
	v_mfma_f32_16x16x32_bf16 v[92:95], v[190:193], v[244:247], v[92:95]
	v_mfma_f32_16x16x32_bf16 v[132:135], v[156:159], v[214:217], v[132:135]
	v_mfma_f32_16x16x32_bf16 v[68:71], v[202:205], v[224:227], v[68:71]
	v_mfma_f32_16x16x32_bf16 v[72:75], v[160:163], v[232:235], v[72:75]
	v_mfma_f32_16x16x32_bf16 v[76:79], v[190:193], v[228:231], v[76:79]
	v_mfma_f32_16x16x32_bf16 v[80:83], v[160:163], v[240:243], v[80:83]
	v_mfma_f32_16x16x32_bf16 v[84:87], v[202:205], v[240:243], v[84:87]
	v_mfma_f32_16x16x32_bf16 v[88:91], v[160:163], v[248:251], v[88:91]
	v_mfma_f32_16x16x32_bf16 v[92:95], v[202:205], v[248:251], v[92:95]
	v_mfma_f32_16x16x32_bf16 v[132:135], v[160:163], v[224:227], v[132:135]
	v_mfma_f32_16x16x32_bf16 v[76:79], v[202:205], v[232:235], v[76:79]
	s_setprio 1
	s_barrier
	s_mov_b64 s[8:9], 0x180
	s_mov_b32 m0, s28
	v_lshl_add_u64 v[8:9], v[2:3], 0, s[8:9]
	ds_read_b128 v[214:217], v208 offset:49152
	ds_read_b128 v[224:227], v208 offset:50176
	ds_read_b128 v[228:231], v208 offset:51200
	ds_read_b128 v[232:235], v208 offset:52224
	ds_read_b128 v[236:239], v208 offset:53248
	ds_read_b128 v[240:243], v208 offset:54272
	ds_read_b128 v[244:247], v208 offset:55296
	ds_read_b128 v[248:251], v208 offset:56320
	global_load_lds_dwordx4 v[8:9], off
	v_lshl_add_u64 v[8:9], v[6:7], 0, s[8:9]
	s_mov_b32 m0, s30
	s_nop 0
	global_load_lds_dwordx4 v[8:9], off
	v_lshl_add_u64 v[8:9], s[6:7], 0, v[0:1]
	s_mov_b32 m0, s36
	s_nop 0
	global_load_lds_dwordx4 v[8:9], off
	v_lshl_add_u64 v[8:9], s[6:7], 0, v[34:35]
	s_mov_b32 m0, s37
	s_nop 0
	global_load_lds_dwordx4 v[8:9], off
	v_lshl_add_u64 v[8:9], v[18:19], 0, s[8:9]
	s_mov_b32 m0, s29
	s_nop 0
	global_load_lds_dwordx4 v[8:9], off
	v_lshl_add_u64 v[8:9], v[28:29], 0, s[8:9]
	s_mov_b32 m0, s31
	s_nop 0
	global_load_lds_dwordx4 v[8:9], off
	s_waitcnt vmcnt(8)
	s_waitcnt lgkmcnt(0)
	s_barrier
	s_setprio 0
	s_waitcnt lgkmcnt(0)
	v_mfma_f32_16x16x32_bf16 v[34:37], v[60:63], v[244:247], v[36:39]
	v_mfma_f32_16x16x32_bf16 v[38:41], v[148:151], v[244:247], v[40:43]
	v_mfma_f32_16x16x32_bf16 v[164:167], v[60:63], v[214:217], v[164:167]
	v_mfma_f32_16x16x32_bf16 v[168:171], v[148:151], v[214:217], v[168:171]
	v_mfma_f32_16x16x32_bf16 v[172:175], v[60:63], v[228:231], v[172:175]
	v_mfma_f32_16x16x32_bf16 v[176:179], v[148:151], v[228:231], v[176:179]
	v_mfma_f32_16x16x32_bf16 v[180:183], v[60:63], v[236:239], v[180:183]
	v_mfma_f32_16x16x32_bf16 v[186:189], v[148:151], v[236:239], v[186:189]
	v_mfma_f32_16x16x32_bf16 v[34:37], v[64:67], v[248:251], v[34:37]
	v_mfma_f32_16x16x32_bf16 v[38:41], v[152:155], v[248:251], v[38:41]
	v_mfma_f32_16x16x32_bf16 v[164:167], v[64:67], v[224:227], v[164:167]
	v_mfma_f32_16x16x32_bf16 v[168:171], v[152:155], v[224:227], v[168:171]
	v_mfma_f32_16x16x32_bf16 v[172:175], v[64:67], v[232:235], v[172:175]
	v_mfma_f32_16x16x32_bf16 v[176:179], v[152:155], v[232:235], v[176:179]
	v_mfma_f32_16x16x32_bf16 v[180:183], v[64:67], v[240:243], v[180:183]
	v_mfma_f32_16x16x32_bf16 v[186:189], v[152:155], v[240:243], v[186:189]
	s_setprio 1
	s_setprio 0
	v_mfma_f32_16x16x32_bf16 v[42:45], v[156:159], v[214:217], v[44:47]
	v_mfma_f32_16x16x32_bf16 v[46:49], v[190:193], v[214:217], v[48:51]
	v_mfma_f32_16x16x32_bf16 v[60:63], v[156:159], v[228:231], v[96:99]
	v_mfma_f32_16x16x32_bf16 v[64:67], v[190:193], v[228:231], v[136:139]
	v_mfma_f32_16x16x32_bf16 v[96:99], v[156:159], v[236:239], v[140:143]
	v_mfma_f32_16x16x32_bf16 v[50:53], v[156:159], v[244:247], v[52:55]
	v_mfma_f32_16x16x32_bf16 v[54:57], v[190:193], v[244:247], v[56:59]
	v_mfma_f32_16x16x32_bf16 v[42:45], v[160:163], v[224:227], v[42:45]
	v_mfma_f32_16x16x32_bf16 v[46:49], v[202:205], v[224:227], v[46:49]
	v_mfma_f32_16x16x32_bf16 v[60:63], v[160:163], v[232:235], v[60:63]
	v_mfma_f32_16x16x32_bf16 v[64:67], v[202:205], v[232:235], v[64:67]
	v_mfma_f32_16x16x32_bf16 v[96:99], v[160:163], v[240:243], v[96:99]
	v_mfma_f32_16x16x32_bf16 v[136:139], v[190:193], v[236:239], v[144:147]
	v_mfma_f32_16x16x32_bf16 v[50:53], v[160:163], v[248:251], v[50:53]
	v_mfma_f32_16x16x32_bf16 v[54:57], v[202:205], v[248:251], v[54:57]
	v_mfma_f32_16x16x32_bf16 v[136:139], v[202:205], v[240:243], v[136:139]
	s_setprio 1
	s_barrier
	ds_read_b128 v[140:143], v11
	ds_read_b128 v[144:147], v11 offset:1024
	ds_read_b128 v[148:151], v11 offset:2048
	ds_read_b128 v[152:155], v11 offset:3072
	ds_read_b128 v[156:159], v184
	ds_read_b128 v[160:163], v184 offset:1024
	ds_read_b128 v[190:193], v184 offset:2048
	ds_read_b128 v[202:205], v184 offset:3072
	s_mov_b32 m0, s45
	v_lshl_add_u64 v[4:5], s[4:5], 0, v[4:5]
	ds_read_b128 v[214:217], v208
	ds_read_b128 v[224:227], v208 offset:1024
	ds_read_b128 v[228:231], v208 offset:2048
	ds_read_b128 v[232:235], v208 offset:3072
	ds_read_b128 v[236:239], v208 offset:4096
	ds_read_b128 v[240:243], v208 offset:5120
	ds_read_b128 v[244:247], v208 offset:6144
	ds_read_b128 v[248:251], v208 offset:7168
	global_load_lds_dwordx4 v[4:5], off
	v_lshl_add_u64 v[4:5], s[4:5], 0, v[16:17]
	s_mov_b32 m0, s44
	s_nop 0
	global_load_lds_dwordx4 v[4:5], off
	s_waitcnt vmcnt(8)
	s_waitcnt lgkmcnt(0)
	s_barrier
	s_setprio 0
	s_waitcnt lgkmcnt(0)
	v_mfma_f32_16x16x32_bf16 v[112:115], v[148:151], v[228:231], v[112:115]
	v_mfma_f32_16x16x32_bf16 v[194:197], v[152:155], v[232:235], v[112:115]
	v_mfma_f32_16x16x32_bf16 v[112:115], v[140:143], v[236:239], v[116:119]
	v_mfma_f32_16x16x32_bf16 v[118:121], v[148:151], v[236:239], v[120:123]
	v_mfma_f32_16x16x32_bf16 v[122:125], v[140:143], v[244:247], v[124:127]
	v_mfma_f32_16x16x32_bf16 v[100:103], v[140:143], v[214:217], v[100:103]
	v_mfma_f32_16x16x32_bf16 v[104:107], v[148:151], v[214:217], v[104:107]
	v_mfma_f32_16x16x32_bf16 v[108:111], v[140:143], v[228:231], v[108:111]
	v_mfma_f32_16x16x32_bf16 v[198:201], v[144:147], v[248:251], v[122:125]
	v_mfma_f32_16x16x32_bf16 v[122:125], v[148:151], v[244:247], v[128:131]
	v_mfma_f32_16x16x32_bf16 v[100:103], v[144:147], v[224:227], v[100:103]
	v_mfma_f32_16x16x32_bf16 v[104:107], v[152:155], v[224:227], v[104:107]
	v_mfma_f32_16x16x32_bf16 v[108:111], v[144:147], v[232:235], v[108:111]
	v_mfma_f32_16x16x32_bf16 v[114:117], v[144:147], v[240:243], v[112:115]
	v_mfma_f32_16x16x32_bf16 v[118:121], v[152:155], v[240:243], v[118:121]
	v_mfma_f32_16x16x32_bf16 v[8:11], v[152:155], v[248:251], v[122:125]
	s_setprio 1
	s_setprio 0
	v_mfma_f32_16x16x32_bf16 v[72:75], v[156:159], v[228:231], v[72:75]
	v_mfma_f32_16x16x32_bf16 v[122:125], v[156:159], v[214:217], v[132:135]
	v_mfma_f32_16x16x32_bf16 v[68:71], v[190:193], v[214:217], v[68:71]
	v_mfma_f32_16x16x32_bf16 v[214:217], v[160:163], v[232:235], v[72:75]
	v_mfma_f32_16x16x32_bf16 v[72:75], v[190:193], v[228:231], v[76:79]
	v_mfma_f32_16x16x32_bf16 v[130:133], v[160:163], v[224:227], v[122:125]
	v_mfma_f32_16x16x32_bf16 v[68:71], v[202:205], v[224:227], v[68:71]
	v_mfma_f32_16x16x32_bf16 v[224:227], v[202:205], v[232:235], v[72:75]
	v_mfma_f32_16x16x32_bf16 v[72:75], v[156:159], v[236:239], v[80:83]
	v_mfma_f32_16x16x32_bf16 v[228:231], v[160:163], v[240:243], v[72:75]
	v_mfma_f32_16x16x32_bf16 v[72:75], v[190:193], v[236:239], v[84:87]
	v_mfma_f32_16x16x32_bf16 v[82:85], v[202:205], v[240:243], v[72:75]
	v_mfma_f32_16x16x32_bf16 v[72:75], v[156:159], v[244:247], v[88:91]
	v_mfma_f32_16x16x32_bf16 v[232:235], v[160:163], v[248:251], v[72:75]
	v_mfma_f32_16x16x32_bf16 v[72:75], v[190:193], v[244:247], v[92:95]
	v_mfma_f32_16x16x32_bf16 v[236:239], v[202:205], v[248:251], v[72:75]
	s_setprio 1
	s_barrier
	s_mov_b32 m0, s40
	s_nop 3
	ds_read_b128 v[72:75], v208 offset:16384
	ds_read_b128 v[76:79], v208 offset:17408
	ds_read_b128 v[86:89], v208 offset:18432
	ds_read_b128 v[90:93], v208 offset:19456
	ds_read_b128 v[122:125], v208 offset:20480
	ds_read_b128 v[126:129], v208 offset:21504
	ds_read_b128 v[240:243], v208 offset:22528
	ds_read_b128 v[244:247], v208 offset:23552
	global_load_lds_dwordx4 v[2:3], off
	s_mov_b32 m0, s39
	s_nop 0
	global_load_lds_dwordx4 v[6:7], off
	s_mov_b32 m0, s42
	s_nop 0
	global_load_lds_dwordx4 v[12:13], off
	s_mov_b32 m0, s41
	s_nop 0
	global_load_lds_dwordx4 v[14:15], off
	s_mov_b32 m0, s3
	s_nop 0
	global_load_lds_dwordx4 v[18:19], off
	s_mov_b32 m0, s38
	s_nop 0
	global_load_lds_dwordx4 v[28:29], off
	s_waitcnt vmcnt(8)
	s_waitcnt lgkmcnt(0)
	s_barrier
	s_setprio 0
	s_waitcnt lgkmcnt(0)
	v_mfma_f32_16x16x32_bf16 v[2:5], v[140:143], v[72:75], v[164:167]
	v_mfma_f32_16x16x32_bf16 v[12:15], v[148:151], v[72:75], v[168:171]
	v_mfma_f32_16x16x32_bf16 v[16:19], v[140:143], v[86:89], v[172:175]
	v_mfma_f32_16x16x32_bf16 v[34:37], v[140:143], v[240:243], v[34:37]
	v_mfma_f32_16x16x32_bf16 v[38:41], v[148:151], v[240:243], v[38:41]
	v_mfma_f32_16x16x32_bf16 v[2:5], v[144:147], v[76:79], v[2:5]
	v_mfma_f32_16x16x32_bf16 v[12:15], v[152:155], v[76:79], v[12:15]
	v_mfma_f32_16x16x32_bf16 v[16:19], v[144:147], v[90:93], v[16:19]
	v_mfma_f32_16x16x32_bf16 v[164:167], v[148:151], v[86:89], v[176:179]
	v_mfma_f32_16x16x32_bf16 v[168:171], v[140:143], v[122:125], v[180:183]
	v_mfma_f32_16x16x32_bf16 v[172:175], v[148:151], v[122:125], v[186:189]
	v_mfma_f32_16x16x32_bf16 v[34:37], v[144:147], v[244:247], v[34:37]
	v_mfma_f32_16x16x32_bf16 v[38:41], v[152:155], v[244:247], v[38:41]
	v_mfma_f32_16x16x32_bf16 v[164:167], v[152:155], v[90:93], v[164:167]
	v_mfma_f32_16x16x32_bf16 v[168:171], v[144:147], v[126:129], v[168:171]
	v_mfma_f32_16x16x32_bf16 v[172:175], v[152:155], v[126:129], v[172:175]
	s_setprio 1
	s_setprio 0
	v_mfma_f32_16x16x32_bf16 v[42:45], v[156:159], v[72:75], v[42:45]
	v_mfma_f32_16x16x32_bf16 v[140:143], v[160:163], v[76:79], v[42:45]
	v_mfma_f32_16x16x32_bf16 v[42:45], v[190:193], v[72:75], v[46:49]
	v_mfma_f32_16x16x32_bf16 v[144:147], v[202:205], v[76:79], v[42:45]
	v_mfma_f32_16x16x32_bf16 v[42:45], v[156:159], v[86:89], v[60:63]
	v_mfma_f32_16x16x32_bf16 v[148:151], v[160:163], v[90:93], v[42:45]
	v_mfma_f32_16x16x32_bf16 v[42:45], v[190:193], v[86:89], v[64:67]
	v_mfma_f32_16x16x32_bf16 v[152:155], v[202:205], v[90:93], v[42:45]
	v_mfma_f32_16x16x32_bf16 v[42:45], v[156:159], v[122:125], v[96:99]
	v_mfma_f32_16x16x32_bf16 v[176:179], v[160:163], v[126:129], v[42:45]
	v_mfma_f32_16x16x32_bf16 v[42:45], v[190:193], v[122:125], v[136:139]
	v_mfma_f32_16x16x32_bf16 v[134:137], v[202:205], v[126:129], v[42:45]
	v_mfma_f32_16x16x32_bf16 v[42:45], v[156:159], v[240:243], v[50:53]
	v_mfma_f32_16x16x32_bf16 v[156:159], v[160:163], v[244:247], v[42:45]
	v_mfma_f32_16x16x32_bf16 v[42:45], v[190:193], v[240:243], v[54:57]
	v_mfma_f32_16x16x32_bf16 v[160:163], v[202:205], v[244:247], v[42:45]
	s_setprio 1
	s_barrier
	ds_read_b128 v[50:53], v212
	ds_read_b128 v[54:57], v212 offset:1024
	ds_read_b128 v[180:183], v212 offset:2048
	ds_read_b128 v[186:189], v212 offset:3072
	ds_read_b128 v[190:193], v218
	ds_read_b128 v[202:205], v218 offset:1024
	ds_read_b128 v[240:243], v218 offset:2048
	ds_read_b128 v[244:247], v218 offset:3072
	s_mov_b32 m0, s25
	ds_read_b128 v[42:45], v208 offset:32768
	ds_read_b128 v[46:49], v208 offset:33792
	ds_read_b128 v[58:61], v208 offset:34816
	ds_read_b128 v[62:65], v208 offset:35840
	ds_read_b128 v[248:251], v208 offset:36864
	ds_read_b128 v[72:75], v208 offset:37888
	ds_read_b128 v[76:79], v208 offset:38912
	ds_read_b128 v[86:89], v208 offset:39936
	global_load_lds_dwordx4 v[206:207], off
	s_mov_b32 m0, s26
	s_nop 0
	global_load_lds_dwordx4 v[210:211], off
	s_waitcnt vmcnt(8)
	s_waitcnt lgkmcnt(0)
	s_barrier
	s_setprio 0
	s_waitcnt lgkmcnt(0)
	v_mfma_f32_16x16x32_bf16 v[90:93], v[50:53], v[42:45], v[100:103]
	v_mfma_f32_16x16x32_bf16 v[126:129], v[54:57], v[46:49], v[90:93]
	v_mfma_f32_16x16x32_bf16 v[90:93], v[180:183], v[42:45], v[104:107]
	v_mfma_f32_16x16x32_bf16 v[122:125], v[186:189], v[46:49], v[90:93]
	v_mfma_f32_16x16x32_bf16 v[90:93], v[50:53], v[58:61], v[108:111]
	v_mfma_f32_16x16x32_bf16 v[110:113], v[54:57], v[62:65], v[90:93]
	v_mfma_f32_16x16x32_bf16 v[90:93], v[180:183], v[58:61], v[194:197]
	v_mfma_f32_16x16x32_bf16 v[106:109], v[186:189], v[62:65], v[90:93]
	v_mfma_f32_16x16x32_bf16 v[90:93], v[50:53], v[248:251], v[114:117]
	v_mfma_f32_16x16x32_bf16 v[94:97], v[54:57], v[72:75], v[90:93]
	v_mfma_f32_16x16x32_bf16 v[90:93], v[180:183], v[248:251], v[118:121]
	v_mfma_f32_16x16x32_bf16 v[98:101], v[50:53], v[76:79], v[198:201]
	v_mfma_f32_16x16x32_bf16 v[6:9], v[180:183], v[76:79], v[8:11]
	v_mfma_f32_16x16x32_bf16 v[90:93], v[186:189], v[72:75], v[90:93]
	v_mfma_f32_16x16x32_bf16 v[198:201], v[54:57], v[86:89], v[98:101]
	v_mfma_f32_16x16x32_bf16 v[194:197], v[186:189], v[86:89], v[6:9]
	s_setprio 1
	s_setprio 0
	v_mfma_f32_16x16x32_bf16 v[6:9], v[190:193], v[42:45], v[130:133]
	v_mfma_f32_16x16x32_bf16 v[118:121], v[202:205], v[46:49], v[6:9]
	v_mfma_f32_16x16x32_bf16 v[6:9], v[240:243], v[42:45], v[68:71]
	v_mfma_f32_16x16x32_bf16 v[114:117], v[244:247], v[46:49], v[6:9]
	v_mfma_f32_16x16x32_bf16 v[6:9], v[190:193], v[58:61], v[214:217]
	v_mfma_f32_16x16x32_bf16 v[102:105], v[202:205], v[62:65], v[6:9]
	v_mfma_f32_16x16x32_bf16 v[6:9], v[240:243], v[58:61], v[224:227]
	v_mfma_f32_16x16x32_bf16 v[98:101], v[244:247], v[62:65], v[6:9]
	v_mfma_f32_16x16x32_bf16 v[6:9], v[190:193], v[248:251], v[228:231]
	v_mfma_f32_16x16x32_bf16 v[214:217], v[202:205], v[72:75], v[6:9]
	v_mfma_f32_16x16x32_bf16 v[6:9], v[240:243], v[248:251], v[82:85]
	v_mfma_f32_16x16x32_bf16 v[82:85], v[244:247], v[72:75], v[6:9]
	v_mfma_f32_16x16x32_bf16 v[6:9], v[190:193], v[76:79], v[232:235]
	v_mfma_f32_16x16x32_bf16 v[70:73], v[202:205], v[86:89], v[6:9]
	v_mfma_f32_16x16x32_bf16 v[6:9], v[240:243], v[76:79], v[236:239]
	v_mfma_f32_16x16x32_bf16 v[66:69], v[244:247], v[86:89], v[6:9]
	s_setprio 1
	s_barrier
	s_mov_b32 m0, s28
	s_nop 3
	ds_read_b128 v[6:9], v208 offset:49152
	ds_read_b128 v[74:77], v208 offset:50176
	ds_read_b128 v[78:81], v208 offset:51200
	ds_read_b128 v[86:89], v208 offset:52224
	ds_read_b128 v[130:133], v208 offset:53248
	ds_read_b128 v[224:227], v208 offset:54272
	ds_read_b128 v[228:231], v208 offset:55296
	ds_read_b128 v[232:235], v208 offset:56320
	global_load_lds_dwordx4 v[22:23], off
	s_mov_b32 m0, s30
	s_nop 0
	global_load_lds_dwordx4 v[24:25], off
	s_mov_b32 m0, s36
	s_nop 0
	global_load_lds_dwordx4 v[30:31], off
	s_mov_b32 m0, s37
	s_nop 0
	global_load_lds_dwordx4 v[32:33], off
	s_mov_b32 m0, s29
	s_nop 0
	global_load_lds_dwordx4 v[20:21], off
	s_mov_b32 m0, s31
	s_nop 0
	global_load_lds_dwordx4 v[26:27], off
	s_waitcnt vmcnt(8)
	s_waitcnt lgkmcnt(0)
	s_barrier
	s_setprio 0
	s_waitcnt lgkmcnt(0)
	v_mfma_f32_16x16x32_bf16 v[2:5], v[50:53], v[6:9], v[2:5]
	v_mfma_f32_16x16x32_bf16 v[62:65], v[54:57], v[74:77], v[2:5]
	v_mfma_f32_16x16x32_bf16 v[2:5], v[180:183], v[6:9], v[12:15]
	v_mfma_f32_16x16x32_bf16 v[58:61], v[186:189], v[74:77], v[2:5]
	v_mfma_f32_16x16x32_bf16 v[2:5], v[50:53], v[78:81], v[16:19]
	v_mfma_f32_16x16x32_bf16 v[46:49], v[54:57], v[86:89], v[2:5]
	v_mfma_f32_16x16x32_bf16 v[2:5], v[180:183], v[78:81], v[164:167]
	v_mfma_f32_16x16x32_bf16 v[42:45], v[186:189], v[86:89], v[2:5]
	v_mfma_f32_16x16x32_bf16 v[2:5], v[50:53], v[130:133], v[168:171]
	v_mfma_f32_16x16x32_bf16 v[30:33], v[54:57], v[224:227], v[2:5]
	v_mfma_f32_16x16x32_bf16 v[2:5], v[180:183], v[130:133], v[172:175]
	v_mfma_f32_16x16x32_bf16 v[26:29], v[186:189], v[224:227], v[2:5]
	v_mfma_f32_16x16x32_bf16 v[2:5], v[50:53], v[228:231], v[34:37]
	v_mfma_f32_16x16x32_bf16 v[14:17], v[54:57], v[232:235], v[2:5]
	v_mfma_f32_16x16x32_bf16 v[2:5], v[180:183], v[228:231], v[38:41]
	v_mfma_f32_16x16x32_bf16 v[10:13], v[186:189], v[232:235], v[2:5]
	s_setprio 1
	s_setprio 0
	v_mfma_f32_16x16x32_bf16 v[2:5], v[190:193], v[6:9], v[140:143]
	v_mfma_f32_16x16x32_bf16 v[54:57], v[202:205], v[74:77], v[2:5]
	v_mfma_f32_16x16x32_bf16 v[2:5], v[240:243], v[6:9], v[144:147]
	v_mfma_f32_16x16x32_bf16 v[50:53], v[244:247], v[74:77], v[2:5]
	v_mfma_f32_16x16x32_bf16 v[2:5], v[190:193], v[78:81], v[148:151]
	v_mfma_f32_16x16x32_bf16 v[38:41], v[202:205], v[86:89], v[2:5]
	v_mfma_f32_16x16x32_bf16 v[2:5], v[240:243], v[78:81], v[152:155]
	v_mfma_f32_16x16x32_bf16 v[34:37], v[244:247], v[86:89], v[2:5]
	v_mfma_f32_16x16x32_bf16 v[2:5], v[190:193], v[130:133], v[176:179]
	v_mfma_f32_16x16x32_bf16 v[22:25], v[202:205], v[224:227], v[2:5]
	v_mfma_f32_16x16x32_bf16 v[2:5], v[240:243], v[130:133], v[134:137]
	v_mfma_f32_16x16x32_bf16 v[18:21], v[244:247], v[224:227], v[2:5]
	v_mfma_f32_16x16x32_bf16 v[2:5], v[190:193], v[228:231], v[156:159]
	v_mfma_f32_16x16x32_bf16 v[6:9], v[202:205], v[232:235], v[2:5]
	v_mfma_f32_16x16x32_bf16 v[2:5], v[240:243], v[228:231], v[160:163]
	v_mfma_f32_16x16x32_bf16 v[2:5], v[244:247], v[232:235], v[2:5]
	s_setprio 1
	s_barrier
	s_cbranch_scc1 .LBB0_1215
	s_barrier

.Lp3r_j0:
	s_waitcnt lgkmcnt(0)
	s_barrier
	s_setprio 0
	s_waitcnt lgkmcnt(0)
	v_mfma_f32_16x16x32_bf16 v[126:129], v[144:147], v[176:179], v[126:129]
	v_mfma_f32_16x16x32_bf16 v[118:121], v[152:155], v[176:179], v[118:121]
	v_mfma_f32_16x16x32_bf16 v[110:113], v[144:147], v[184:187], v[110:113]
	v_mfma_f32_16x16x32_bf16 v[102:105], v[152:155], v[184:187], v[102:105]
	v_mfma_f32_16x16x32_bf16 v[94:97], v[144:147], v[192:195], v[94:97]
	v_mfma_f32_16x16x32_bf16 v[86:89], v[152:155], v[192:195], v[86:89]
	v_mfma_f32_16x16x32_bf16 v[78:81], v[144:147], v[200:203], v[78:81]
	v_mfma_f32_16x16x32_bf16 v[70:73], v[152:155], v[200:203], v[70:73]
	v_mfma_f32_16x16x32_bf16 v[126:129], v[148:151], v[180:183], v[126:129]
	v_mfma_f32_16x16x32_bf16 v[118:121], v[156:159], v[180:183], v[118:121]
	v_mfma_f32_16x16x32_bf16 v[110:113], v[148:151], v[188:191], v[110:113]
	v_mfma_f32_16x16x32_bf16 v[102:105], v[156:159], v[188:191], v[102:105]
	v_mfma_f32_16x16x32_bf16 v[94:97], v[148:151], v[196:199], v[94:97]
	v_mfma_f32_16x16x32_bf16 v[86:89], v[156:159], v[196:199], v[86:89]
	v_mfma_f32_16x16x32_bf16 v[78:81], v[148:151], v[204:207], v[78:81]
	v_mfma_f32_16x16x32_bf16 v[70:73], v[156:159], v[204:207], v[70:73]
	s_setprio 1
	s_setprio 0
	v_mfma_f32_16x16x32_bf16 v[122:125], v[160:163], v[176:179], v[122:125]
	v_mfma_f32_16x16x32_bf16 v[114:117], v[168:171], v[176:179], v[114:117]
	v_mfma_f32_16x16x32_bf16 v[106:109], v[160:163], v[184:187], v[106:109]
	v_mfma_f32_16x16x32_bf16 v[98:101], v[168:171], v[184:187], v[98:101]
	v_mfma_f32_16x16x32_bf16 v[90:93], v[160:163], v[192:195], v[90:93]
	v_mfma_f32_16x16x32_bf16 v[82:85], v[168:171], v[192:195], v[82:85]
	v_mfma_f32_16x16x32_bf16 v[74:77], v[160:163], v[200:203], v[74:77]
	v_mfma_f32_16x16x32_bf16 v[66:69], v[168:171], v[200:203], v[66:69]
	v_mfma_f32_16x16x32_bf16 v[122:125], v[164:167], v[180:183], v[122:125]
	v_mfma_f32_16x16x32_bf16 v[114:117], v[172:175], v[180:183], v[114:117]
	v_mfma_f32_16x16x32_bf16 v[106:109], v[164:167], v[188:191], v[106:109]
	v_mfma_f32_16x16x32_bf16 v[98:101], v[172:175], v[188:191], v[98:101]
	v_mfma_f32_16x16x32_bf16 v[90:93], v[164:167], v[196:199], v[90:93]
	v_mfma_f32_16x16x32_bf16 v[82:85], v[172:175], v[196:199], v[82:85]
	v_mfma_f32_16x16x32_bf16 v[74:77], v[164:167], v[204:207], v[74:77]
	v_mfma_f32_16x16x32_bf16 v[66:69], v[172:175], v[204:207], v[66:69]
	s_setprio 1
	s_barrier
	s_add_i32 s52, s52, s39
	v_lshl_add_u64 v[210:211], s[28:29], 0, v[0:1]
	s_mov_b32 m0, s52
	ds_read_b128 v[176:179], v143 offset:16384
	ds_read_b128 v[180:183], v143 offset:17408
	ds_read_b128 v[184:187], v143 offset:18432
	ds_read_b128 v[188:191], v143 offset:19456
	ds_read_b128 v[192:195], v143 offset:20480
	ds_read_b128 v[196:199], v143 offset:21504
	ds_read_b128 v[200:203], v143 offset:22528
	ds_read_b128 v[204:207], v143 offset:23552
	global_load_lds_dwordx4 v[210:211], off
	s_add_i32 m0, s52, 0x2000
	s_add_u32 s52, s28, 0x40000
	v_lshl_add_u64 v[214:215], s[28:29], 0, v[130:131]
	s_addc_u32 s53, s29, 0
	s_add_i32 s54, s54, s39
	global_load_lds_dwordx4 v[214:215], off
	v_lshl_add_u64 v[216:217], s[52:53], 0, v[0:1]
	s_mov_b32 m0, s54
	v_lshl_add_u64 v[224:225], s[30:31], 0, v[132:133]
	global_load_lds_dwordx4 v[216:217], off
	v_lshl_add_u64 v[216:217], s[52:53], 0, v[130:131]
	s_add_i32 m0, s54, 0x2000
	s_nop 0
	global_load_lds_dwordx4 v[216:217], off
	v_lshl_add_u64 v[216:217], s[30:31], 0, v[134:135]
	s_mov_b32 m0, s25
	s_nop 0
	global_load_lds_dwordx4 v[216:217], off
	s_mov_b32 m0, s40
	s_nop 0
	global_load_lds_dwordx4 v[224:225], off
	s_cmp_lg_u32 s51, 12
	s_cbranch_scc1 .Lp3r_nlA
	s_lshl_b32 s54, s22, 8
	s_add_i32 s54, s54, s43
	v_and_b32_e32 v228, 15, v212
	v_lshrrev_b32_e32 v229, 4, v212
	v_or_b32_e32 v228, s54, v228
	v_lshlrev_b32_e32 v228, 6, v228
	v_lshl_add_u32 v230, v229, 4, v228
	v_mov_b32_e32 v231, 0
	v_lshl_add_u64 v[250:251], s[4:5], 0, v[230:231]
	v_mov_b32_e32 v230, 0x2000
	v_lshl_add_u64 v[248:249], v[250:251], 0, v[230:231]
	global_load_dwordx4 v[228:231], v[250:251], off
	global_load_dwordx4 v[232:235], v[250:251], off offset:1024
	global_load_dwordx4 v[236:239], v[250:251], off offset:2048
	global_load_dwordx4 v[240:243], v[250:251], off offset:3072
	global_load_dwordx4 v[244:247], v[248:249], off
	s_nop 0
	global_load_dwordx4 v[248:251], v[248:249], off offset:1024
	s_waitcnt vmcnt(14)
	s_branch .Lp3r_jA

.Lp3r_jA:
	s_waitcnt lgkmcnt(0)
	s_barrier
	s_setprio 0
	s_waitcnt lgkmcnt(0)
	v_mfma_f32_16x16x32_bf16 v[62:65], v[144:147], v[176:179], v[62:65]
	v_mfma_f32_16x16x32_bf16 v[54:57], v[152:155], v[176:179], v[54:57]
	v_mfma_f32_16x16x32_bf16 v[46:49], v[144:147], v[184:187], v[46:49]
	v_mfma_f32_16x16x32_bf16 v[38:41], v[152:155], v[184:187], v[38:41]
	v_mfma_f32_16x16x32_bf16 v[30:33], v[144:147], v[192:195], v[30:33]
	v_mfma_f32_16x16x32_bf16 v[22:25], v[152:155], v[192:195], v[22:25]
	v_mfma_f32_16x16x32_bf16 v[14:17], v[144:147], v[200:203], v[14:17]
	v_mfma_f32_16x16x32_bf16 v[6:9], v[152:155], v[200:203], v[6:9]
	v_mfma_f32_16x16x32_bf16 v[62:65], v[148:151], v[180:183], v[62:65]
	v_mfma_f32_16x16x32_bf16 v[54:57], v[156:159], v[180:183], v[54:57]
	v_mfma_f32_16x16x32_bf16 v[46:49], v[148:151], v[188:191], v[46:49]
	v_mfma_f32_16x16x32_bf16 v[38:41], v[156:159], v[188:191], v[38:41]
	v_mfma_f32_16x16x32_bf16 v[30:33], v[148:151], v[196:199], v[30:33]
	v_mfma_f32_16x16x32_bf16 v[22:25], v[156:159], v[196:199], v[22:25]
	v_mfma_f32_16x16x32_bf16 v[14:17], v[148:151], v[204:207], v[14:17]
	v_mfma_f32_16x16x32_bf16 v[6:9], v[156:159], v[204:207], v[6:9]
	s_setprio 1
	s_setprio 0
	v_mfma_f32_16x16x32_bf16 v[58:61], v[160:163], v[176:179], v[58:61]
	v_mfma_f32_16x16x32_bf16 v[50:53], v[168:171], v[176:179], v[50:53]
	v_mfma_f32_16x16x32_bf16 v[42:45], v[160:163], v[184:187], v[42:45]
	v_mfma_f32_16x16x32_bf16 v[34:37], v[168:171], v[184:187], v[34:37]
	v_mfma_f32_16x16x32_bf16 v[26:29], v[160:163], v[192:195], v[26:29]
	v_mfma_f32_16x16x32_bf16 v[18:21], v[168:171], v[192:195], v[18:21]
	v_mfma_f32_16x16x32_bf16 v[10:13], v[160:163], v[200:203], v[10:13]
	v_mfma_f32_16x16x32_bf16 v[2:5], v[168:171], v[200:203], v[2:5]
	v_mfma_f32_16x16x32_bf16 v[58:61], v[164:167], v[180:183], v[58:61]
	v_mfma_f32_16x16x32_bf16 v[50:53], v[172:175], v[180:183], v[50:53]
	v_mfma_f32_16x16x32_bf16 v[42:45], v[164:167], v[188:191], v[42:45]
	v_mfma_f32_16x16x32_bf16 v[34:37], v[172:175], v[188:191], v[34:37]
	v_mfma_f32_16x16x32_bf16 v[26:29], v[164:167], v[196:199], v[26:29]
	v_mfma_f32_16x16x32_bf16 v[18:21], v[172:175], v[196:199], v[18:21]
	v_mfma_f32_16x16x32_bf16 v[10:13], v[164:167], v[204:207], v[10:13]
	v_mfma_f32_16x16x32_bf16 v[2:5], v[172:175], v[204:207], v[2:5]
	s_setprio 1
	s_barrier
	s_add_i32 s52, 0, 0x18000
	v_add_u32_e32 v140, s52, v141
	s_add_i32 s53, 0, 0x1c000
	ds_read_b128 v[144:147], v140
	ds_read_b128 v[148:151], v140 offset:1024
	ds_read_b128 v[152:155], v140 offset:2048
	ds_read_b128 v[156:159], v140 offset:3072
	v_add_u32_e32 v140, s53, v141
	ds_read_b128 v[160:163], v140
	ds_read_b128 v[164:167], v140 offset:1024
	ds_read_b128 v[168:171], v140 offset:2048
	ds_read_b128 v[172:175], v140 offset:3072
	s_add_u32 s30, s30, 0x40000
	s_addc_u32 s31, s31, 0
	s_mov_b32 m0, s41
	v_lshl_add_u64 v[226:227], s[30:31], 0, v[134:135]
	ds_read_b128 v[176:179], v143 offset:32768
	ds_read_b128 v[180:183], v143 offset:33792
	ds_read_b128 v[184:187], v143 offset:34816
	ds_read_b128 v[188:191], v143 offset:35840
	ds_read_b128 v[192:195], v143 offset:36864
	ds_read_b128 v[196:199], v143 offset:37888
	ds_read_b128 v[200:203], v143 offset:38912
	ds_read_b128 v[204:207], v143 offset:39936
	global_load_lds_dwordx4 v[226:227], off
	v_lshl_add_u64 v[226:227], s[30:31], 0, v[132:133]
	s_mov_b32 m0, s42
	s_nop 0
	global_load_lds_dwordx4 v[226:227], off
	s_cmp_lg_u32 s51, 12
	s_cbranch_scc1 .Lp3r_nlB
	s_waitcnt vmcnt(14)
	s_branch .Lp3r_jB

.Lp3r_jB:
	s_waitcnt lgkmcnt(0)
	s_barrier
	s_setprio 0
	s_waitcnt lgkmcnt(0)
	v_mfma_f32_16x16x32_bf16 v[126:129], v[144:147], v[176:179], v[126:129]
	v_mfma_f32_16x16x32_bf16 v[118:121], v[152:155], v[176:179], v[118:121]
	v_mfma_f32_16x16x32_bf16 v[110:113], v[144:147], v[184:187], v[110:113]
	v_mfma_f32_16x16x32_bf16 v[102:105], v[152:155], v[184:187], v[102:105]
	v_mfma_f32_16x16x32_bf16 v[94:97], v[144:147], v[192:195], v[94:97]
	v_mfma_f32_16x16x32_bf16 v[86:89], v[152:155], v[192:195], v[86:89]
	v_mfma_f32_16x16x32_bf16 v[78:81], v[144:147], v[200:203], v[78:81]
	v_mfma_f32_16x16x32_bf16 v[70:73], v[152:155], v[200:203], v[70:73]
	v_mfma_f32_16x16x32_bf16 v[126:129], v[148:151], v[180:183], v[126:129]
	v_mfma_f32_16x16x32_bf16 v[118:121], v[156:159], v[180:183], v[118:121]
	v_mfma_f32_16x16x32_bf16 v[110:113], v[148:151], v[188:191], v[110:113]
	v_mfma_f32_16x16x32_bf16 v[102:105], v[156:159], v[188:191], v[102:105]
	v_mfma_f32_16x16x32_bf16 v[94:97], v[148:151], v[196:199], v[94:97]
	v_mfma_f32_16x16x32_bf16 v[86:89], v[156:159], v[196:199], v[86:89]
	v_mfma_f32_16x16x32_bf16 v[78:81], v[148:151], v[204:207], v[78:81]
	v_mfma_f32_16x16x32_bf16 v[70:73], v[156:159], v[204:207], v[70:73]
	s_setprio 1
	s_setprio 0
	v_mfma_f32_16x16x32_bf16 v[122:125], v[160:163], v[176:179], v[122:125]
	v_mfma_f32_16x16x32_bf16 v[114:117], v[168:171], v[176:179], v[114:117]
	v_mfma_f32_16x16x32_bf16 v[106:109], v[160:163], v[184:187], v[106:109]
	v_mfma_f32_16x16x32_bf16 v[98:101], v[168:171], v[184:187], v[98:101]
	v_mfma_f32_16x16x32_bf16 v[90:93], v[160:163], v[192:195], v[90:93]
	v_mfma_f32_16x16x32_bf16 v[82:85], v[168:171], v[192:195], v[82:85]
	v_mfma_f32_16x16x32_bf16 v[74:77], v[160:163], v[200:203], v[74:77]
	v_mfma_f32_16x16x32_bf16 v[66:69], v[168:171], v[200:203], v[66:69]
	v_mfma_f32_16x16x32_bf16 v[122:125], v[164:167], v[180:183], v[122:125]
	v_mfma_f32_16x16x32_bf16 v[114:117], v[172:175], v[180:183], v[114:117]
	v_mfma_f32_16x16x32_bf16 v[106:109], v[164:167], v[188:191], v[106:109]
	v_mfma_f32_16x16x32_bf16 v[98:101], v[172:175], v[188:191], v[98:101]
	v_mfma_f32_16x16x32_bf16 v[90:93], v[164:167], v[196:199], v[90:93]
	v_mfma_f32_16x16x32_bf16 v[82:85], v[172:175], v[196:199], v[82:85]
	v_mfma_f32_16x16x32_bf16 v[74:77], v[164:167], v[204:207], v[74:77]
	v_mfma_f32_16x16x32_bf16 v[66:69], v[172:175], v[204:207], v[66:69]
	s_setprio 1
	s_barrier
	s_add_i32 s30, s52, s39
	v_lshl_add_u64 v[210:211], v[210:211], 0, s[94:95]
	s_mov_b32 m0, s30
	ds_read_b128 v[176:179], v143 offset:49152
	ds_read_b128 v[180:183], v143 offset:50176
	ds_read_b128 v[184:187], v143 offset:51200
	ds_read_b128 v[188:191], v143 offset:52224
	ds_read_b128 v[192:195], v143 offset:53248
	ds_read_b128 v[196:199], v143 offset:54272
	ds_read_b128 v[200:203], v143 offset:55296
	ds_read_b128 v[204:207], v143 offset:56320
	global_load_lds_dwordx4 v[210:211], off
	s_add_i32 m0, s30, 0x2000
	s_add_u32 s28, s28, 0x40080
	v_lshl_add_u64 v[210:211], v[214:215], 0, s[94:95]
	s_addc_u32 s29, s29, 0
	s_add_i32 s30, s53, s39
	global_load_lds_dwordx4 v[210:211], off
	v_lshl_add_u64 v[210:211], s[28:29], 0, v[0:1]
	s_mov_b32 m0, s30
	s_nop 0
	global_load_lds_dwordx4 v[210:211], off
	v_lshl_add_u64 v[210:211], s[28:29], 0, v[130:131]
	s_add_i32 m0, s30, 0x2000
	s_nop 0
	global_load_lds_dwordx4 v[210:211], off
	v_lshl_add_u64 v[210:211], v[216:217], 0, s[94:95]
	s_mov_b32 m0, s45
	s_nop 0
	global_load_lds_dwordx4 v[210:211], off
	v_lshl_add_u64 v[210:211], v[224:225], 0, s[94:95]
	s_mov_b32 m0, s46
	s_nop 0
	global_load_lds_dwordx4 v[210:211], off
	s_cmp_lg_u32 s51, 12
	s_cbranch_scc1 .Lp3r_nlC
	s_lshl_b32 s54, s22, 8
	s_add_i32 s54, s54, s43
	v_and_b32_e32 v214, 15, v212
	v_lshrrev_b32_e32 v215, 4, v212
	v_or_b32_e32 v214, s54, v214
	v_lshlrev_b32_e32 v214, 6, v214
	v_lshl_add_u32 v214, v215, 4, v214
	v_add_u32_e32 v214, 0x2800, v214
	v_mov_b32_e32 v215, 0
	v_lshl_add_u64 v[210:211], s[4:5], 0, v[214:215]
	global_load_dwordx4 v[214:217], v[210:211], off
	global_load_dwordx4 v[224:227], v[210:211], off offset:1024
	s_waitcnt vmcnt(16)
	s_branch .Lp3r_jC

.Lp3r_jC:
	s_waitcnt lgkmcnt(0)
	s_barrier
	s_setprio 0
	s_waitcnt lgkmcnt(0)
	v_mfma_f32_16x16x32_bf16 v[62:65], v[144:147], v[176:179], v[62:65]
	v_mfma_f32_16x16x32_bf16 v[54:57], v[152:155], v[176:179], v[54:57]
	v_mfma_f32_16x16x32_bf16 v[46:49], v[144:147], v[184:187], v[46:49]
	v_mfma_f32_16x16x32_bf16 v[38:41], v[152:155], v[184:187], v[38:41]
	v_mfma_f32_16x16x32_bf16 v[30:33], v[144:147], v[192:195], v[30:33]
	v_mfma_f32_16x16x32_bf16 v[22:25], v[152:155], v[192:195], v[22:25]
	v_mfma_f32_16x16x32_bf16 v[14:17], v[144:147], v[200:203], v[14:17]
	v_mfma_f32_16x16x32_bf16 v[6:9], v[152:155], v[200:203], v[6:9]
	v_mfma_f32_16x16x32_bf16 v[62:65], v[148:151], v[180:183], v[62:65]
	v_mfma_f32_16x16x32_bf16 v[54:57], v[156:159], v[180:183], v[54:57]
	v_mfma_f32_16x16x32_bf16 v[46:49], v[148:151], v[188:191], v[46:49]
	v_mfma_f32_16x16x32_bf16 v[38:41], v[156:159], v[188:191], v[38:41]
	v_mfma_f32_16x16x32_bf16 v[30:33], v[148:151], v[196:199], v[30:33]
	v_mfma_f32_16x16x32_bf16 v[22:25], v[156:159], v[196:199], v[22:25]
	v_mfma_f32_16x16x32_bf16 v[14:17], v[148:151], v[204:207], v[14:17]
	v_mfma_f32_16x16x32_bf16 v[6:9], v[156:159], v[204:207], v[6:9]
	s_setprio 1
	s_setprio 0
	v_mfma_f32_16x16x32_bf16 v[58:61], v[160:163], v[176:179], v[58:61]
	v_mfma_f32_16x16x32_bf16 v[50:53], v[168:171], v[176:179], v[50:53]
	v_mfma_f32_16x16x32_bf16 v[42:45], v[160:163], v[184:187], v[42:45]
	v_mfma_f32_16x16x32_bf16 v[34:37], v[168:171], v[184:187], v[34:37]
	v_mfma_f32_16x16x32_bf16 v[26:29], v[160:163], v[192:195], v[26:29]
	v_mfma_f32_16x16x32_bf16 v[18:21], v[168:171], v[192:195], v[18:21]
	v_mfma_f32_16x16x32_bf16 v[10:13], v[160:163], v[200:203], v[10:13]
	v_mfma_f32_16x16x32_bf16 v[2:5], v[168:171], v[200:203], v[2:5]
	v_mfma_f32_16x16x32_bf16 v[58:61], v[164:167], v[180:183], v[58:61]
	v_mfma_f32_16x16x32_bf16 v[50:53], v[172:175], v[180:183], v[50:53]
	v_mfma_f32_16x16x32_bf16 v[42:45], v[164:167], v[188:191], v[42:45]
	v_mfma_f32_16x16x32_bf16 v[34:37], v[172:175], v[188:191], v[34:37]
	v_mfma_f32_16x16x32_bf16 v[26:29], v[164:167], v[196:199], v[26:29]
	v_mfma_f32_16x16x32_bf16 v[18:21], v[172:175], v[196:199], v[18:21]
	v_mfma_f32_16x16x32_bf16 v[10:13], v[164:167], v[204:207], v[10:13]
	v_mfma_f32_16x16x32_bf16 v[2:5], v[172:175], v[204:207], v[2:5]
	s_setprio 1
	s_barrier
	s_add_i32 s51, s51, 2
	s_add_u32 s26, s26, 0x100
	s_addc_u32 s27, s27, 0
	s_add_u32 s49, s49, 0x100
	s_addc_u32 s50, s50, 0
	s_cmp_gt_u32 s51, 13
	s_cbranch_scc0 .LBB0_1238
	v_mov_b32_e32 v140, v212
	s_lshl_b32 s13, s24, 7
	v_and_b32_e32 v153, 15, v140
	v_ashrrev_i32_e32 v140, 4, v140
	s_or_b32 s13, s13, s44
	v_lshl_add_u32 v152, v140, 3, s13
	s_lshl_b32 s13, s22, 8
	s_movk_i32 s15, 0x2000
	s_and_b64 vcc, exec, s[8:9]
	s_cbranch_vccz .LBB0_1241
	s_barrier

.Lp4b_j0:
	s_waitcnt lgkmcnt(0)
	s_barrier
	s_setprio 0
	s_waitcnt lgkmcnt(0)
	v_mfma_f32_16x16x32_bf16 v[126:129], v[136:139], v[170:173], v[126:129]
	v_mfma_f32_16x16x32_bf16 v[122:125], v[146:149], v[170:173], v[122:125]
	v_mfma_f32_16x16x32_bf16 v[114:117], v[136:139], v[178:181], v[114:117]
	v_mfma_f32_16x16x32_bf16 v[106:109], v[146:149], v[178:181], v[106:109]
	v_mfma_f32_16x16x32_bf16 v[98:101], v[136:139], v[186:189], v[98:101]
	v_mfma_f32_16x16x32_bf16 v[90:93], v[146:149], v[186:189], v[90:93]
	v_mfma_f32_16x16x32_bf16 v[82:85], v[136:139], v[194:197], v[82:85]
	v_mfma_f32_16x16x32_bf16 v[74:77], v[146:149], v[194:197], v[74:77]
	v_mfma_f32_16x16x32_bf16 v[126:129], v[140:143], v[174:177], v[126:129]
	v_mfma_f32_16x16x32_bf16 v[122:125], v[150:153], v[174:177], v[122:125]
	v_mfma_f32_16x16x32_bf16 v[114:117], v[140:143], v[182:185], v[114:117]
	v_mfma_f32_16x16x32_bf16 v[106:109], v[150:153], v[182:185], v[106:109]
	v_mfma_f32_16x16x32_bf16 v[98:101], v[140:143], v[190:193], v[98:101]
	v_mfma_f32_16x16x32_bf16 v[90:93], v[150:153], v[190:193], v[90:93]
	v_mfma_f32_16x16x32_bf16 v[82:85], v[140:143], v[198:201], v[82:85]
	v_mfma_f32_16x16x32_bf16 v[74:77], v[150:153], v[198:201], v[74:77]
	s_setprio 1
	s_setprio 0
	v_mfma_f32_16x16x32_bf16 v[118:121], v[154:157], v[170:173], v[118:121]
	v_mfma_f32_16x16x32_bf16 v[110:113], v[162:165], v[170:173], v[110:113]
	v_mfma_f32_16x16x32_bf16 v[102:105], v[154:157], v[178:181], v[102:105]
	v_mfma_f32_16x16x32_bf16 v[94:97], v[162:165], v[178:181], v[94:97]
	v_mfma_f32_16x16x32_bf16 v[86:89], v[154:157], v[186:189], v[86:89]
	v_mfma_f32_16x16x32_bf16 v[78:81], v[162:165], v[186:189], v[78:81]
	v_mfma_f32_16x16x32_bf16 v[70:73], v[154:157], v[194:197], v[70:73]
	v_mfma_f32_16x16x32_bf16 v[66:69], v[162:165], v[194:197], v[66:69]
	v_mfma_f32_16x16x32_bf16 v[118:121], v[158:161], v[174:177], v[118:121]
	v_mfma_f32_16x16x32_bf16 v[110:113], v[166:169], v[174:177], v[110:113]
	v_mfma_f32_16x16x32_bf16 v[102:105], v[158:161], v[182:185], v[102:105]
	v_mfma_f32_16x16x32_bf16 v[94:97], v[166:169], v[182:185], v[94:97]
	v_mfma_f32_16x16x32_bf16 v[86:89], v[158:161], v[190:193], v[86:89]
	v_mfma_f32_16x16x32_bf16 v[78:81], v[166:169], v[190:193], v[78:81]
	v_mfma_f32_16x16x32_bf16 v[70:73], v[158:161], v[198:201], v[70:73]
	v_mfma_f32_16x16x32_bf16 v[66:69], v[166:169], v[198:201], v[66:69]
	s_setprio 1
	s_barrier
	s_add_i32 s18, s51, s30
	v_lshl_add_u64 v[202:203], s[22:23], 0, v[0:1]
	s_mov_b32 m0, s18
	ds_read_b128 v[170:173], v145 offset:16384
	ds_read_b128 v[174:177], v145 offset:17408
	ds_read_b128 v[178:181], v145 offset:18432
	ds_read_b128 v[182:185], v145 offset:19456
	ds_read_b128 v[186:189], v145 offset:20480
	ds_read_b128 v[190:193], v145 offset:21504
	ds_read_b128 v[194:197], v145 offset:22528
	ds_read_b128 v[198:201], v145 offset:23552
	global_load_lds_dwordx4 v[202:203], off
	s_add_i32 m0, s18, 0x2000
	s_add_u32 s18, s22, 0xb0000
	v_lshl_add_u64 v[204:205], s[22:23], 0, v[130:131]
	s_addc_u32 s19, s23, 0
	s_add_i32 s51, s52, s30
	global_load_lds_dwordx4 v[204:205], off
	v_lshl_add_u64 v[206:207], s[18:19], 0, v[0:1]
	s_mov_b32 m0, s51
	v_lshl_add_u64 v[210:211], s[24:25], 0, v[130:131]
	global_load_lds_dwordx4 v[206:207], off
	v_lshl_add_u64 v[206:207], s[18:19], 0, v[130:131]
	s_add_i32 m0, s51, 0x2000
	s_nop 0
	global_load_lds_dwordx4 v[206:207], off
	v_lshl_add_u64 v[206:207], s[24:25], 0, v[0:1]
	s_mov_b32 m0, s31
	s_nop 0
	global_load_lds_dwordx4 v[206:207], off
	s_mov_b32 m0, s36
	s_nop 0
	global_load_lds_dwordx4 v[210:211], off
	s_cmp_eq_u32 s50, -2
	s_cbranch_scc1 .Lp4b_f1
	s_waitcnt vmcnt(8)
	s_branch .Lp4b_j1

.Lp4b_j1:
	s_waitcnt lgkmcnt(0)
	s_barrier
	s_setprio 0
	s_waitcnt lgkmcnt(0)
	v_mfma_f32_16x16x32_bf16 v[62:65], v[136:139], v[170:173], v[62:65]
	v_mfma_f32_16x16x32_bf16 v[58:61], v[146:149], v[170:173], v[58:61]
	v_mfma_f32_16x16x32_bf16 v[50:53], v[136:139], v[178:181], v[50:53]
	v_mfma_f32_16x16x32_bf16 v[42:45], v[146:149], v[178:181], v[42:45]
	v_mfma_f32_16x16x32_bf16 v[34:37], v[136:139], v[186:189], v[34:37]
	v_mfma_f32_16x16x32_bf16 v[26:29], v[146:149], v[186:189], v[26:29]
	v_mfma_f32_16x16x32_bf16 v[18:21], v[136:139], v[194:197], v[18:21]
	v_mfma_f32_16x16x32_bf16 v[10:13], v[146:149], v[194:197], v[10:13]
	v_mfma_f32_16x16x32_bf16 v[62:65], v[140:143], v[174:177], v[62:65]
	v_mfma_f32_16x16x32_bf16 v[58:61], v[150:153], v[174:177], v[58:61]
	v_mfma_f32_16x16x32_bf16 v[50:53], v[140:143], v[182:185], v[50:53]
	v_mfma_f32_16x16x32_bf16 v[42:45], v[150:153], v[182:185], v[42:45]
	v_mfma_f32_16x16x32_bf16 v[34:37], v[140:143], v[190:193], v[34:37]
	v_mfma_f32_16x16x32_bf16 v[26:29], v[150:153], v[190:193], v[26:29]
	v_mfma_f32_16x16x32_bf16 v[18:21], v[140:143], v[198:201], v[18:21]
	v_mfma_f32_16x16x32_bf16 v[10:13], v[150:153], v[198:201], v[10:13]
	s_setprio 1
	s_setprio 0
	v_mfma_f32_16x16x32_bf16 v[54:57], v[154:157], v[170:173], v[54:57]
	v_mfma_f32_16x16x32_bf16 v[46:49], v[162:165], v[170:173], v[46:49]
	v_mfma_f32_16x16x32_bf16 v[38:41], v[154:157], v[178:181], v[38:41]
	v_mfma_f32_16x16x32_bf16 v[30:33], v[162:165], v[178:181], v[30:33]
	v_mfma_f32_16x16x32_bf16 v[22:25], v[154:157], v[186:189], v[22:25]
	v_mfma_f32_16x16x32_bf16 v[14:17], v[162:165], v[186:189], v[14:17]
	v_mfma_f32_16x16x32_bf16 v[6:9], v[154:157], v[194:197], v[6:9]
	v_mfma_f32_16x16x32_bf16 v[2:5], v[162:165], v[194:197], v[2:5]
	v_mfma_f32_16x16x32_bf16 v[54:57], v[158:161], v[174:177], v[54:57]
	v_mfma_f32_16x16x32_bf16 v[46:49], v[166:169], v[174:177], v[46:49]
	v_mfma_f32_16x16x32_bf16 v[38:41], v[158:161], v[182:185], v[38:41]
	v_mfma_f32_16x16x32_bf16 v[30:33], v[166:169], v[182:185], v[30:33]
	v_mfma_f32_16x16x32_bf16 v[22:25], v[158:161], v[190:193], v[22:25]
	v_mfma_f32_16x16x32_bf16 v[14:17], v[166:169], v[190:193], v[14:17]
	v_mfma_f32_16x16x32_bf16 v[6:9], v[158:161], v[198:201], v[6:9]
	v_mfma_f32_16x16x32_bf16 v[2:5], v[166:169], v[198:201], v[2:5]
	s_setprio 1
	s_barrier
	s_add_i32 s51, 0, 0x18000
	s_add_i32 s52, 0, 0x1c000
	v_add_u32_e32 v150, s51, v144
	v_add_u32_e32 v166, s52, v144
	ds_read_b128 v[136:139], v150
	ds_read_b128 v[140:143], v150 offset:1024
	ds_read_b128 v[146:149], v150 offset:2048
	ds_read_b128 v[150:153], v150 offset:3072
	ds_read_b128 v[154:157], v166
	ds_read_b128 v[158:161], v166 offset:1024
	ds_read_b128 v[162:165], v166 offset:2048
	ds_read_b128 v[166:169], v166 offset:3072
	s_add_u32 s18, s24, 0xb0000
	s_addc_u32 s19, s25, 0
	s_mov_b32 m0, s37
	v_lshl_add_u64 v[214:215], s[18:19], 0, v[0:1]
	ds_read_b128 v[170:173], v145 offset:32768
	ds_read_b128 v[174:177], v145 offset:33792
	ds_read_b128 v[178:181], v145 offset:34816
	ds_read_b128 v[182:185], v145 offset:35840
	ds_read_b128 v[186:189], v145 offset:36864
	ds_read_b128 v[190:193], v145 offset:37888
	ds_read_b128 v[194:197], v145 offset:38912
	ds_read_b128 v[198:201], v145 offset:39936
	global_load_lds_dwordx4 v[214:215], off
	v_lshl_add_u64 v[214:215], s[18:19], 0, v[130:131]
	s_mov_b32 m0, s38
	s_nop 0
	global_load_lds_dwordx4 v[214:215], off
	s_waitcnt vmcnt(8)
	s_waitcnt lgkmcnt(0)
	s_barrier
	s_setprio 0
	s_waitcnt lgkmcnt(0)
	v_mfma_f32_16x16x32_bf16 v[126:129], v[136:139], v[170:173], v[126:129]
	v_mfma_f32_16x16x32_bf16 v[122:125], v[146:149], v[170:173], v[122:125]
	v_mfma_f32_16x16x32_bf16 v[114:117], v[136:139], v[178:181], v[114:117]
	v_mfma_f32_16x16x32_bf16 v[106:109], v[146:149], v[178:181], v[106:109]
	v_mfma_f32_16x16x32_bf16 v[98:101], v[136:139], v[186:189], v[98:101]
	v_mfma_f32_16x16x32_bf16 v[90:93], v[146:149], v[186:189], v[90:93]
	v_mfma_f32_16x16x32_bf16 v[82:85], v[136:139], v[194:197], v[82:85]
	v_mfma_f32_16x16x32_bf16 v[74:77], v[146:149], v[194:197], v[74:77]
	v_mfma_f32_16x16x32_bf16 v[126:129], v[140:143], v[174:177], v[126:129]
	v_mfma_f32_16x16x32_bf16 v[122:125], v[150:153], v[174:177], v[122:125]
	v_mfma_f32_16x16x32_bf16 v[114:117], v[140:143], v[182:185], v[114:117]
	v_mfma_f32_16x16x32_bf16 v[106:109], v[150:153], v[182:185], v[106:109]
	v_mfma_f32_16x16x32_bf16 v[98:101], v[140:143], v[190:193], v[98:101]
	v_mfma_f32_16x16x32_bf16 v[90:93], v[150:153], v[190:193], v[90:93]
	v_mfma_f32_16x16x32_bf16 v[82:85], v[140:143], v[198:201], v[82:85]
	v_mfma_f32_16x16x32_bf16 v[74:77], v[150:153], v[198:201], v[74:77]
	s_setprio 1
	s_setprio 0
	v_mfma_f32_16x16x32_bf16 v[118:121], v[154:157], v[170:173], v[118:121]
	v_mfma_f32_16x16x32_bf16 v[110:113], v[162:165], v[170:173], v[110:113]
	v_mfma_f32_16x16x32_bf16 v[102:105], v[154:157], v[178:181], v[102:105]
	v_mfma_f32_16x16x32_bf16 v[94:97], v[162:165], v[178:181], v[94:97]
	v_mfma_f32_16x16x32_bf16 v[86:89], v[154:157], v[186:189], v[86:89]
	v_mfma_f32_16x16x32_bf16 v[78:81], v[162:165], v[186:189], v[78:81]
	v_mfma_f32_16x16x32_bf16 v[70:73], v[154:157], v[194:197], v[70:73]
	v_mfma_f32_16x16x32_bf16 v[66:69], v[162:165], v[194:197], v[66:69]
	v_mfma_f32_16x16x32_bf16 v[118:121], v[158:161], v[174:177], v[118:121]
	v_mfma_f32_16x16x32_bf16 v[110:113], v[166:169], v[174:177], v[110:113]
	v_mfma_f32_16x16x32_bf16 v[102:105], v[158:161], v[182:185], v[102:105]
	v_mfma_f32_16x16x32_bf16 v[94:97], v[166:169], v[182:185], v[94:97]
	v_mfma_f32_16x16x32_bf16 v[86:89], v[158:161], v[190:193], v[86:89]
	v_mfma_f32_16x16x32_bf16 v[78:81], v[166:169], v[190:193], v[78:81]
	v_mfma_f32_16x16x32_bf16 v[70:73], v[158:161], v[198:201], v[70:73]
	v_mfma_f32_16x16x32_bf16 v[66:69], v[166:169], v[198:201], v[66:69]
	s_setprio 1
	s_barrier
	s_add_i32 s18, s51, s30
	v_lshl_add_u64 v[202:203], v[202:203], 0, s[94:95]
	s_mov_b32 m0, s18
	ds_read_b128 v[170:173], v145 offset:49152
	ds_read_b128 v[174:177], v145 offset:50176
	ds_read_b128 v[178:181], v145 offset:51200
	ds_read_b128 v[182:185], v145 offset:52224
	ds_read_b128 v[186:189], v145 offset:53248
	ds_read_b128 v[190:193], v145 offset:54272
	ds_read_b128 v[194:197], v145 offset:55296
	ds_read_b128 v[198:201], v145 offset:56320
	global_load_lds_dwordx4 v[202:203], off
	s_add_i32 m0, s18, 0x2000
	s_add_u32 s18, s22, 0xb0080
	v_lshl_add_u64 v[202:203], v[204:205], 0, s[94:95]
	s_addc_u32 s19, s23, 0
	s_add_i32 s22, s52, s30
	global_load_lds_dwordx4 v[202:203], off
	v_lshl_add_u64 v[202:203], s[18:19], 0, v[0:1]
	s_mov_b32 m0, s22
	s_nop 0
	global_load_lds_dwordx4 v[202:203], off
	v_lshl_add_u64 v[202:203], s[18:19], 0, v[130:131]
	s_add_i32 m0, s22, 0x2000
	s_nop 0
	global_load_lds_dwordx4 v[202:203], off
	v_lshl_add_u64 v[202:203], v[206:207], 0, s[94:95]
	s_mov_b32 m0, s41
	s_nop 0
	global_load_lds_dwordx4 v[202:203], off
	v_lshl_add_u64 v[202:203], v[210:211], 0, s[94:95]
	s_mov_b32 m0, s42
	s_nop 0
	global_load_lds_dwordx4 v[202:203], off
	s_waitcnt vmcnt(8)
	s_waitcnt lgkmcnt(0)
	s_barrier
	s_setprio 0
	s_waitcnt lgkmcnt(0)
	v_mfma_f32_16x16x32_bf16 v[62:65], v[136:139], v[170:173], v[62:65]
	v_mfma_f32_16x16x32_bf16 v[58:61], v[146:149], v[170:173], v[58:61]
	v_mfma_f32_16x16x32_bf16 v[50:53], v[136:139], v[178:181], v[50:53]
	v_mfma_f32_16x16x32_bf16 v[42:45], v[146:149], v[178:181], v[42:45]
	v_mfma_f32_16x16x32_bf16 v[34:37], v[136:139], v[186:189], v[34:37]
	v_mfma_f32_16x16x32_bf16 v[26:29], v[146:149], v[186:189], v[26:29]
	v_mfma_f32_16x16x32_bf16 v[18:21], v[136:139], v[194:197], v[18:21]
	v_mfma_f32_16x16x32_bf16 v[10:13], v[146:149], v[194:197], v[10:13]
	v_mfma_f32_16x16x32_bf16 v[62:65], v[140:143], v[174:177], v[62:65]
	v_mfma_f32_16x16x32_bf16 v[58:61], v[150:153], v[174:177], v[58:61]
	v_mfma_f32_16x16x32_bf16 v[50:53], v[140:143], v[182:185], v[50:53]
	v_mfma_f32_16x16x32_bf16 v[42:45], v[150:153], v[182:185], v[42:45]
	v_mfma_f32_16x16x32_bf16 v[34:37], v[140:143], v[190:193], v[34:37]
	v_mfma_f32_16x16x32_bf16 v[26:29], v[150:153], v[190:193], v[26:29]
	v_mfma_f32_16x16x32_bf16 v[18:21], v[140:143], v[198:201], v[18:21]
	v_mfma_f32_16x16x32_bf16 v[10:13], v[150:153], v[198:201], v[10:13]
	s_setprio 1
	s_setprio 0
	v_mfma_f32_16x16x32_bf16 v[54:57], v[154:157], v[170:173], v[54:57]
	v_mfma_f32_16x16x32_bf16 v[46:49], v[162:165], v[170:173], v[46:49]
	v_mfma_f32_16x16x32_bf16 v[38:41], v[154:157], v[178:181], v[38:41]
	v_mfma_f32_16x16x32_bf16 v[30:33], v[162:165], v[178:181], v[30:33]
	v_mfma_f32_16x16x32_bf16 v[22:25], v[154:157], v[186:189], v[22:25]
	v_mfma_f32_16x16x32_bf16 v[14:17], v[162:165], v[186:189], v[14:17]
	v_mfma_f32_16x16x32_bf16 v[6:9], v[154:157], v[194:197], v[6:9]
	v_mfma_f32_16x16x32_bf16 v[2:5], v[162:165], v[194:197], v[2:5]
	v_mfma_f32_16x16x32_bf16 v[54:57], v[158:161], v[174:177], v[54:57]
	v_mfma_f32_16x16x32_bf16 v[46:49], v[166:169], v[174:177], v[46:49]
	v_mfma_f32_16x16x32_bf16 v[38:41], v[158:161], v[182:185], v[38:41]
	v_mfma_f32_16x16x32_bf16 v[30:33], v[166:169], v[182:185], v[30:33]
	v_mfma_f32_16x16x32_bf16 v[22:25], v[158:161], v[190:193], v[22:25]
	v_mfma_f32_16x16x32_bf16 v[14:17], v[166:169], v[190:193], v[14:17]
	v_mfma_f32_16x16x32_bf16 v[6:9], v[158:161], v[198:201], v[6:9]
	v_mfma_f32_16x16x32_bf16 v[2:5], v[166:169], v[198:201], v[2:5]
	s_setprio 1
	s_barrier
	s_add_i32 s50, s50, 2
	s_add_u32 s48, s48, 0x100
	s_addc_u32 s49, s49, 0
	s_cmp_gt_u32 s50, 41
	s_mov_b64 s[18:19], s[20:21]
	s_cbranch_scc0 .LBB0_1316
	s_and_b64 vcc, exec, s[14:15]
	s_cbranch_vccz .LBB0_1319
	s_barrier

.Lp4a_j0:
	s_waitcnt lgkmcnt(0)
	s_barrier
	s_setprio 0
	s_waitcnt lgkmcnt(0)
	v_mfma_f32_16x16x32_bf16 v[126:129], v[136:139], v[172:175], v[126:129]
	v_mfma_f32_16x16x32_bf16 v[122:125], v[144:147], v[172:175], v[122:125]
	v_mfma_f32_16x16x32_bf16 v[114:117], v[136:139], v[180:183], v[114:117]
	v_mfma_f32_16x16x32_bf16 v[106:109], v[144:147], v[180:183], v[106:109]
	v_mfma_f32_16x16x32_bf16 v[98:101], v[136:139], v[188:191], v[98:101]
	v_mfma_f32_16x16x32_bf16 v[90:93], v[144:147], v[188:191], v[90:93]
	v_mfma_f32_16x16x32_bf16 v[82:85], v[136:139], v[196:199], v[82:85]
	v_mfma_f32_16x16x32_bf16 v[74:77], v[144:147], v[196:199], v[74:77]
	v_mfma_f32_16x16x32_bf16 v[126:129], v[140:143], v[176:179], v[126:129]
	v_mfma_f32_16x16x32_bf16 v[122:125], v[148:151], v[176:179], v[122:125]
	v_mfma_f32_16x16x32_bf16 v[114:117], v[140:143], v[184:187], v[114:117]
	v_mfma_f32_16x16x32_bf16 v[106:109], v[148:151], v[184:187], v[106:109]
	v_mfma_f32_16x16x32_bf16 v[98:101], v[140:143], v[192:195], v[98:101]
	v_mfma_f32_16x16x32_bf16 v[90:93], v[148:151], v[192:195], v[90:93]
	v_mfma_f32_16x16x32_bf16 v[82:85], v[140:143], v[200:203], v[82:85]
	v_mfma_f32_16x16x32_bf16 v[74:77], v[148:151], v[200:203], v[74:77]
	s_setprio 1
	s_setprio 0
	v_mfma_f32_16x16x32_bf16 v[118:121], v[152:155], v[172:175], v[118:121]
	v_mfma_f32_16x16x32_bf16 v[110:113], v[160:163], v[172:175], v[110:113]
	v_mfma_f32_16x16x32_bf16 v[102:105], v[152:155], v[180:183], v[102:105]
	v_mfma_f32_16x16x32_bf16 v[94:97], v[160:163], v[180:183], v[94:97]
	v_mfma_f32_16x16x32_bf16 v[86:89], v[152:155], v[188:191], v[86:89]
	v_mfma_f32_16x16x32_bf16 v[78:81], v[160:163], v[188:191], v[78:81]
	v_mfma_f32_16x16x32_bf16 v[70:73], v[152:155], v[196:199], v[70:73]
	v_mfma_f32_16x16x32_bf16 v[66:69], v[160:163], v[196:199], v[66:69]
	v_mfma_f32_16x16x32_bf16 v[118:121], v[156:159], v[176:179], v[118:121]
	v_mfma_f32_16x16x32_bf16 v[110:113], v[168:171], v[176:179], v[110:113]
	v_mfma_f32_16x16x32_bf16 v[102:105], v[156:159], v[184:187], v[102:105]
	v_mfma_f32_16x16x32_bf16 v[94:97], v[168:171], v[184:187], v[94:97]
	v_mfma_f32_16x16x32_bf16 v[86:89], v[156:159], v[192:195], v[86:89]
	v_mfma_f32_16x16x32_bf16 v[78:81], v[168:171], v[192:195], v[78:81]
	v_mfma_f32_16x16x32_bf16 v[70:73], v[156:159], v[200:203], v[70:73]
	v_mfma_f32_16x16x32_bf16 v[66:69], v[168:171], v[200:203], v[66:69]
	s_setprio 1
	s_barrier
	s_add_i32 s14, s47, s22
	v_lshl_add_u64 v[164:165], s[18:19], 0, v[0:1]
	s_mov_b32 m0, s14
	ds_read_b128 v[172:175], v167 offset:16384
	ds_read_b128 v[176:179], v167 offset:17408
	ds_read_b128 v[180:183], v167 offset:18432
	ds_read_b128 v[184:187], v167 offset:19456
	ds_read_b128 v[188:191], v167 offset:20480
	ds_read_b128 v[192:195], v167 offset:21504
	ds_read_b128 v[196:199], v167 offset:22528
	ds_read_b128 v[200:203], v167 offset:23552
	global_load_lds_dwordx4 v[164:165], off
	s_add_i32 m0, s14, 0x2000
	s_add_u32 s14, s18, 0xb0000
	v_lshl_add_u64 v[204:205], s[18:19], 0, v[130:131]
	s_addc_u32 s15, s19, 0
	s_add_i32 s47, s48, s22
	global_load_lds_dwordx4 v[204:205], off
	v_lshl_add_u64 v[206:207], s[14:15], 0, v[0:1]
	s_mov_b32 m0, s47
	v_lshl_add_u64 v[210:211], s[20:21], 0, v[130:131]
	global_load_lds_dwordx4 v[206:207], off
	v_lshl_add_u64 v[206:207], s[14:15], 0, v[130:131]
	s_add_i32 m0, s47, 0x2000
	s_nop 0
	global_load_lds_dwordx4 v[206:207], off
	v_lshl_add_u64 v[206:207], s[20:21], 0, v[0:1]
	s_mov_b32 m0, s23
	s_nop 0
	global_load_lds_dwordx4 v[206:207], off
	s_mov_b32 m0, s24
	s_nop 0
	global_load_lds_dwordx4 v[210:211], off
	s_cmp_eq_u32 s46, -2
	s_cbranch_scc1 .Lp4a_f1
	s_waitcnt vmcnt(8)
	s_branch .Lp4a_j1

.Lp4a_j1:
	s_waitcnt lgkmcnt(0)
	s_barrier
	s_setprio 0
	s_waitcnt lgkmcnt(0)
	v_mfma_f32_16x16x32_bf16 v[62:65], v[136:139], v[172:175], v[62:65]
	v_mfma_f32_16x16x32_bf16 v[58:61], v[144:147], v[172:175], v[58:61]
	v_mfma_f32_16x16x32_bf16 v[50:53], v[136:139], v[180:183], v[50:53]
	v_mfma_f32_16x16x32_bf16 v[42:45], v[144:147], v[180:183], v[42:45]
	v_mfma_f32_16x16x32_bf16 v[34:37], v[136:139], v[188:191], v[34:37]
	v_mfma_f32_16x16x32_bf16 v[26:29], v[144:147], v[188:191], v[26:29]
	v_mfma_f32_16x16x32_bf16 v[18:21], v[136:139], v[196:199], v[18:21]
	v_mfma_f32_16x16x32_bf16 v[10:13], v[144:147], v[196:199], v[10:13]
	v_mfma_f32_16x16x32_bf16 v[62:65], v[140:143], v[176:179], v[62:65]
	v_mfma_f32_16x16x32_bf16 v[58:61], v[148:151], v[176:179], v[58:61]
	v_mfma_f32_16x16x32_bf16 v[50:53], v[140:143], v[184:187], v[50:53]
	v_mfma_f32_16x16x32_bf16 v[42:45], v[148:151], v[184:187], v[42:45]
	v_mfma_f32_16x16x32_bf16 v[34:37], v[140:143], v[192:195], v[34:37]
	v_mfma_f32_16x16x32_bf16 v[26:29], v[148:151], v[192:195], v[26:29]
	v_mfma_f32_16x16x32_bf16 v[18:21], v[140:143], v[200:203], v[18:21]
	v_mfma_f32_16x16x32_bf16 v[10:13], v[148:151], v[200:203], v[10:13]
	s_setprio 1
	s_setprio 0
	v_mfma_f32_16x16x32_bf16 v[54:57], v[152:155], v[172:175], v[54:57]
	v_mfma_f32_16x16x32_bf16 v[46:49], v[160:163], v[172:175], v[46:49]
	v_mfma_f32_16x16x32_bf16 v[38:41], v[152:155], v[180:183], v[38:41]
	v_mfma_f32_16x16x32_bf16 v[30:33], v[160:163], v[180:183], v[30:33]
	v_mfma_f32_16x16x32_bf16 v[22:25], v[152:155], v[188:191], v[22:25]
	v_mfma_f32_16x16x32_bf16 v[14:17], v[160:163], v[188:191], v[14:17]
	v_mfma_f32_16x16x32_bf16 v[6:9], v[152:155], v[196:199], v[6:9]
	v_mfma_f32_16x16x32_bf16 v[2:5], v[160:163], v[196:199], v[2:5]
	v_mfma_f32_16x16x32_bf16 v[54:57], v[156:159], v[176:179], v[54:57]
	v_mfma_f32_16x16x32_bf16 v[46:49], v[168:171], v[176:179], v[46:49]
	v_mfma_f32_16x16x32_bf16 v[38:41], v[156:159], v[184:187], v[38:41]
	v_mfma_f32_16x16x32_bf16 v[30:33], v[168:171], v[184:187], v[30:33]
	v_mfma_f32_16x16x32_bf16 v[22:25], v[156:159], v[192:195], v[22:25]
	v_mfma_f32_16x16x32_bf16 v[14:17], v[168:171], v[192:195], v[14:17]
	v_mfma_f32_16x16x32_bf16 v[6:9], v[156:159], v[200:203], v[6:9]
	v_mfma_f32_16x16x32_bf16 v[2:5], v[168:171], v[200:203], v[2:5]
	s_setprio 1
	s_barrier
	s_add_i32 s47, 0, 0x18000
	s_add_i32 s48, 0, 0x1c000
	v_add_u32_e32 v148, s47, v166
	v_add_u32_e32 v168, s48, v166
	ds_read_b128 v[136:139], v148
	ds_read_b128 v[140:143], v148 offset:1024
	ds_read_b128 v[144:147], v148 offset:2048
	ds_read_b128 v[148:151], v148 offset:3072
	ds_read_b128 v[152:155], v168
	ds_read_b128 v[156:159], v168 offset:1024
	ds_read_b128 v[160:163], v168 offset:2048
	ds_read_b128 v[168:171], v168 offset:3072
	s_add_u32 s14, s20, 0xb0000
	s_addc_u32 s15, s21, 0
	s_mov_b32 m0, s25
	v_lshl_add_u64 v[214:215], s[14:15], 0, v[0:1]
	ds_read_b128 v[172:175], v167 offset:32768
	ds_read_b128 v[176:179], v167 offset:33792
	ds_read_b128 v[180:183], v167 offset:34816
	ds_read_b128 v[184:187], v167 offset:35840
	ds_read_b128 v[188:191], v167 offset:36864
	ds_read_b128 v[192:195], v167 offset:37888
	ds_read_b128 v[196:199], v167 offset:38912
	ds_read_b128 v[200:203], v167 offset:39936
	global_load_lds_dwordx4 v[214:215], off
	v_lshl_add_u64 v[214:215], s[14:15], 0, v[130:131]
	s_mov_b32 m0, s30
	s_nop 0
	global_load_lds_dwordx4 v[214:215], off
	s_waitcnt vmcnt(8)
	s_waitcnt lgkmcnt(0)
	s_barrier
	s_setprio 0
	s_waitcnt lgkmcnt(0)
	v_mfma_f32_16x16x32_bf16 v[126:129], v[136:139], v[172:175], v[126:129]
	v_mfma_f32_16x16x32_bf16 v[122:125], v[144:147], v[172:175], v[122:125]
	v_mfma_f32_16x16x32_bf16 v[114:117], v[136:139], v[180:183], v[114:117]
	v_mfma_f32_16x16x32_bf16 v[106:109], v[144:147], v[180:183], v[106:109]
	v_mfma_f32_16x16x32_bf16 v[98:101], v[136:139], v[188:191], v[98:101]
	v_mfma_f32_16x16x32_bf16 v[90:93], v[144:147], v[188:191], v[90:93]
	v_mfma_f32_16x16x32_bf16 v[82:85], v[136:139], v[196:199], v[82:85]
	v_mfma_f32_16x16x32_bf16 v[74:77], v[144:147], v[196:199], v[74:77]
	v_mfma_f32_16x16x32_bf16 v[126:129], v[140:143], v[176:179], v[126:129]
	v_mfma_f32_16x16x32_bf16 v[122:125], v[148:151], v[176:179], v[122:125]
	v_mfma_f32_16x16x32_bf16 v[114:117], v[140:143], v[184:187], v[114:117]
	v_mfma_f32_16x16x32_bf16 v[106:109], v[148:151], v[184:187], v[106:109]
	v_mfma_f32_16x16x32_bf16 v[98:101], v[140:143], v[192:195], v[98:101]
	v_mfma_f32_16x16x32_bf16 v[90:93], v[148:151], v[192:195], v[90:93]
	v_mfma_f32_16x16x32_bf16 v[82:85], v[140:143], v[200:203], v[82:85]
	v_mfma_f32_16x16x32_bf16 v[74:77], v[148:151], v[200:203], v[74:77]
	s_setprio 1
	s_setprio 0
	v_mfma_f32_16x16x32_bf16 v[118:121], v[152:155], v[172:175], v[118:121]
	v_mfma_f32_16x16x32_bf16 v[110:113], v[160:163], v[172:175], v[110:113]
	v_mfma_f32_16x16x32_bf16 v[102:105], v[152:155], v[180:183], v[102:105]
	v_mfma_f32_16x16x32_bf16 v[94:97], v[160:163], v[180:183], v[94:97]
	v_mfma_f32_16x16x32_bf16 v[86:89], v[152:155], v[188:191], v[86:89]
	v_mfma_f32_16x16x32_bf16 v[78:81], v[160:163], v[188:191], v[78:81]
	v_mfma_f32_16x16x32_bf16 v[70:73], v[152:155], v[196:199], v[70:73]
	v_mfma_f32_16x16x32_bf16 v[66:69], v[160:163], v[196:199], v[66:69]
	v_mfma_f32_16x16x32_bf16 v[118:121], v[156:159], v[176:179], v[118:121]
	v_mfma_f32_16x16x32_bf16 v[110:113], v[168:171], v[176:179], v[110:113]
	v_mfma_f32_16x16x32_bf16 v[102:105], v[156:159], v[184:187], v[102:105]
	v_mfma_f32_16x16x32_bf16 v[94:97], v[168:171], v[184:187], v[94:97]
	v_mfma_f32_16x16x32_bf16 v[86:89], v[156:159], v[192:195], v[86:89]
	v_mfma_f32_16x16x32_bf16 v[78:81], v[168:171], v[192:195], v[78:81]
	v_mfma_f32_16x16x32_bf16 v[70:73], v[156:159], v[200:203], v[70:73]
	v_mfma_f32_16x16x32_bf16 v[66:69], v[168:171], v[200:203], v[66:69]
	s_setprio 1
	s_barrier
	s_add_i32 s14, s47, s22
	v_lshl_add_u64 v[164:165], v[164:165], 0, s[94:95]
	s_mov_b32 m0, s14
	ds_read_b128 v[172:175], v167 offset:49152
	ds_read_b128 v[176:179], v167 offset:50176
	ds_read_b128 v[180:183], v167 offset:51200
	ds_read_b128 v[184:187], v167 offset:52224
	ds_read_b128 v[188:191], v167 offset:53248
	ds_read_b128 v[192:195], v167 offset:54272
	ds_read_b128 v[196:199], v167 offset:55296
	ds_read_b128 v[200:203], v167 offset:56320
	global_load_lds_dwordx4 v[164:165], off
	s_add_i32 m0, s14, 0x2000
	s_add_u32 s14, s18, 0xb0080
	v_lshl_add_u64 v[164:165], v[204:205], 0, s[94:95]
	s_addc_u32 s15, s19, 0
	s_add_i32 s18, s48, s22
	global_load_lds_dwordx4 v[164:165], off
	v_lshl_add_u64 v[164:165], s[14:15], 0, v[0:1]
	s_mov_b32 m0, s18
	s_nop 0
	global_load_lds_dwordx4 v[164:165], off
	v_lshl_add_u64 v[164:165], s[14:15], 0, v[130:131]
	s_add_i32 m0, s18, 0x2000
	s_nop 0
	global_load_lds_dwordx4 v[164:165], off
	v_lshl_add_u64 v[164:165], v[206:207], 0, s[94:95]
	s_mov_b32 m0, s37
	s_nop 0
	global_load_lds_dwordx4 v[164:165], off
	v_lshl_add_u64 v[164:165], v[210:211], 0, s[94:95]
	s_mov_b32 m0, s38
	s_nop 0
	global_load_lds_dwordx4 v[164:165], off
	s_waitcnt vmcnt(8)
	s_waitcnt lgkmcnt(0)
	s_barrier
	s_setprio 0
	s_waitcnt lgkmcnt(0)
	v_mfma_f32_16x16x32_bf16 v[62:65], v[136:139], v[172:175], v[62:65]
	v_mfma_f32_16x16x32_bf16 v[58:61], v[144:147], v[172:175], v[58:61]
	v_mfma_f32_16x16x32_bf16 v[50:53], v[136:139], v[180:183], v[50:53]
	v_mfma_f32_16x16x32_bf16 v[42:45], v[144:147], v[180:183], v[42:45]
	v_mfma_f32_16x16x32_bf16 v[34:37], v[136:139], v[188:191], v[34:37]
	v_mfma_f32_16x16x32_bf16 v[26:29], v[144:147], v[188:191], v[26:29]
	v_mfma_f32_16x16x32_bf16 v[18:21], v[136:139], v[196:199], v[18:21]
	v_mfma_f32_16x16x32_bf16 v[10:13], v[144:147], v[196:199], v[10:13]
	v_mfma_f32_16x16x32_bf16 v[62:65], v[140:143], v[176:179], v[62:65]
	v_mfma_f32_16x16x32_bf16 v[58:61], v[148:151], v[176:179], v[58:61]
	v_mfma_f32_16x16x32_bf16 v[50:53], v[140:143], v[184:187], v[50:53]
	v_mfma_f32_16x16x32_bf16 v[42:45], v[148:151], v[184:187], v[42:45]
	v_mfma_f32_16x16x32_bf16 v[34:37], v[140:143], v[192:195], v[34:37]
	v_mfma_f32_16x16x32_bf16 v[26:29], v[148:151], v[192:195], v[26:29]
	v_mfma_f32_16x16x32_bf16 v[18:21], v[140:143], v[200:203], v[18:21]
	v_mfma_f32_16x16x32_bf16 v[10:13], v[148:151], v[200:203], v[10:13]
	s_setprio 1
	s_setprio 0
	v_mfma_f32_16x16x32_bf16 v[54:57], v[152:155], v[172:175], v[54:57]
	v_mfma_f32_16x16x32_bf16 v[46:49], v[160:163], v[172:175], v[46:49]
	v_mfma_f32_16x16x32_bf16 v[38:41], v[152:155], v[180:183], v[38:41]
	v_mfma_f32_16x16x32_bf16 v[30:33], v[160:163], v[180:183], v[30:33]
	v_mfma_f32_16x16x32_bf16 v[22:25], v[152:155], v[188:191], v[22:25]
	v_mfma_f32_16x16x32_bf16 v[14:17], v[160:163], v[188:191], v[14:17]
	v_mfma_f32_16x16x32_bf16 v[6:9], v[152:155], v[196:199], v[6:9]
	v_mfma_f32_16x16x32_bf16 v[2:5], v[160:163], v[196:199], v[2:5]
	v_mfma_f32_16x16x32_bf16 v[54:57], v[156:159], v[176:179], v[54:57]
	v_mfma_f32_16x16x32_bf16 v[46:49], v[168:171], v[176:179], v[46:49]
	v_mfma_f32_16x16x32_bf16 v[38:41], v[156:159], v[184:187], v[38:41]
	v_mfma_f32_16x16x32_bf16 v[30:33], v[168:171], v[184:187], v[30:33]
	v_mfma_f32_16x16x32_bf16 v[22:25], v[156:159], v[192:195], v[22:25]
	v_mfma_f32_16x16x32_bf16 v[14:17], v[168:171], v[192:195], v[14:17]
	v_mfma_f32_16x16x32_bf16 v[6:9], v[156:159], v[200:203], v[6:9]
	v_mfma_f32_16x16x32_bf16 v[2:5], v[168:171], v[200:203], v[2:5]
	s_setprio 1
	s_barrier
	s_add_i32 s46, s46, 2
	s_add_u32 s44, s44, 0x100
	s_addc_u32 s45, s45, 0
	s_cmp_gt_u32 s46, 41
	s_mov_b64 s[14:15], s[16:17]
	s_cbranch_scc0 .LBB0_1342
	s_and_b64 vcc, exec, s[10:11]
	s_cbranch_vccz .LBB0_1345
	s_barrier
